# attn: grouped LDS waits in QK blocks, running tile pointers, redundant v_max dropped; GEMM loops: merged vmcnt/lgkmcnt waits
# speedup vs baseline: 1.0307x; 1.0298x over previous
; #define PG8_STAGE(bufoff, gbase, voff) do { _Pragma("unroll") for (int _i = 0; _i < 2; ++_i) \
;         __builtin_amdgcn_global_load_lds((const unsigned*)((const char*)(gbase) + (voff)[_i]), (LAS unsigned*)(lds + (bufoff) + ldsw + _i * 8192), 16, 0, 0); } while (0)
; #define PG8_LDA(dst, b, h) do { _Pragma("unroll") for (int m = 0; m < 4; ++m) _Pragma("unroll") for (int k = 0; k < 2; ++k) dst[m][k] = *(const LAS bf16x8*)(lds + PG8_SA(b, h) + aoff + m * 2048 + k * 1024); } while (0)
; #define PG8_LDB(dst, b, h) do { _Pragma("unroll") for (int n = 0; n < 2; ++n) _Pragma("unroll") for (int k = 0; k < 2; ++k) dst[n][k] = *(const LAS bf16x8*)(lds + PG8_SB(b, h) + boff + n * 2048 + k * 1024); } while (0)
; #define PG8_MMA(ai, bj, At, Bt) do { __builtin_amdgcn_s_setprio(1); _Pragma("unroll") for (int m = 0; m < 4; ++m) _Pragma("unroll") for (int n = 0; n < 2; ++n) _Pragma("unroll") for (int k = 0; k < 2; ++k) \
;         acc[ai][bj][m][n] = __builtin_amdgcn_mfma_f32_16x16x32_bf16(Bt[n][k], At[m][k], acc[ai][bj][m][n], 0, 0, 0); __builtin_amdgcn_s_setprio(0); } while (0)
; #define PG8_WAIT_V(n) asm volatile("s_waitcnt vmcnt(" #n ")" ::: "memory")
; #define PG8_WAIT_L(n) asm volatile("s_waitcnt lgkmcnt(" #n ")" ::: "memory")
; #define PG8_BAR __builtin_amdgcn_s_barrier()
; #define PG8_SCHED __builtin_amdgcn_sched_barrier(0)
; template <class Epi, class Sched>
; __device__ __forceinline__ void gemm_phase(LAS unsigned char* lds, const Gemm g, const Sched& S, const Epi& E, const int wave_s) {
;     ...
;             const bool last = (t == nt - 2);
;             const char* a1 = cA + (size_t)(t + 1) * kstep;
;             const char* a2 = last ? nA : cA + (size_t)(t + 2) * kstep; const char* b2 = last ? nB : cB + (size_t)(t + 2) * kstep;
;             const char* a3 = a2 + kstep; const char* b3 = b2 + kstep;
;             PG8_LDB(B0, 0, 0); PG8_LDB(B1, 0, 1); PG8_SCHED; PG8_LDA(At, 0, 0); PG8_STAGE(PG8_SA(1, 1), a1 + hstepA, voffA);
;             PG8_WAIT_V(8); PG8_WAIT_L(0); PG8_BAR; PG8_MMA(0, 0, At, B0); PG8_MMA(0, 1, At, B1); PG8_BAR; PG8_SCHED;
;             PG8_LDA(At, 0, 1); PG8_STAGE(PG8_SB(0, 0), b2, voffB); PG8_STAGE(PG8_SB(0, 1), b2 + hstepB, voffB); PG8_STAGE(PG8_SA(0, 0), a2, voffA);
;             PG8_WAIT_V(8); PG8_WAIT_L(0); PG8_BAR; PG8_MMA(1, 0, At, B0); PG8_MMA(1, 1, At, B1); PG8_BAR; PG8_SCHED;
.LBB0_125:
	ds_read_b128 v[152:155], v149
	ds_read_b128 v[156:159], v149 offset:1024
	ds_read_b128 v[160:163], v149 offset:2048
	ds_read_b128 v[164:167], v149 offset:3072
	ds_read_b128 v[168:171], v150
	ds_read_b128 v[172:175], v150 offset:1024
	ds_read_b128 v[176:179], v150 offset:2048
	ds_read_b128 v[180:183], v150 offset:3072
	s_add_u32 s4, s44, 0xfffc0080
	s_addc_u32 s5, s45, -1
	s_cmp_eq_u32 s65, 12
	s_cselect_b32 s47, s29, s5
	s_cselect_b32 s46, s61, s4
	s_cselect_b32 s5, s27, s64
	s_cselect_b32 s4, s62, s63
	v_lshl_add_u64 v[144:145], s[44:45], 0, v[136:137]
	s_add_i32 m0, s33, 0xc000
	ds_read_b128 v[184:187], v151
	ds_read_b128 v[188:191], v151 offset:1024
	ds_read_b128 v[192:195], v151 offset:2048
	ds_read_b128 v[196:199], v151 offset:3072
	ds_read_b128 v[200:203], v151 offset:4096
	ds_read_b128 v[204:207], v151 offset:5120
	ds_read_b128 v[210:213], v151 offset:6144
	ds_read_b128 v[214:217], v151 offset:7168
	global_load_lds_dwordx4 v[144:145], off
	v_lshl_add_u64 v[144:145], s[44:45], 0, v[138:139]
	s_add_i32 m0, s33, 0xe000
	s_nop 0
	global_load_lds_dwordx4 v[144:145], off
	s_waitcnt vmcnt(8) lgkmcnt(0)
	s_barrier
	s_setprio 1
	v_mfma_f32_16x16x32_bf16 v[124:127], v[152:155], v[184:187], v[124:127]
	v_mfma_f32_16x16x32_bf16 v[120:123], v[160:163], v[184:187], v[120:123]
	v_mfma_f32_16x16x32_bf16 v[116:119], v[152:155], v[192:195], v[116:119]
	v_mfma_f32_16x16x32_bf16 v[108:111], v[160:163], v[192:195], v[108:111]
	v_mfma_f32_16x16x32_bf16 v[100:103], v[152:155], v[200:203], v[100:103]
	v_mfma_f32_16x16x32_bf16 v[92:95], v[160:163], v[200:203], v[92:95]
	v_mfma_f32_16x16x32_bf16 v[84:87], v[152:155], v[210:213], v[84:87]
	v_mfma_f32_16x16x32_bf16 v[76:79], v[160:163], v[210:213], v[76:79]
	v_mfma_f32_16x16x32_bf16 v[124:127], v[156:159], v[188:191], v[124:127]
	v_mfma_f32_16x16x32_bf16 v[120:123], v[164:167], v[188:191], v[120:123]
	v_mfma_f32_16x16x32_bf16 v[116:119], v[156:159], v[196:199], v[116:119]
	v_mfma_f32_16x16x32_bf16 v[108:111], v[164:167], v[196:199], v[108:111]
	v_mfma_f32_16x16x32_bf16 v[100:103], v[156:159], v[204:207], v[100:103]
	v_mfma_f32_16x16x32_bf16 v[92:95], v[164:167], v[204:207], v[92:95]
	v_mfma_f32_16x16x32_bf16 v[84:87], v[156:159], v[214:217], v[84:87]
	v_mfma_f32_16x16x32_bf16 v[76:79], v[164:167], v[214:217], v[76:79]
	s_setprio 0
	s_setprio 1
	v_mfma_f32_16x16x32_bf16 v[112:115], v[168:171], v[184:187], v[112:115]
	v_mfma_f32_16x16x32_bf16 v[104:107], v[176:179], v[184:187], v[104:107]
	v_mfma_f32_16x16x32_bf16 v[96:99], v[168:171], v[192:195], v[96:99]
	v_mfma_f32_16x16x32_bf16 v[88:91], v[176:179], v[192:195], v[88:91]
	v_mfma_f32_16x16x32_bf16 v[80:83], v[168:171], v[200:203], v[80:83]
	v_mfma_f32_16x16x32_bf16 v[72:75], v[176:179], v[200:203], v[72:75]
	v_mfma_f32_16x16x32_bf16 v[68:71], v[168:171], v[210:213], v[68:71]
	v_mfma_f32_16x16x32_bf16 v[64:67], v[176:179], v[210:213], v[64:67]
	v_mfma_f32_16x16x32_bf16 v[112:115], v[172:175], v[188:191], v[112:115]
	v_mfma_f32_16x16x32_bf16 v[104:107], v[180:183], v[188:191], v[104:107]
	v_mfma_f32_16x16x32_bf16 v[96:99], v[172:175], v[196:199], v[96:99]
	v_mfma_f32_16x16x32_bf16 v[88:91], v[180:183], v[196:199], v[88:91]
	v_mfma_f32_16x16x32_bf16 v[80:83], v[172:175], v[204:207], v[80:83]
	v_mfma_f32_16x16x32_bf16 v[72:75], v[180:183], v[204:207], v[72:75]
	v_mfma_f32_16x16x32_bf16 v[68:71], v[172:175], v[214:217], v[68:71]
	v_mfma_f32_16x16x32_bf16 v[64:67], v[180:183], v[214:217], v[64:67]
	s_setprio 0
	s_barrier
	s_add_i32 s66, s53, s81
	v_lshl_add_u64 v[144:145], s[4:5], 0, v[130:131]
	s_mov_b32 m0, s66
	ds_read_b128 v[184:187], v151 offset:16384
	ds_read_b128 v[188:191], v151 offset:17408
	ds_read_b128 v[192:195], v151 offset:18432
	ds_read_b128 v[196:199], v151 offset:19456
	ds_read_b128 v[200:203], v151 offset:20480
	ds_read_b128 v[204:207], v151 offset:21504
	ds_read_b128 v[210:213], v151 offset:22528
	ds_read_b128 v[214:217], v151 offset:23552
	global_load_lds_dwordx4 v[144:145], off
	s_add_i32 m0, s66, 0x2000
	s_add_u32 s66, s4, 0x40000
	v_lshl_add_u64 v[218:219], s[4:5], 0, v[134:135]
	s_addc_u32 s67, s5, 0
	s_add_i32 s68, s54, s81
	global_load_lds_dwordx4 v[218:219], off
	v_lshl_add_u64 v[220:221], s[66:67], 0, v[130:131]
	s_mov_b32 m0, s68
	v_lshl_add_u64 v[222:223], s[46:47], 0, v[132:133]
	global_load_lds_dwordx4 v[220:221], off
	v_lshl_add_u64 v[220:221], s[66:67], 0, v[134:135]
	s_add_i32 m0, s68, 0x2000
	s_nop 0
	global_load_lds_dwordx4 v[220:221], off
	v_lshl_add_u64 v[220:221], s[46:47], 0, v[128:129]
	s_mov_b32 m0, s33
	s_nop 0
	global_load_lds_dwordx4 v[220:221], off
	s_mov_b32 m0, s35
	s_nop 0
	global_load_lds_dwordx4 v[222:223], off
	s_waitcnt vmcnt(8) lgkmcnt(0)
	s_barrier
; #define PG8_STAGE(bufoff, gbase, voff) do { _Pragma("unroll") for (int _i = 0; _i < 2; ++_i) \
;         __builtin_amdgcn_global_load_lds((const unsigned*)((const char*)(gbase) + (voff)[_i]), (LAS unsigned*)(lds + (bufoff) + ldsw + _i * 8192), 16, 0, 0); } while (0)
; #define PG8_LDA(dst, b, h) do { _Pragma("unroll") for (int m = 0; m < 4; ++m) _Pragma("unroll") for (int k = 0; k < 2; ++k) dst[m][k] = *(const LAS bf16x8*)(lds + PG8_SA(b, h) + aoff + m * 2048 + k * 1024); } while (0)
; #define PG8_LDB(dst, b, h) do { _Pragma("unroll") for (int n = 0; n < 2; ++n) _Pragma("unroll") for (int k = 0; k < 2; ++k) dst[n][k] = *(const LAS bf16x8*)(lds + PG8_SB(b, h) + boff + n * 2048 + k * 1024); } while (0)
; #define PG8_MMA(ai, bj, At, Bt) do { __builtin_amdgcn_s_setprio(1); _Pragma("unroll") for (int m = 0; m < 4; ++m) _Pragma("unroll") for (int n = 0; n < 2; ++n) _Pragma("unroll") for (int k = 0; k < 2; ++k) \
;         acc[ai][bj][m][n] = __builtin_amdgcn_mfma_f32_16x16x32_bf16(Bt[n][k], At[m][k], acc[ai][bj][m][n], 0, 0, 0); __builtin_amdgcn_s_setprio(0); } while (0)
; #define PG8_WAIT_V(n) asm volatile("s_waitcnt vmcnt(" #n ")" ::: "memory")
; #define PG8_WAIT_L(n) asm volatile("s_waitcnt lgkmcnt(" #n ")" ::: "memory")
; #define PG8_BAR __builtin_amdgcn_s_barrier()
; #define PG8_SCHED __builtin_amdgcn_sched_barrier(0)
; template <class Epi, class Sched>
; __device__ __forceinline__ void gemm_phase(LAS unsigned char* lds, const Gemm g, const Sched& S, const Epi& E, const int wave_s) {
;     ...
;             PG8_WAIT_V(8); PG8_WAIT_L(0); PG8_BAR; PG8_MMA(1, 0, At, B0); PG8_MMA(1, 1, At, B1); PG8_BAR; PG8_SCHED;
;             PG8_LDB(B0, 1, 0); PG8_LDB(B1, 1, 1); PG8_SCHED; PG8_LDA(At, 1, 0); PG8_STAGE(PG8_SA(0, 1), a2 + hstepA, voffA);
;             PG8_WAIT_V(8); PG8_WAIT_L(0); PG8_BAR; PG8_MMA(0, 0, At, B0); PG8_MMA(0, 1, At, B1); PG8_BAR; PG8_SCHED;
	s_setprio 1
	v_mfma_f32_16x16x32_bf16 v[60:63], v[152:155], v[184:187], v[60:63]
	v_mfma_f32_16x16x32_bf16 v[56:59], v[160:163], v[184:187], v[56:59]
	v_mfma_f32_16x16x32_bf16 v[52:55], v[152:155], v[192:195], v[52:55]
	v_mfma_f32_16x16x32_bf16 v[44:47], v[160:163], v[192:195], v[44:47]
	v_mfma_f32_16x16x32_bf16 v[36:39], v[152:155], v[200:203], v[36:39]
	v_mfma_f32_16x16x32_bf16 v[28:31], v[160:163], v[200:203], v[28:31]
	v_mfma_f32_16x16x32_bf16 v[20:23], v[152:155], v[210:213], v[20:23]
	v_mfma_f32_16x16x32_bf16 v[12:15], v[160:163], v[210:213], v[12:15]
	v_mfma_f32_16x16x32_bf16 v[60:63], v[156:159], v[188:191], v[60:63]
	v_mfma_f32_16x16x32_bf16 v[56:59], v[164:167], v[188:191], v[56:59]
	v_mfma_f32_16x16x32_bf16 v[52:55], v[156:159], v[196:199], v[52:55]
	v_mfma_f32_16x16x32_bf16 v[44:47], v[164:167], v[196:199], v[44:47]
	v_mfma_f32_16x16x32_bf16 v[36:39], v[156:159], v[204:207], v[36:39]
	v_mfma_f32_16x16x32_bf16 v[28:31], v[164:167], v[204:207], v[28:31]
	v_mfma_f32_16x16x32_bf16 v[20:23], v[156:159], v[214:217], v[20:23]
	v_mfma_f32_16x16x32_bf16 v[12:15], v[164:167], v[214:217], v[12:15]
	s_setprio 0
	s_setprio 1
	v_mfma_f32_16x16x32_bf16 v[48:51], v[168:171], v[184:187], v[48:51]
	v_mfma_f32_16x16x32_bf16 v[40:43], v[176:179], v[184:187], v[40:43]
	v_mfma_f32_16x16x32_bf16 v[32:35], v[168:171], v[192:195], v[32:35]
	v_mfma_f32_16x16x32_bf16 v[24:27], v[176:179], v[192:195], v[24:27]
	v_mfma_f32_16x16x32_bf16 v[16:19], v[168:171], v[200:203], v[16:19]
	v_mfma_f32_16x16x32_bf16 v[8:11], v[176:179], v[200:203], v[8:11]
	v_mfma_f32_16x16x32_bf16 v[4:7], v[168:171], v[210:213], v[4:7]
	v_mfma_f32_16x16x32_bf16 v[0:3], v[176:179], v[210:213], v[0:3]
	v_mfma_f32_16x16x32_bf16 v[48:51], v[172:175], v[188:191], v[48:51]
	v_mfma_f32_16x16x32_bf16 v[40:43], v[180:183], v[188:191], v[40:43]
	v_mfma_f32_16x16x32_bf16 v[32:35], v[172:175], v[196:199], v[32:35]
	v_mfma_f32_16x16x32_bf16 v[24:27], v[180:183], v[196:199], v[24:27]
	v_mfma_f32_16x16x32_bf16 v[16:19], v[172:175], v[204:207], v[16:19]
	v_mfma_f32_16x16x32_bf16 v[8:11], v[180:183], v[204:207], v[8:11]
	v_mfma_f32_16x16x32_bf16 v[4:7], v[172:175], v[214:217], v[4:7]
	v_mfma_f32_16x16x32_bf16 v[0:3], v[180:183], v[214:217], v[0:3]
	s_setprio 0
	s_barrier
	s_add_i32 s66, 0, 0x18000
	s_add_i32 s67, 0, 0x1c000
	v_add_u32_e32 v164, s66, v147
	v_add_u32_e32 v180, s67, v147
	ds_read_b128 v[152:155], v164
	ds_read_b128 v[156:159], v164 offset:1024
	ds_read_b128 v[160:163], v164 offset:2048
	ds_read_b128 v[164:167], v164 offset:3072
	ds_read_b128 v[168:171], v180
	ds_read_b128 v[172:175], v180 offset:1024
	ds_read_b128 v[176:179], v180 offset:2048
	ds_read_b128 v[180:183], v180 offset:3072
	s_add_u32 s46, s46, 0x40000
	s_addc_u32 s47, s47, 0
	s_mov_b32 m0, s37
	v_lshl_add_u64 v[224:225], s[46:47], 0, v[128:129]
	ds_read_b128 v[184:187], v151 offset:32768
	ds_read_b128 v[188:191], v151 offset:33792
	ds_read_b128 v[192:195], v151 offset:34816
	ds_read_b128 v[196:199], v151 offset:35840
	ds_read_b128 v[200:203], v151 offset:36864
	ds_read_b128 v[204:207], v151 offset:37888
	ds_read_b128 v[210:213], v151 offset:38912
	ds_read_b128 v[214:217], v151 offset:39936
	global_load_lds_dwordx4 v[224:225], off
	v_lshl_add_u64 v[224:225], s[46:47], 0, v[132:133]
	s_mov_b32 m0, s43
	s_nop 0
	global_load_lds_dwordx4 v[224:225], off
	s_waitcnt vmcnt(8) lgkmcnt(0)
	s_barrier
	s_setprio 1
	v_mfma_f32_16x16x32_bf16 v[124:127], v[152:155], v[184:187], v[124:127]
	v_mfma_f32_16x16x32_bf16 v[120:123], v[160:163], v[184:187], v[120:123]
	v_mfma_f32_16x16x32_bf16 v[116:119], v[152:155], v[192:195], v[116:119]
	v_mfma_f32_16x16x32_bf16 v[108:111], v[160:163], v[192:195], v[108:111]
	v_mfma_f32_16x16x32_bf16 v[100:103], v[152:155], v[200:203], v[100:103]
	v_mfma_f32_16x16x32_bf16 v[92:95], v[160:163], v[200:203], v[92:95]
	v_mfma_f32_16x16x32_bf16 v[84:87], v[152:155], v[210:213], v[84:87]
	v_mfma_f32_16x16x32_bf16 v[76:79], v[160:163], v[210:213], v[76:79]
	v_mfma_f32_16x16x32_bf16 v[124:127], v[156:159], v[188:191], v[124:127]
	v_mfma_f32_16x16x32_bf16 v[120:123], v[164:167], v[188:191], v[120:123]
	v_mfma_f32_16x16x32_bf16 v[116:119], v[156:159], v[196:199], v[116:119]
	v_mfma_f32_16x16x32_bf16 v[108:111], v[164:167], v[196:199], v[108:111]
	v_mfma_f32_16x16x32_bf16 v[100:103], v[156:159], v[204:207], v[100:103]
	v_mfma_f32_16x16x32_bf16 v[92:95], v[164:167], v[204:207], v[92:95]
	v_mfma_f32_16x16x32_bf16 v[84:87], v[156:159], v[214:217], v[84:87]
	v_mfma_f32_16x16x32_bf16 v[76:79], v[164:167], v[214:217], v[76:79]
	s_setprio 0
	s_setprio 1
	v_mfma_f32_16x16x32_bf16 v[112:115], v[168:171], v[184:187], v[112:115]
	v_mfma_f32_16x16x32_bf16 v[104:107], v[176:179], v[184:187], v[104:107]
	v_mfma_f32_16x16x32_bf16 v[96:99], v[168:171], v[192:195], v[96:99]
	v_mfma_f32_16x16x32_bf16 v[88:91], v[176:179], v[192:195], v[88:91]
	v_mfma_f32_16x16x32_bf16 v[80:83], v[168:171], v[200:203], v[80:83]
	v_mfma_f32_16x16x32_bf16 v[72:75], v[176:179], v[200:203], v[72:75]
	v_mfma_f32_16x16x32_bf16 v[68:71], v[168:171], v[210:213], v[68:71]
	v_mfma_f32_16x16x32_bf16 v[64:67], v[176:179], v[210:213], v[64:67]
	v_mfma_f32_16x16x32_bf16 v[112:115], v[172:175], v[188:191], v[112:115]
	v_mfma_f32_16x16x32_bf16 v[104:107], v[180:183], v[188:191], v[104:107]
	v_mfma_f32_16x16x32_bf16 v[96:99], v[172:175], v[196:199], v[96:99]
	v_mfma_f32_16x16x32_bf16 v[88:91], v[180:183], v[196:199], v[88:91]
	v_mfma_f32_16x16x32_bf16 v[80:83], v[172:175], v[204:207], v[80:83]
	v_mfma_f32_16x16x32_bf16 v[72:75], v[180:183], v[204:207], v[72:75]
	v_mfma_f32_16x16x32_bf16 v[68:71], v[172:175], v[214:217], v[68:71]
	v_mfma_f32_16x16x32_bf16 v[64:67], v[180:183], v[214:217], v[64:67]
	s_setprio 0
	s_barrier
; #define PG8_STAGE(bufoff, gbase, voff) do { _Pragma("unroll") for (int _i = 0; _i < 2; ++_i) \
;         __builtin_amdgcn_global_load_lds((const unsigned*)((const char*)(gbase) + (voff)[_i]), (LAS unsigned*)(lds + (bufoff) + ldsw + _i * 8192), 16, 0, 0); } while (0)
; #define PG8_LDA(dst, b, h) do { _Pragma("unroll") for (int m = 0; m < 4; ++m) _Pragma("unroll") for (int k = 0; k < 2; ++k) dst[m][k] = *(const LAS bf16x8*)(lds + PG8_SA(b, h) + aoff + m * 2048 + k * 1024); } while (0)
; #define PG8_MMA(ai, bj, At, Bt) do { __builtin_amdgcn_s_setprio(1); _Pragma("unroll") for (int m = 0; m < 4; ++m) _Pragma("unroll") for (int n = 0; n < 2; ++n) _Pragma("unroll") for (int k = 0; k < 2; ++k) \
;         acc[ai][bj][m][n] = __builtin_amdgcn_mfma_f32_16x16x32_bf16(Bt[n][k], At[m][k], acc[ai][bj][m][n], 0, 0, 0); __builtin_amdgcn_s_setprio(0); } while (0)
; #define PG8_WAIT_V(n) asm volatile("s_waitcnt vmcnt(" #n ")" ::: "memory")
; #define PG8_WAIT_L(n) asm volatile("s_waitcnt lgkmcnt(" #n ")" ::: "memory")
; #define PG8_BAR __builtin_amdgcn_s_barrier()
; #define PG8_SCHED __builtin_amdgcn_sched_barrier(0)
; template <class Epi, class Sched>
; __device__ __forceinline__ void gemm_phase(LAS unsigned char* lds, const Gemm g, const Sched& S, const Epi& E, const int wave_s) {
;     ...
;             PG8_LDA(At, 1, 1); PG8_STAGE(PG8_SB(1, 0), b3, voffB); PG8_STAGE(PG8_SB(1, 1), b3 + hstepB, voffB); PG8_STAGE(PG8_SA(1, 0), a3, voffA);
;             PG8_WAIT_V(8); PG8_WAIT_L(0); PG8_BAR; PG8_MMA(1, 0, At, B0); PG8_MMA(1, 1, At, B1); PG8_BAR; PG8_SCHED;
;         }
;         if (wr == 0) PG8_BAR;
	s_add_i32 s46, s66, s81
	v_lshl_add_u64 v[144:145], v[144:145], 0, s[14:15]
	s_mov_b32 m0, s46
	ds_read_b128 v[184:187], v151 offset:49152
	ds_read_b128 v[188:191], v151 offset:50176
	ds_read_b128 v[192:195], v151 offset:51200
	ds_read_b128 v[196:199], v151 offset:52224
	ds_read_b128 v[200:203], v151 offset:53248
	ds_read_b128 v[204:207], v151 offset:54272
	ds_read_b128 v[210:213], v151 offset:55296
	ds_read_b128 v[214:217], v151 offset:56320
	global_load_lds_dwordx4 v[144:145], off
	s_add_i32 m0, s46, 0x2000
	s_add_u32 s4, s4, 0x40080
	v_lshl_add_u64 v[144:145], v[218:219], 0, s[14:15]
	s_addc_u32 s5, s5, 0
	s_add_i32 s46, s67, s81
	global_load_lds_dwordx4 v[144:145], off
	v_lshl_add_u64 v[144:145], s[4:5], 0, v[130:131]
	s_mov_b32 m0, s46
	s_nop 0
	global_load_lds_dwordx4 v[144:145], off
	v_lshl_add_u64 v[144:145], s[4:5], 0, v[134:135]
	s_add_i32 m0, s46, 0x2000
	s_nop 0
	global_load_lds_dwordx4 v[144:145], off
	v_lshl_add_u64 v[144:145], v[220:221], 0, s[14:15]
	s_mov_b32 m0, s49
	s_nop 0
	global_load_lds_dwordx4 v[144:145], off
	v_lshl_add_u64 v[144:145], v[222:223], 0, s[14:15]
	s_mov_b32 m0, s50
	s_nop 0
	global_load_lds_dwordx4 v[144:145], off
	s_waitcnt vmcnt(8) lgkmcnt(0)
	s_barrier
	s_setprio 1
	v_mfma_f32_16x16x32_bf16 v[60:63], v[152:155], v[184:187], v[60:63]
	v_mfma_f32_16x16x32_bf16 v[56:59], v[160:163], v[184:187], v[56:59]
	v_mfma_f32_16x16x32_bf16 v[52:55], v[152:155], v[192:195], v[52:55]
	v_mfma_f32_16x16x32_bf16 v[44:47], v[160:163], v[192:195], v[44:47]
	v_mfma_f32_16x16x32_bf16 v[36:39], v[152:155], v[200:203], v[36:39]
	v_mfma_f32_16x16x32_bf16 v[28:31], v[160:163], v[200:203], v[28:31]
	v_mfma_f32_16x16x32_bf16 v[20:23], v[152:155], v[210:213], v[20:23]
	v_mfma_f32_16x16x32_bf16 v[12:15], v[160:163], v[210:213], v[12:15]
	v_mfma_f32_16x16x32_bf16 v[60:63], v[156:159], v[188:191], v[60:63]
	v_mfma_f32_16x16x32_bf16 v[56:59], v[164:167], v[188:191], v[56:59]
	v_mfma_f32_16x16x32_bf16 v[52:55], v[156:159], v[196:199], v[52:55]
	v_mfma_f32_16x16x32_bf16 v[44:47], v[164:167], v[196:199], v[44:47]
	v_mfma_f32_16x16x32_bf16 v[36:39], v[156:159], v[204:207], v[36:39]
	v_mfma_f32_16x16x32_bf16 v[28:31], v[164:167], v[204:207], v[28:31]
	v_mfma_f32_16x16x32_bf16 v[20:23], v[156:159], v[214:217], v[20:23]
	v_mfma_f32_16x16x32_bf16 v[12:15], v[164:167], v[214:217], v[12:15]
	s_setprio 0
	s_setprio 1
	v_mfma_f32_16x16x32_bf16 v[48:51], v[168:171], v[184:187], v[48:51]
	v_mfma_f32_16x16x32_bf16 v[40:43], v[176:179], v[184:187], v[40:43]
	v_mfma_f32_16x16x32_bf16 v[32:35], v[168:171], v[192:195], v[32:35]
	v_mfma_f32_16x16x32_bf16 v[24:27], v[176:179], v[192:195], v[24:27]
	v_mfma_f32_16x16x32_bf16 v[16:19], v[168:171], v[200:203], v[16:19]
	v_mfma_f32_16x16x32_bf16 v[8:11], v[176:179], v[200:203], v[8:11]
	v_mfma_f32_16x16x32_bf16 v[4:7], v[168:171], v[210:213], v[4:7]
	v_mfma_f32_16x16x32_bf16 v[0:3], v[176:179], v[210:213], v[0:3]
	v_mfma_f32_16x16x32_bf16 v[48:51], v[172:175], v[188:191], v[48:51]
	v_mfma_f32_16x16x32_bf16 v[40:43], v[180:183], v[188:191], v[40:43]
	v_mfma_f32_16x16x32_bf16 v[32:35], v[172:175], v[196:199], v[32:35]
	v_mfma_f32_16x16x32_bf16 v[24:27], v[180:183], v[196:199], v[24:27]
	v_mfma_f32_16x16x32_bf16 v[16:19], v[172:175], v[204:207], v[16:19]
	v_mfma_f32_16x16x32_bf16 v[8:11], v[180:183], v[204:207], v[8:11]
	v_mfma_f32_16x16x32_bf16 v[4:7], v[172:175], v[214:217], v[4:7]
	v_mfma_f32_16x16x32_bf16 v[0:3], v[180:183], v[214:217], v[0:3]
	s_setprio 0
	s_barrier
	s_add_i32 s65, s65, 2
	s_add_u32 s44, s44, 0x100
	s_addc_u32 s45, s45, 0
	s_add_u32 s63, s63, 0x100
	s_addc_u32 s64, s64, 0
	s_cmp_gt_u32 s65, 13
	s_cbranch_scc0 .LBB0_125
	s_and_b64 vcc, exec, s[16:17]
	s_cbranch_vccz .LBB0_128
	s_barrier

; #define PG8_STAGE(bufoff, gbase, voff) do { _Pragma("unroll") for (int _i = 0; _i < 2; ++_i) \
;         __builtin_amdgcn_global_load_lds((const unsigned*)((const char*)(gbase) + (voff)[_i]), (LAS unsigned*)(lds + (bufoff) + ldsw + _i * 8192), 16, 0, 0); } while (0)
; #define PG8_LDA(dst, b, h) do { _Pragma("unroll") for (int m = 0; m < 4; ++m) _Pragma("unroll") for (int k = 0; k < 2; ++k) dst[m][k] = *(const LAS bf16x8*)(lds + PG8_SA(b, h) + aoff + m * 2048 + k * 1024); } while (0)
; #define PG8_LDB(dst, b, h) do { _Pragma("unroll") for (int n = 0; n < 2; ++n) _Pragma("unroll") for (int k = 0; k < 2; ++k) dst[n][k] = *(const LAS bf16x8*)(lds + PG8_SB(b, h) + boff + n * 2048 + k * 1024); } while (0)
; #define PG8_MMA(ai, bj, At, Bt) do { __builtin_amdgcn_s_setprio(1); _Pragma("unroll") for (int m = 0; m < 4; ++m) _Pragma("unroll") for (int n = 0; n < 2; ++n) _Pragma("unroll") for (int k = 0; k < 2; ++k) \
;         acc[ai][bj][m][n] = __builtin_amdgcn_mfma_f32_16x16x32_bf16(Bt[n][k], At[m][k], acc[ai][bj][m][n], 0, 0, 0); __builtin_amdgcn_s_setprio(0); } while (0)
; #define PG8_WAIT_V(n) asm volatile("s_waitcnt vmcnt(" #n ")" ::: "memory")
; #define PG8_WAIT_L(n) asm volatile("s_waitcnt lgkmcnt(" #n ")" ::: "memory")
; #define PG8_BAR __builtin_amdgcn_s_barrier()
; #define PG8_SCHED __builtin_amdgcn_sched_barrier(0)
; template <class Epi, class Sched>
; __device__ __forceinline__ void gemm_phase(LAS unsigned char* lds, const Gemm g, const Sched& S, const Epi& E, const int wave_s) {
;     ...
;             const bool last = (t == nt - 2);
;             const char* a1 = cA + (size_t)(t + 1) * kstep;
;             const char* a2 = last ? nA : cA + (size_t)(t + 2) * kstep; const char* b2 = last ? nB : cB + (size_t)(t + 2) * kstep;
;             const char* a3 = a2 + kstep; const char* b3 = b2 + kstep;
;             PG8_LDB(B0, 0, 0); PG8_LDB(B1, 0, 1); PG8_SCHED; PG8_LDA(At, 0, 0); PG8_STAGE(PG8_SA(1, 1), a1 + hstepA, voffA);
;             PG8_WAIT_V(8); PG8_WAIT_L(0); PG8_BAR; PG8_MMA(0, 0, At, B0); PG8_MMA(0, 1, At, B1); PG8_BAR; PG8_SCHED;
;             PG8_LDA(At, 0, 1); PG8_STAGE(PG8_SB(0, 0), b2, voffB); PG8_STAGE(PG8_SB(0, 1), b2 + hstepB, voffB); PG8_STAGE(PG8_SA(0, 0), a2, voffA);
;             PG8_WAIT_V(8); PG8_WAIT_L(0); PG8_BAR; PG8_MMA(1, 0, At, B0); PG8_MMA(1, 1, At, B1); PG8_BAR; PG8_SCHED;
.LBB0_194:
	ds_read_b128 v[144:147], v151
	ds_read_b128 v[154:157], v151 offset:1024
	ds_read_b128 v[158:161], v151 offset:2048
	ds_read_b128 v[162:165], v151 offset:3072
	ds_read_b128 v[166:169], v152
	ds_read_b128 v[170:173], v152 offset:1024
	ds_read_b128 v[174:177], v152 offset:2048
	ds_read_b128 v[178:181], v152 offset:3072
	s_add_u32 s4, s24, 0xfffc0080
	s_addc_u32 s5, s25, -1
	s_cmp_eq_u32 s54, 12
	s_cselect_b32 s27, s19, s5
	s_cselect_b32 s26, s50, s4
	s_cselect_b32 s5, s17, s53
	s_cselect_b32 s4, s51, s52
	v_lshl_add_u64 v[206:207], s[24:25], 0, v[136:137]
	s_add_i32 m0, s30, 0xc000
	ds_read_b128 v[182:185], v153
	ds_read_b128 v[186:189], v153 offset:1024
	ds_read_b128 v[190:193], v153 offset:2048
	ds_read_b128 v[194:197], v153 offset:3072
	ds_read_b128 v[198:201], v153 offset:4096
	ds_read_b128 v[202:205], v153 offset:5120
	ds_read_b128 v[210:213], v153 offset:6144
	ds_read_b128 v[214:217], v153 offset:7168
	global_load_lds_dwordx4 v[206:207], off
	v_lshl_add_u64 v[206:207], s[24:25], 0, v[138:139]
	s_add_i32 m0, s30, 0xe000
	s_nop 0
	global_load_lds_dwordx4 v[206:207], off
	s_waitcnt vmcnt(8) lgkmcnt(0)
	s_barrier
	s_setprio 1
	v_mfma_f32_16x16x32_bf16 v[124:127], v[144:147], v[182:185], v[124:127]
	v_mfma_f32_16x16x32_bf16 v[120:123], v[158:161], v[182:185], v[120:123]
	v_mfma_f32_16x16x32_bf16 v[116:119], v[144:147], v[190:193], v[116:119]
	v_mfma_f32_16x16x32_bf16 v[108:111], v[158:161], v[190:193], v[108:111]
	v_mfma_f32_16x16x32_bf16 v[100:103], v[144:147], v[198:201], v[100:103]
	v_mfma_f32_16x16x32_bf16 v[92:95], v[158:161], v[198:201], v[92:95]
	v_mfma_f32_16x16x32_bf16 v[84:87], v[144:147], v[210:213], v[84:87]
	v_mfma_f32_16x16x32_bf16 v[76:79], v[158:161], v[210:213], v[76:79]
	v_mfma_f32_16x16x32_bf16 v[124:127], v[154:157], v[186:189], v[124:127]
	v_mfma_f32_16x16x32_bf16 v[120:123], v[162:165], v[186:189], v[120:123]
	v_mfma_f32_16x16x32_bf16 v[116:119], v[154:157], v[194:197], v[116:119]
	v_mfma_f32_16x16x32_bf16 v[108:111], v[162:165], v[194:197], v[108:111]
	v_mfma_f32_16x16x32_bf16 v[100:103], v[154:157], v[202:205], v[100:103]
	v_mfma_f32_16x16x32_bf16 v[92:95], v[162:165], v[202:205], v[92:95]
	v_mfma_f32_16x16x32_bf16 v[84:87], v[154:157], v[214:217], v[84:87]
	v_mfma_f32_16x16x32_bf16 v[76:79], v[162:165], v[214:217], v[76:79]
	s_setprio 0
	s_setprio 1
	v_mfma_f32_16x16x32_bf16 v[112:115], v[166:169], v[182:185], v[112:115]
	v_mfma_f32_16x16x32_bf16 v[104:107], v[174:177], v[182:185], v[104:107]
	v_mfma_f32_16x16x32_bf16 v[96:99], v[166:169], v[190:193], v[96:99]
	v_mfma_f32_16x16x32_bf16 v[88:91], v[174:177], v[190:193], v[88:91]
	v_mfma_f32_16x16x32_bf16 v[80:83], v[166:169], v[198:201], v[80:83]
	v_mfma_f32_16x16x32_bf16 v[72:75], v[174:177], v[198:201], v[72:75]
	v_mfma_f32_16x16x32_bf16 v[68:71], v[166:169], v[210:213], v[68:71]
	v_mfma_f32_16x16x32_bf16 v[64:67], v[174:177], v[210:213], v[64:67]
	v_mfma_f32_16x16x32_bf16 v[112:115], v[170:173], v[186:189], v[112:115]
	v_mfma_f32_16x16x32_bf16 v[104:107], v[178:181], v[186:189], v[104:107]
	v_mfma_f32_16x16x32_bf16 v[96:99], v[170:173], v[194:197], v[96:99]
	v_mfma_f32_16x16x32_bf16 v[88:91], v[178:181], v[194:197], v[88:91]
	v_mfma_f32_16x16x32_bf16 v[80:83], v[170:173], v[202:205], v[80:83]
	v_mfma_f32_16x16x32_bf16 v[72:75], v[178:181], v[202:205], v[72:75]
	v_mfma_f32_16x16x32_bf16 v[68:71], v[170:173], v[214:217], v[68:71]
	v_mfma_f32_16x16x32_bf16 v[64:67], v[178:181], v[214:217], v[64:67]
	s_setprio 0
	s_barrier
	s_add_i32 s55, s45, s81
	v_lshl_add_u64 v[206:207], s[4:5], 0, v[132:133]
	s_mov_b32 m0, s55
	ds_read_b128 v[182:185], v153 offset:16384
	ds_read_b128 v[186:189], v153 offset:17408
	ds_read_b128 v[190:193], v153 offset:18432
	ds_read_b128 v[194:197], v153 offset:19456
	ds_read_b128 v[198:201], v153 offset:20480
	ds_read_b128 v[202:205], v153 offset:21504
	ds_read_b128 v[210:213], v153 offset:22528
	ds_read_b128 v[214:217], v153 offset:23552
	global_load_lds_dwordx4 v[206:207], off
	s_add_i32 m0, s55, 0x2000
	s_add_u32 s58, s4, 0x40000
	v_lshl_add_u64 v[218:219], s[4:5], 0, v[128:129]
	s_addc_u32 s59, s5, 0
	s_add_i32 s55, s46, s81
	global_load_lds_dwordx4 v[218:219], off
	v_lshl_add_u64 v[220:221], s[58:59], 0, v[132:133]
	s_mov_b32 m0, s55
	v_lshl_add_u64 v[222:223], s[26:27], 0, v[130:131]
	global_load_lds_dwordx4 v[220:221], off
	v_lshl_add_u64 v[220:221], s[58:59], 0, v[128:129]
	s_add_i32 m0, s55, 0x2000
	s_nop 0
	global_load_lds_dwordx4 v[220:221], off
	v_lshl_add_u64 v[220:221], s[26:27], 0, v[134:135]
	s_mov_b32 m0, s30
	s_nop 0
	global_load_lds_dwordx4 v[220:221], off
	s_mov_b32 m0, s31
	s_nop 0
	global_load_lds_dwordx4 v[222:223], off
	s_waitcnt vmcnt(8) lgkmcnt(0)
	s_barrier
; #define PG8_STAGE(bufoff, gbase, voff) do { _Pragma("unroll") for (int _i = 0; _i < 2; ++_i) \
;         __builtin_amdgcn_global_load_lds((const unsigned*)((const char*)(gbase) + (voff)[_i]), (LAS unsigned*)(lds + (bufoff) + ldsw + _i * 8192), 16, 0, 0); } while (0)
; #define PG8_LDA(dst, b, h) do { _Pragma("unroll") for (int m = 0; m < 4; ++m) _Pragma("unroll") for (int k = 0; k < 2; ++k) dst[m][k] = *(const LAS bf16x8*)(lds + PG8_SA(b, h) + aoff + m * 2048 + k * 1024); } while (0)
; #define PG8_LDB(dst, b, h) do { _Pragma("unroll") for (int n = 0; n < 2; ++n) _Pragma("unroll") for (int k = 0; k < 2; ++k) dst[n][k] = *(const LAS bf16x8*)(lds + PG8_SB(b, h) + boff + n * 2048 + k * 1024); } while (0)
; #define PG8_MMA(ai, bj, At, Bt) do { __builtin_amdgcn_s_setprio(1); _Pragma("unroll") for (int m = 0; m < 4; ++m) _Pragma("unroll") for (int n = 0; n < 2; ++n) _Pragma("unroll") for (int k = 0; k < 2; ++k) \
;         acc[ai][bj][m][n] = __builtin_amdgcn_mfma_f32_16x16x32_bf16(Bt[n][k], At[m][k], acc[ai][bj][m][n], 0, 0, 0); __builtin_amdgcn_s_setprio(0); } while (0)
; #define PG8_WAIT_V(n) asm volatile("s_waitcnt vmcnt(" #n ")" ::: "memory")
; #define PG8_WAIT_L(n) asm volatile("s_waitcnt lgkmcnt(" #n ")" ::: "memory")
; #define PG8_BAR __builtin_amdgcn_s_barrier()
; #define PG8_SCHED __builtin_amdgcn_sched_barrier(0)
; template <class Epi, class Sched>
; __device__ __forceinline__ void gemm_phase(LAS unsigned char* lds, const Gemm g, const Sched& S, const Epi& E, const int wave_s) {
;     ...
;             PG8_WAIT_V(8); PG8_WAIT_L(0); PG8_BAR; PG8_MMA(1, 0, At, B0); PG8_MMA(1, 1, At, B1); PG8_BAR; PG8_SCHED;
;             PG8_LDB(B0, 1, 0); PG8_LDB(B1, 1, 1); PG8_SCHED; PG8_LDA(At, 1, 0); PG8_STAGE(PG8_SA(0, 1), a2 + hstepA, voffA);
;             PG8_WAIT_V(8); PG8_WAIT_L(0); PG8_BAR; PG8_MMA(0, 0, At, B0); PG8_MMA(0, 1, At, B1); PG8_BAR; PG8_SCHED;
	s_setprio 1
	v_mfma_f32_16x16x32_bf16 v[60:63], v[144:147], v[182:185], v[60:63]
	v_mfma_f32_16x16x32_bf16 v[56:59], v[158:161], v[182:185], v[56:59]
	v_mfma_f32_16x16x32_bf16 v[52:55], v[144:147], v[190:193], v[52:55]
	v_mfma_f32_16x16x32_bf16 v[44:47], v[158:161], v[190:193], v[44:47]
	v_mfma_f32_16x16x32_bf16 v[36:39], v[144:147], v[198:201], v[36:39]
	v_mfma_f32_16x16x32_bf16 v[28:31], v[158:161], v[198:201], v[28:31]
	v_mfma_f32_16x16x32_bf16 v[20:23], v[144:147], v[210:213], v[20:23]
	v_mfma_f32_16x16x32_bf16 v[12:15], v[158:161], v[210:213], v[12:15]
	v_mfma_f32_16x16x32_bf16 v[60:63], v[154:157], v[186:189], v[60:63]
	v_mfma_f32_16x16x32_bf16 v[56:59], v[162:165], v[186:189], v[56:59]
	v_mfma_f32_16x16x32_bf16 v[52:55], v[154:157], v[194:197], v[52:55]
	v_mfma_f32_16x16x32_bf16 v[44:47], v[162:165], v[194:197], v[44:47]
	v_mfma_f32_16x16x32_bf16 v[36:39], v[154:157], v[202:205], v[36:39]
	v_mfma_f32_16x16x32_bf16 v[28:31], v[162:165], v[202:205], v[28:31]
	v_mfma_f32_16x16x32_bf16 v[20:23], v[154:157], v[214:217], v[20:23]
	v_mfma_f32_16x16x32_bf16 v[12:15], v[162:165], v[214:217], v[12:15]
	s_setprio 0
	s_setprio 1
	v_mfma_f32_16x16x32_bf16 v[48:51], v[166:169], v[182:185], v[48:51]
	v_mfma_f32_16x16x32_bf16 v[40:43], v[174:177], v[182:185], v[40:43]
	v_mfma_f32_16x16x32_bf16 v[32:35], v[166:169], v[190:193], v[32:35]
	v_mfma_f32_16x16x32_bf16 v[24:27], v[174:177], v[190:193], v[24:27]
	v_mfma_f32_16x16x32_bf16 v[16:19], v[166:169], v[198:201], v[16:19]
	v_mfma_f32_16x16x32_bf16 v[8:11], v[174:177], v[198:201], v[8:11]
	v_mfma_f32_16x16x32_bf16 v[4:7], v[166:169], v[210:213], v[4:7]
	v_mfma_f32_16x16x32_bf16 v[0:3], v[174:177], v[210:213], v[0:3]
	v_mfma_f32_16x16x32_bf16 v[48:51], v[170:173], v[186:189], v[48:51]
	v_mfma_f32_16x16x32_bf16 v[40:43], v[178:181], v[186:189], v[40:43]
	v_mfma_f32_16x16x32_bf16 v[32:35], v[170:173], v[194:197], v[32:35]
	v_mfma_f32_16x16x32_bf16 v[24:27], v[178:181], v[194:197], v[24:27]
	v_mfma_f32_16x16x32_bf16 v[16:19], v[170:173], v[202:205], v[16:19]
	v_mfma_f32_16x16x32_bf16 v[8:11], v[178:181], v[202:205], v[8:11]
	v_mfma_f32_16x16x32_bf16 v[4:7], v[170:173], v[214:217], v[4:7]
	v_mfma_f32_16x16x32_bf16 v[0:3], v[178:181], v[214:217], v[0:3]
	s_setprio 0
	s_barrier
	s_add_i32 s55, 0, 0x18000
	s_add_i32 s57, 0, 0x1c000
	v_add_u32_e32 v162, s55, v149
	v_add_u32_e32 v178, s57, v149
	ds_read_b128 v[144:147], v162
	ds_read_b128 v[154:157], v162 offset:1024
	ds_read_b128 v[158:161], v162 offset:2048
	ds_read_b128 v[162:165], v162 offset:3072
	ds_read_b128 v[166:169], v178
	ds_read_b128 v[170:173], v178 offset:1024
	ds_read_b128 v[174:177], v178 offset:2048
	ds_read_b128 v[178:181], v178 offset:3072
	s_add_u32 s26, s26, 0x40000
	s_addc_u32 s27, s27, 0
	s_mov_b32 m0, s33
	v_lshl_add_u64 v[224:225], s[26:27], 0, v[134:135]
	ds_read_b128 v[182:185], v153 offset:32768
	ds_read_b128 v[186:189], v153 offset:33792
	ds_read_b128 v[190:193], v153 offset:34816
	ds_read_b128 v[194:197], v153 offset:35840
	ds_read_b128 v[198:201], v153 offset:36864
	ds_read_b128 v[202:205], v153 offset:37888
	ds_read_b128 v[210:213], v153 offset:38912
	ds_read_b128 v[214:217], v153 offset:39936
	global_load_lds_dwordx4 v[224:225], off
	v_lshl_add_u64 v[224:225], s[26:27], 0, v[130:131]
	s_mov_b32 m0, s35
	s_nop 0
	global_load_lds_dwordx4 v[224:225], off
	s_waitcnt vmcnt(8) lgkmcnt(0)
	s_barrier
	s_setprio 1
	v_mfma_f32_16x16x32_bf16 v[124:127], v[144:147], v[182:185], v[124:127]
	v_mfma_f32_16x16x32_bf16 v[120:123], v[158:161], v[182:185], v[120:123]
	v_mfma_f32_16x16x32_bf16 v[116:119], v[144:147], v[190:193], v[116:119]
	v_mfma_f32_16x16x32_bf16 v[108:111], v[158:161], v[190:193], v[108:111]
	v_mfma_f32_16x16x32_bf16 v[100:103], v[144:147], v[198:201], v[100:103]
	v_mfma_f32_16x16x32_bf16 v[92:95], v[158:161], v[198:201], v[92:95]
	v_mfma_f32_16x16x32_bf16 v[84:87], v[144:147], v[210:213], v[84:87]
	v_mfma_f32_16x16x32_bf16 v[76:79], v[158:161], v[210:213], v[76:79]
	v_mfma_f32_16x16x32_bf16 v[124:127], v[154:157], v[186:189], v[124:127]
	v_mfma_f32_16x16x32_bf16 v[120:123], v[162:165], v[186:189], v[120:123]
	v_mfma_f32_16x16x32_bf16 v[116:119], v[154:157], v[194:197], v[116:119]
	v_mfma_f32_16x16x32_bf16 v[108:111], v[162:165], v[194:197], v[108:111]
	v_mfma_f32_16x16x32_bf16 v[100:103], v[154:157], v[202:205], v[100:103]
	v_mfma_f32_16x16x32_bf16 v[92:95], v[162:165], v[202:205], v[92:95]
	v_mfma_f32_16x16x32_bf16 v[84:87], v[154:157], v[214:217], v[84:87]
	v_mfma_f32_16x16x32_bf16 v[76:79], v[162:165], v[214:217], v[76:79]
	s_setprio 0
	s_setprio 1
	v_mfma_f32_16x16x32_bf16 v[112:115], v[166:169], v[182:185], v[112:115]
	v_mfma_f32_16x16x32_bf16 v[104:107], v[174:177], v[182:185], v[104:107]
	v_mfma_f32_16x16x32_bf16 v[96:99], v[166:169], v[190:193], v[96:99]
	v_mfma_f32_16x16x32_bf16 v[88:91], v[174:177], v[190:193], v[88:91]
	v_mfma_f32_16x16x32_bf16 v[80:83], v[166:169], v[198:201], v[80:83]
	v_mfma_f32_16x16x32_bf16 v[72:75], v[174:177], v[198:201], v[72:75]
	v_mfma_f32_16x16x32_bf16 v[68:71], v[166:169], v[210:213], v[68:71]
	v_mfma_f32_16x16x32_bf16 v[64:67], v[174:177], v[210:213], v[64:67]
	v_mfma_f32_16x16x32_bf16 v[112:115], v[170:173], v[186:189], v[112:115]
	v_mfma_f32_16x16x32_bf16 v[104:107], v[178:181], v[186:189], v[104:107]
	v_mfma_f32_16x16x32_bf16 v[96:99], v[170:173], v[194:197], v[96:99]
	v_mfma_f32_16x16x32_bf16 v[88:91], v[178:181], v[194:197], v[88:91]
	v_mfma_f32_16x16x32_bf16 v[80:83], v[170:173], v[202:205], v[80:83]
	v_mfma_f32_16x16x32_bf16 v[72:75], v[178:181], v[202:205], v[72:75]
	v_mfma_f32_16x16x32_bf16 v[68:71], v[170:173], v[214:217], v[68:71]
	v_mfma_f32_16x16x32_bf16 v[64:67], v[178:181], v[214:217], v[64:67]
	s_setprio 0
	s_barrier
; #define PG8_STAGE(bufoff, gbase, voff) do { _Pragma("unroll") for (int _i = 0; _i < 2; ++_i) \
;         __builtin_amdgcn_global_load_lds((const unsigned*)((const char*)(gbase) + (voff)[_i]), (LAS unsigned*)(lds + (bufoff) + ldsw + _i * 8192), 16, 0, 0); } while (0)
; #define PG8_LDA(dst, b, h) do { _Pragma("unroll") for (int m = 0; m < 4; ++m) _Pragma("unroll") for (int k = 0; k < 2; ++k) dst[m][k] = *(const LAS bf16x8*)(lds + PG8_SA(b, h) + aoff + m * 2048 + k * 1024); } while (0)
; #define PG8_MMA(ai, bj, At, Bt) do { __builtin_amdgcn_s_setprio(1); _Pragma("unroll") for (int m = 0; m < 4; ++m) _Pragma("unroll") for (int n = 0; n < 2; ++n) _Pragma("unroll") for (int k = 0; k < 2; ++k) \
;         acc[ai][bj][m][n] = __builtin_amdgcn_mfma_f32_16x16x32_bf16(Bt[n][k], At[m][k], acc[ai][bj][m][n], 0, 0, 0); __builtin_amdgcn_s_setprio(0); } while (0)
; #define PG8_WAIT_V(n) asm volatile("s_waitcnt vmcnt(" #n ")" ::: "memory")
; #define PG8_WAIT_L(n) asm volatile("s_waitcnt lgkmcnt(" #n ")" ::: "memory")
; #define PG8_BAR __builtin_amdgcn_s_barrier()
; #define PG8_SCHED __builtin_amdgcn_sched_barrier(0)
; template <class Epi, class Sched>
; __device__ __forceinline__ void gemm_phase(LAS unsigned char* lds, const Gemm g, const Sched& S, const Epi& E, const int wave_s) {
;     ...
;             PG8_LDA(At, 1, 1); PG8_STAGE(PG8_SB(1, 0), b3, voffB); PG8_STAGE(PG8_SB(1, 1), b3 + hstepB, voffB); PG8_STAGE(PG8_SA(1, 0), a3, voffA);
;             PG8_WAIT_V(8); PG8_WAIT_L(0); PG8_BAR; PG8_MMA(1, 0, At, B0); PG8_MMA(1, 1, At, B1); PG8_BAR; PG8_SCHED;
;         }
;         if (wr == 0) PG8_BAR;
	s_add_i32 s26, s55, s81
	v_lshl_add_u64 v[206:207], v[206:207], 0, s[12:13]
	s_mov_b32 m0, s26
	ds_read_b128 v[182:185], v153 offset:49152
	ds_read_b128 v[186:189], v153 offset:50176
	ds_read_b128 v[190:193], v153 offset:51200
	ds_read_b128 v[194:197], v153 offset:52224
	ds_read_b128 v[198:201], v153 offset:53248
	ds_read_b128 v[202:205], v153 offset:54272
	ds_read_b128 v[210:213], v153 offset:55296
	ds_read_b128 v[214:217], v153 offset:56320
	global_load_lds_dwordx4 v[206:207], off
	s_add_i32 m0, s26, 0x2000
	s_add_u32 s4, s4, 0x40080
	v_lshl_add_u64 v[206:207], v[218:219], 0, s[12:13]
	s_addc_u32 s5, s5, 0
	s_add_i32 s26, s57, s81
	global_load_lds_dwordx4 v[206:207], off
	v_lshl_add_u64 v[206:207], s[4:5], 0, v[132:133]
	s_mov_b32 m0, s26
	s_nop 0
	global_load_lds_dwordx4 v[206:207], off
	v_lshl_add_u64 v[206:207], s[4:5], 0, v[128:129]
	s_add_i32 m0, s26, 0x2000
	s_nop 0
	global_load_lds_dwordx4 v[206:207], off
	v_lshl_add_u64 v[206:207], v[220:221], 0, s[12:13]
	s_mov_b32 m0, s41
	s_nop 0
	global_load_lds_dwordx4 v[206:207], off
	v_lshl_add_u64 v[206:207], v[222:223], 0, s[12:13]
	s_mov_b32 m0, s42
	s_nop 0
	global_load_lds_dwordx4 v[206:207], off
	s_waitcnt vmcnt(8) lgkmcnt(0)
	s_barrier
	s_setprio 1
	v_mfma_f32_16x16x32_bf16 v[60:63], v[144:147], v[182:185], v[60:63]
	v_mfma_f32_16x16x32_bf16 v[56:59], v[158:161], v[182:185], v[56:59]
	v_mfma_f32_16x16x32_bf16 v[52:55], v[144:147], v[190:193], v[52:55]
	v_mfma_f32_16x16x32_bf16 v[44:47], v[158:161], v[190:193], v[44:47]
	v_mfma_f32_16x16x32_bf16 v[36:39], v[144:147], v[198:201], v[36:39]
	v_mfma_f32_16x16x32_bf16 v[28:31], v[158:161], v[198:201], v[28:31]
	v_mfma_f32_16x16x32_bf16 v[20:23], v[144:147], v[210:213], v[20:23]
	v_mfma_f32_16x16x32_bf16 v[12:15], v[158:161], v[210:213], v[12:15]
	v_mfma_f32_16x16x32_bf16 v[60:63], v[154:157], v[186:189], v[60:63]
	v_mfma_f32_16x16x32_bf16 v[56:59], v[162:165], v[186:189], v[56:59]
	v_mfma_f32_16x16x32_bf16 v[52:55], v[154:157], v[194:197], v[52:55]
	v_mfma_f32_16x16x32_bf16 v[44:47], v[162:165], v[194:197], v[44:47]
	v_mfma_f32_16x16x32_bf16 v[36:39], v[154:157], v[202:205], v[36:39]
	v_mfma_f32_16x16x32_bf16 v[28:31], v[162:165], v[202:205], v[28:31]
	v_mfma_f32_16x16x32_bf16 v[20:23], v[154:157], v[214:217], v[20:23]
	v_mfma_f32_16x16x32_bf16 v[12:15], v[162:165], v[214:217], v[12:15]
	s_setprio 0
	s_setprio 1
	v_mfma_f32_16x16x32_bf16 v[48:51], v[166:169], v[182:185], v[48:51]
	v_mfma_f32_16x16x32_bf16 v[40:43], v[174:177], v[182:185], v[40:43]
	v_mfma_f32_16x16x32_bf16 v[32:35], v[166:169], v[190:193], v[32:35]
	v_mfma_f32_16x16x32_bf16 v[24:27], v[174:177], v[190:193], v[24:27]
	v_mfma_f32_16x16x32_bf16 v[16:19], v[166:169], v[198:201], v[16:19]
	v_mfma_f32_16x16x32_bf16 v[8:11], v[174:177], v[198:201], v[8:11]
	v_mfma_f32_16x16x32_bf16 v[4:7], v[166:169], v[210:213], v[4:7]
	v_mfma_f32_16x16x32_bf16 v[0:3], v[174:177], v[210:213], v[0:3]
	v_mfma_f32_16x16x32_bf16 v[48:51], v[170:173], v[186:189], v[48:51]
	v_mfma_f32_16x16x32_bf16 v[40:43], v[178:181], v[186:189], v[40:43]
	v_mfma_f32_16x16x32_bf16 v[32:35], v[170:173], v[194:197], v[32:35]
	v_mfma_f32_16x16x32_bf16 v[24:27], v[178:181], v[194:197], v[24:27]
	v_mfma_f32_16x16x32_bf16 v[16:19], v[170:173], v[202:205], v[16:19]
	v_mfma_f32_16x16x32_bf16 v[8:11], v[178:181], v[202:205], v[8:11]
	v_mfma_f32_16x16x32_bf16 v[4:7], v[170:173], v[214:217], v[4:7]
	v_mfma_f32_16x16x32_bf16 v[0:3], v[178:181], v[214:217], v[0:3]
	s_setprio 0
	s_barrier
	s_add_i32 s54, s54, 2
	s_add_u32 s24, s24, 0x100
	s_addc_u32 s25, s25, 0
	s_add_u32 s52, s52, 0x100
	s_addc_u32 s53, s53, 0
	s_cmp_gt_u32 s54, 13
	s_cbranch_scc0 .LBB0_194
	s_and_b64 vcc, exec, s[14:15]
	s_cbranch_vccz .LBB0_197
	s_barrier

; #define PG8_STAGE(bufoff, gbase, voff) do { _Pragma("unroll") for (int _i = 0; _i < 2; ++_i) \
;         __builtin_amdgcn_global_load_lds((const unsigned*)((const char*)(gbase) + (voff)[_i]), (LAS unsigned*)(lds + (bufoff) + ldsw + _i * 8192), 16, 0, 0); } while (0)
; #define PG8_LDA(dst, b, h) do { _Pragma("unroll") for (int m = 0; m < 4; ++m) _Pragma("unroll") for (int k = 0; k < 2; ++k) dst[m][k] = *(const LAS bf16x8*)(lds + PG8_SA(b, h) + aoff + m * 2048 + k * 1024); } while (0)
; #define PG8_LDB(dst, b, h) do { _Pragma("unroll") for (int n = 0; n < 2; ++n) _Pragma("unroll") for (int k = 0; k < 2; ++k) dst[n][k] = *(const LAS bf16x8*)(lds + PG8_SB(b, h) + boff + n * 2048 + k * 1024); } while (0)
; #define PG8_MMA(ai, bj, At, Bt) do { __builtin_amdgcn_s_setprio(1); _Pragma("unroll") for (int m = 0; m < 4; ++m) _Pragma("unroll") for (int n = 0; n < 2; ++n) _Pragma("unroll") for (int k = 0; k < 2; ++k) \
;         acc[ai][bj][m][n] = __builtin_amdgcn_mfma_f32_16x16x32_bf16(Bt[n][k], At[m][k], acc[ai][bj][m][n], 0, 0, 0); __builtin_amdgcn_s_setprio(0); } while (0)
; #define PG8_WAIT_V(n) asm volatile("s_waitcnt vmcnt(" #n ")" ::: "memory")
; #define PG8_WAIT_L(n) asm volatile("s_waitcnt lgkmcnt(" #n ")" ::: "memory")
; #define PG8_BAR __builtin_amdgcn_s_barrier()
; #define PG8_SCHED __builtin_amdgcn_sched_barrier(0)
; template <class Epi, class Sched>
; __device__ __forceinline__ void gemm_phase(LAS unsigned char* lds, const Gemm g, const Sched& S, const Epi& E, const int wave_s) {
;     ...
;             const bool last = (t == nt - 2);
;             const char* a1 = cA + (size_t)(t + 1) * kstep;
;             const char* a2 = last ? nA : cA + (size_t)(t + 2) * kstep; const char* b2 = last ? nB : cB + (size_t)(t + 2) * kstep;
;             const char* a3 = a2 + kstep; const char* b3 = b2 + kstep;
;             PG8_LDB(B0, 0, 0); PG8_LDB(B1, 0, 1); PG8_SCHED; PG8_LDA(At, 0, 0); PG8_STAGE(PG8_SA(1, 1), a1 + hstepA, voffA);
;             PG8_WAIT_V(8); PG8_WAIT_L(0); PG8_BAR; PG8_MMA(0, 0, At, B0); PG8_MMA(0, 1, At, B1); PG8_BAR; PG8_SCHED;
;             PG8_LDA(At, 0, 1); PG8_STAGE(PG8_SB(0, 0), b2, voffB); PG8_STAGE(PG8_SB(0, 1), b2 + hstepB, voffB); PG8_STAGE(PG8_SA(0, 0), a2, voffA);
;             PG8_WAIT_V(8); PG8_WAIT_L(0); PG8_BAR; PG8_MMA(1, 0, At, B0); PG8_MMA(1, 1, At, B1); PG8_BAR; PG8_SCHED;
.LBB0_375:
	ds_read_b128 v[158:161], v155
	ds_read_b128 v[162:165], v155 offset:1024
	ds_read_b128 v[166:169], v155 offset:2048
	ds_read_b128 v[170:173], v155 offset:3072
	ds_read_b128 v[174:177], v156
	ds_read_b128 v[178:181], v156 offset:1024
	ds_read_b128 v[182:185], v156 offset:2048
	ds_read_b128 v[186:189], v156 offset:3072
	s_add_u32 s4, s22, 0x100
	s_addc_u32 s5, s23, 0
	s_cmp_eq_u32 s48, 2
	s_cselect_b32 s25, s19, s5
	s_cselect_b32 s24, s18, s4
	s_cselect_b32 s9, s21, s47
	s_cselect_b32 s8, s20, s46
	v_lshl_add_u64 v[150:151], s[22:23], 0, v[142:143]
	s_add_i32 m0, s27, 0xc000
	ds_read_b128 v[190:193], v157
	ds_read_b128 v[194:197], v157 offset:1024
	ds_read_b128 v[198:201], v157 offset:2048
	ds_read_b128 v[202:205], v157 offset:3072
	ds_read_b128 v[210:213], v157 offset:4096
	ds_read_b128 v[214:217], v157 offset:5120
	ds_read_b128 v[218:221], v157 offset:6144
	ds_read_b128 v[222:225], v157 offset:7168
	global_load_lds_dwordx4 v[150:151], off
	v_lshl_add_u64 v[150:151], s[22:23], 0, v[144:145]
	s_add_i32 m0, s27, 0xe000
	s_nop 0
	global_load_lds_dwordx4 v[150:151], off
	s_waitcnt vmcnt(8) lgkmcnt(0)
	s_barrier
	s_setprio 1
	v_mfma_f32_16x16x32_bf16 v[124:127], v[158:161], v[190:193], v[124:127]
	v_mfma_f32_16x16x32_bf16 v[120:123], v[166:169], v[190:193], v[120:123]
	v_mfma_f32_16x16x32_bf16 v[108:111], v[158:161], v[198:201], v[108:111]
	v_mfma_f32_16x16x32_bf16 v[104:107], v[166:169], v[198:201], v[104:107]
	v_mfma_f32_16x16x32_bf16 v[92:95], v[158:161], v[210:213], v[92:95]
	v_mfma_f32_16x16x32_bf16 v[88:91], v[166:169], v[210:213], v[88:91]
	v_mfma_f32_16x16x32_bf16 v[76:79], v[158:161], v[218:221], v[76:79]
	v_mfma_f32_16x16x32_bf16 v[72:75], v[166:169], v[218:221], v[72:75]
	v_mfma_f32_16x16x32_bf16 v[124:127], v[162:165], v[194:197], v[124:127]
	v_mfma_f32_16x16x32_bf16 v[120:123], v[170:173], v[194:197], v[120:123]
	v_mfma_f32_16x16x32_bf16 v[108:111], v[162:165], v[202:205], v[108:111]
	v_mfma_f32_16x16x32_bf16 v[104:107], v[170:173], v[202:205], v[104:107]
	v_mfma_f32_16x16x32_bf16 v[92:95], v[162:165], v[214:217], v[92:95]
	v_mfma_f32_16x16x32_bf16 v[88:91], v[170:173], v[214:217], v[88:91]
	v_mfma_f32_16x16x32_bf16 v[76:79], v[162:165], v[222:225], v[76:79]
	v_mfma_f32_16x16x32_bf16 v[72:75], v[170:173], v[222:225], v[72:75]
	s_setprio 0
	s_setprio 1
	v_mfma_f32_16x16x32_bf16 v[116:119], v[174:177], v[190:193], v[116:119]
	v_mfma_f32_16x16x32_bf16 v[112:115], v[182:185], v[190:193], v[112:115]
	v_mfma_f32_16x16x32_bf16 v[100:103], v[174:177], v[198:201], v[100:103]
	v_mfma_f32_16x16x32_bf16 v[96:99], v[182:185], v[198:201], v[96:99]
	v_mfma_f32_16x16x32_bf16 v[84:87], v[174:177], v[210:213], v[84:87]
	v_mfma_f32_16x16x32_bf16 v[80:83], v[182:185], v[210:213], v[80:83]
	v_mfma_f32_16x16x32_bf16 v[68:71], v[174:177], v[218:221], v[68:71]
	v_mfma_f32_16x16x32_bf16 v[64:67], v[182:185], v[218:221], v[64:67]
	v_mfma_f32_16x16x32_bf16 v[116:119], v[178:181], v[194:197], v[116:119]
	v_mfma_f32_16x16x32_bf16 v[112:115], v[186:189], v[194:197], v[112:115]
	v_mfma_f32_16x16x32_bf16 v[100:103], v[178:181], v[202:205], v[100:103]
	v_mfma_f32_16x16x32_bf16 v[96:99], v[186:189], v[202:205], v[96:99]
	v_mfma_f32_16x16x32_bf16 v[84:87], v[178:181], v[214:217], v[84:87]
	v_mfma_f32_16x16x32_bf16 v[80:83], v[186:189], v[214:217], v[80:83]
	v_mfma_f32_16x16x32_bf16 v[68:71], v[178:181], v[222:225], v[68:71]
	v_mfma_f32_16x16x32_bf16 v[64:67], v[186:189], v[222:225], v[64:67]
	s_setprio 0
	s_barrier
	s_add_i32 s22, s39, s81
	v_lshl_add_u64 v[150:151], s[8:9], 0, v[130:131]
	s_mov_b32 m0, s22
	ds_read_b128 v[190:193], v157 offset:16384
	ds_read_b128 v[194:197], v157 offset:17408
	ds_read_b128 v[198:201], v157 offset:18432
	ds_read_b128 v[202:205], v157 offset:19456
	ds_read_b128 v[210:213], v157 offset:20480
	ds_read_b128 v[214:217], v157 offset:21504
	ds_read_b128 v[218:221], v157 offset:22528
	ds_read_b128 v[222:225], v157 offset:23552
	global_load_lds_dwordx4 v[150:151], off
	s_add_i32 m0, s22, 0x2000
	s_add_u32 s22, s8, 0x18000
	v_lshl_add_u64 v[206:207], s[8:9], 0, v[134:135]
	s_addc_u32 s23, s9, 0
	s_add_i32 s49, s40, s81
	global_load_lds_dwordx4 v[206:207], off
	v_lshl_add_u64 v[226:227], s[22:23], 0, v[130:131]
	s_mov_b32 m0, s49
	v_lshl_add_u64 v[228:229], s[24:25], 0, v[132:133]
	global_load_lds_dwordx4 v[226:227], off
	v_lshl_add_u64 v[226:227], s[22:23], 0, v[134:135]
	s_add_i32 m0, s49, 0x2000
	s_nop 0
	global_load_lds_dwordx4 v[226:227], off
	v_lshl_add_u64 v[226:227], s[24:25], 0, v[128:129]
	s_mov_b32 m0, s27
	s_nop 0
	global_load_lds_dwordx4 v[226:227], off
	s_mov_b32 m0, s28
	s_nop 0
	global_load_lds_dwordx4 v[228:229], off
	s_waitcnt vmcnt(8) lgkmcnt(0)
	s_barrier
; #define PG8_STAGE(bufoff, gbase, voff) do { _Pragma("unroll") for (int _i = 0; _i < 2; ++_i) \
;         __builtin_amdgcn_global_load_lds((const unsigned*)((const char*)(gbase) + (voff)[_i]), (LAS unsigned*)(lds + (bufoff) + ldsw + _i * 8192), 16, 0, 0); } while (0)
; #define PG8_LDA(dst, b, h) do { _Pragma("unroll") for (int m = 0; m < 4; ++m) _Pragma("unroll") for (int k = 0; k < 2; ++k) dst[m][k] = *(const LAS bf16x8*)(lds + PG8_SA(b, h) + aoff + m * 2048 + k * 1024); } while (0)
; #define PG8_LDB(dst, b, h) do { _Pragma("unroll") for (int n = 0; n < 2; ++n) _Pragma("unroll") for (int k = 0; k < 2; ++k) dst[n][k] = *(const LAS bf16x8*)(lds + PG8_SB(b, h) + boff + n * 2048 + k * 1024); } while (0)
; #define PG8_MMA(ai, bj, At, Bt) do { __builtin_amdgcn_s_setprio(1); _Pragma("unroll") for (int m = 0; m < 4; ++m) _Pragma("unroll") for (int n = 0; n < 2; ++n) _Pragma("unroll") for (int k = 0; k < 2; ++k) \
;         acc[ai][bj][m][n] = __builtin_amdgcn_mfma_f32_16x16x32_bf16(Bt[n][k], At[m][k], acc[ai][bj][m][n], 0, 0, 0); __builtin_amdgcn_s_setprio(0); } while (0)
; #define PG8_WAIT_V(n) asm volatile("s_waitcnt vmcnt(" #n ")" ::: "memory")
; #define PG8_WAIT_L(n) asm volatile("s_waitcnt lgkmcnt(" #n ")" ::: "memory")
; #define PG8_BAR __builtin_amdgcn_s_barrier()
; #define PG8_SCHED __builtin_amdgcn_sched_barrier(0)
; template <class Epi, class Sched>
; __device__ __forceinline__ void gemm_phase(LAS unsigned char* lds, const Gemm g, const Sched& S, const Epi& E, const int wave_s) {
;     ...
;             PG8_WAIT_V(8); PG8_WAIT_L(0); PG8_BAR; PG8_MMA(1, 0, At, B0); PG8_MMA(1, 1, At, B1); PG8_BAR; PG8_SCHED;
;             PG8_LDB(B0, 1, 0); PG8_LDB(B1, 1, 1); PG8_SCHED; PG8_LDA(At, 1, 0); PG8_STAGE(PG8_SA(0, 1), a2 + hstepA, voffA);
;             PG8_WAIT_V(8); PG8_WAIT_L(0); PG8_BAR; PG8_MMA(0, 0, At, B0); PG8_MMA(0, 1, At, B1); PG8_BAR; PG8_SCHED;
	s_setprio 1
	v_mfma_f32_16x16x32_bf16 v[60:63], v[158:161], v[190:193], v[60:63]
	v_mfma_f32_16x16x32_bf16 v[56:59], v[166:169], v[190:193], v[56:59]
	v_mfma_f32_16x16x32_bf16 v[44:47], v[158:161], v[198:201], v[44:47]
	v_mfma_f32_16x16x32_bf16 v[40:43], v[166:169], v[198:201], v[40:43]
	v_mfma_f32_16x16x32_bf16 v[28:31], v[158:161], v[210:213], v[28:31]
	v_mfma_f32_16x16x32_bf16 v[24:27], v[166:169], v[210:213], v[24:27]
	v_mfma_f32_16x16x32_bf16 v[12:15], v[158:161], v[218:221], v[12:15]
	v_mfma_f32_16x16x32_bf16 v[8:11], v[166:169], v[218:221], v[8:11]
	v_mfma_f32_16x16x32_bf16 v[60:63], v[162:165], v[194:197], v[60:63]
	v_mfma_f32_16x16x32_bf16 v[56:59], v[170:173], v[194:197], v[56:59]
	v_mfma_f32_16x16x32_bf16 v[44:47], v[162:165], v[202:205], v[44:47]
	v_mfma_f32_16x16x32_bf16 v[40:43], v[170:173], v[202:205], v[40:43]
	v_mfma_f32_16x16x32_bf16 v[28:31], v[162:165], v[214:217], v[28:31]
	v_mfma_f32_16x16x32_bf16 v[24:27], v[170:173], v[214:217], v[24:27]
	v_mfma_f32_16x16x32_bf16 v[12:15], v[162:165], v[222:225], v[12:15]
	v_mfma_f32_16x16x32_bf16 v[8:11], v[170:173], v[222:225], v[8:11]
	s_setprio 0
	s_setprio 1
	v_mfma_f32_16x16x32_bf16 v[52:55], v[174:177], v[190:193], v[52:55]
	v_mfma_f32_16x16x32_bf16 v[48:51], v[182:185], v[190:193], v[48:51]
	v_mfma_f32_16x16x32_bf16 v[36:39], v[174:177], v[198:201], v[36:39]
	v_mfma_f32_16x16x32_bf16 v[32:35], v[182:185], v[198:201], v[32:35]
	v_mfma_f32_16x16x32_bf16 v[20:23], v[174:177], v[210:213], v[20:23]
	v_mfma_f32_16x16x32_bf16 v[16:19], v[182:185], v[210:213], v[16:19]
	v_mfma_f32_16x16x32_bf16 v[4:7], v[174:177], v[218:221], v[4:7]
	v_mfma_f32_16x16x32_bf16 v[0:3], v[182:185], v[218:221], v[0:3]
	v_mfma_f32_16x16x32_bf16 v[52:55], v[178:181], v[194:197], v[52:55]
	v_mfma_f32_16x16x32_bf16 v[48:51], v[186:189], v[194:197], v[48:51]
	v_mfma_f32_16x16x32_bf16 v[36:39], v[178:181], v[202:205], v[36:39]
	v_mfma_f32_16x16x32_bf16 v[32:35], v[186:189], v[202:205], v[32:35]
	v_mfma_f32_16x16x32_bf16 v[20:23], v[178:181], v[214:217], v[20:23]
	v_mfma_f32_16x16x32_bf16 v[16:19], v[186:189], v[214:217], v[16:19]
	v_mfma_f32_16x16x32_bf16 v[4:7], v[178:181], v[222:225], v[4:7]
	v_mfma_f32_16x16x32_bf16 v[0:3], v[186:189], v[222:225], v[0:3]
	s_setprio 0
	s_barrier
	s_add_i32 s49, 0, 0x18000
	v_add_u32_e32 v136, s49, v153
	s_add_i32 s50, 0, 0x1c000
	ds_read_b128 v[158:161], v136
	ds_read_b128 v[162:165], v136 offset:1024
	ds_read_b128 v[166:169], v136 offset:2048
	ds_read_b128 v[170:173], v136 offset:3072
	v_add_u32_e32 v136, s50, v153
	ds_read_b128 v[174:177], v136
	ds_read_b128 v[178:181], v136 offset:1024
	ds_read_b128 v[182:185], v136 offset:2048
	ds_read_b128 v[186:189], v136 offset:3072
	s_add_u32 s22, s24, 0xf0000
	s_addc_u32 s23, s25, 0
	s_mov_b32 m0, s29
	v_lshl_add_u64 v[230:231], s[22:23], 0, v[128:129]
	ds_read_b128 v[190:193], v157 offset:32768
	ds_read_b128 v[194:197], v157 offset:33792
	ds_read_b128 v[198:201], v157 offset:34816
	ds_read_b128 v[202:205], v157 offset:35840
	ds_read_b128 v[210:213], v157 offset:36864
	ds_read_b128 v[214:217], v157 offset:37888
	ds_read_b128 v[218:221], v157 offset:38912
	ds_read_b128 v[222:225], v157 offset:39936
	global_load_lds_dwordx4 v[230:231], off
	v_lshl_add_u64 v[230:231], s[22:23], 0, v[132:133]
	s_mov_b32 m0, s30
	s_nop 0
	global_load_lds_dwordx4 v[230:231], off
	s_waitcnt vmcnt(8) lgkmcnt(0)
	s_barrier
	s_setprio 1
	v_mfma_f32_16x16x32_bf16 v[124:127], v[158:161], v[190:193], v[124:127]
	v_mfma_f32_16x16x32_bf16 v[120:123], v[166:169], v[190:193], v[120:123]
	v_mfma_f32_16x16x32_bf16 v[108:111], v[158:161], v[198:201], v[108:111]
	v_mfma_f32_16x16x32_bf16 v[104:107], v[166:169], v[198:201], v[104:107]
	v_mfma_f32_16x16x32_bf16 v[92:95], v[158:161], v[210:213], v[92:95]
	v_mfma_f32_16x16x32_bf16 v[88:91], v[166:169], v[210:213], v[88:91]
	v_mfma_f32_16x16x32_bf16 v[76:79], v[158:161], v[218:221], v[76:79]
	v_mfma_f32_16x16x32_bf16 v[72:75], v[166:169], v[218:221], v[72:75]
	v_mfma_f32_16x16x32_bf16 v[124:127], v[162:165], v[194:197], v[124:127]
	v_mfma_f32_16x16x32_bf16 v[120:123], v[170:173], v[194:197], v[120:123]
	v_mfma_f32_16x16x32_bf16 v[108:111], v[162:165], v[202:205], v[108:111]
	v_mfma_f32_16x16x32_bf16 v[104:107], v[170:173], v[202:205], v[104:107]
	v_mfma_f32_16x16x32_bf16 v[92:95], v[162:165], v[214:217], v[92:95]
	v_mfma_f32_16x16x32_bf16 v[88:91], v[170:173], v[214:217], v[88:91]
	v_mfma_f32_16x16x32_bf16 v[76:79], v[162:165], v[222:225], v[76:79]
	v_mfma_f32_16x16x32_bf16 v[72:75], v[170:173], v[222:225], v[72:75]
	s_setprio 0
	s_setprio 1
	v_mfma_f32_16x16x32_bf16 v[116:119], v[174:177], v[190:193], v[116:119]
	v_mfma_f32_16x16x32_bf16 v[112:115], v[182:185], v[190:193], v[112:115]
	v_mfma_f32_16x16x32_bf16 v[100:103], v[174:177], v[198:201], v[100:103]
	v_mfma_f32_16x16x32_bf16 v[96:99], v[182:185], v[198:201], v[96:99]
	v_mfma_f32_16x16x32_bf16 v[84:87], v[174:177], v[210:213], v[84:87]
	v_mfma_f32_16x16x32_bf16 v[80:83], v[182:185], v[210:213], v[80:83]
	v_mfma_f32_16x16x32_bf16 v[68:71], v[174:177], v[218:221], v[68:71]
	v_mfma_f32_16x16x32_bf16 v[64:67], v[182:185], v[218:221], v[64:67]
	v_mfma_f32_16x16x32_bf16 v[116:119], v[178:181], v[194:197], v[116:119]
	v_mfma_f32_16x16x32_bf16 v[112:115], v[186:189], v[194:197], v[112:115]
	v_mfma_f32_16x16x32_bf16 v[100:103], v[178:181], v[202:205], v[100:103]
	v_mfma_f32_16x16x32_bf16 v[96:99], v[186:189], v[202:205], v[96:99]
	v_mfma_f32_16x16x32_bf16 v[84:87], v[178:181], v[214:217], v[84:87]
	v_mfma_f32_16x16x32_bf16 v[80:83], v[186:189], v[214:217], v[80:83]
	v_mfma_f32_16x16x32_bf16 v[68:71], v[178:181], v[222:225], v[68:71]
	v_mfma_f32_16x16x32_bf16 v[64:67], v[186:189], v[222:225], v[64:67]
	s_setprio 0
	s_barrier
; #define PG8_STAGE(bufoff, gbase, voff) do { _Pragma("unroll") for (int _i = 0; _i < 2; ++_i) \
;         __builtin_amdgcn_global_load_lds((const unsigned*)((const char*)(gbase) + (voff)[_i]), (LAS unsigned*)(lds + (bufoff) + ldsw + _i * 8192), 16, 0, 0); } while (0)
; #define PG8_LDA(dst, b, h) do { _Pragma("unroll") for (int m = 0; m < 4; ++m) _Pragma("unroll") for (int k = 0; k < 2; ++k) dst[m][k] = *(const LAS bf16x8*)(lds + PG8_SA(b, h) + aoff + m * 2048 + k * 1024); } while (0)
; #define PG8_MMA(ai, bj, At, Bt) do { __builtin_amdgcn_s_setprio(1); _Pragma("unroll") for (int m = 0; m < 4; ++m) _Pragma("unroll") for (int n = 0; n < 2; ++n) _Pragma("unroll") for (int k = 0; k < 2; ++k) \
;         acc[ai][bj][m][n] = __builtin_amdgcn_mfma_f32_16x16x32_bf16(Bt[n][k], At[m][k], acc[ai][bj][m][n], 0, 0, 0); __builtin_amdgcn_s_setprio(0); } while (0)
; #define PG8_WAIT_V(n) asm volatile("s_waitcnt vmcnt(" #n ")" ::: "memory")
; #define PG8_WAIT_L(n) asm volatile("s_waitcnt lgkmcnt(" #n ")" ::: "memory")
; #define PG8_BAR __builtin_amdgcn_s_barrier()
; #define PG8_SCHED __builtin_amdgcn_sched_barrier(0)
; template <class Epi, class Sched>
; __device__ __forceinline__ void gemm_phase(LAS unsigned char* lds, const Gemm g, const Sched& S, const Epi& E, const int wave_s) {
;     ...
;             PG8_LDA(At, 1, 1); PG8_STAGE(PG8_SB(1, 0), b3, voffB); PG8_STAGE(PG8_SB(1, 1), b3 + hstepB, voffB); PG8_STAGE(PG8_SA(1, 0), a3, voffA);
;             PG8_WAIT_V(8); PG8_WAIT_L(0); PG8_BAR; PG8_MMA(1, 0, At, B0); PG8_MMA(1, 1, At, B1); PG8_BAR; PG8_SCHED;
;         }
;         if (wr == 0) PG8_BAR;
	s_add_i32 s22, s49, s81
	v_lshl_add_u64 v[150:151], v[150:151], 0, s[14:15]
	s_mov_b32 m0, s22
	ds_read_b128 v[190:193], v157 offset:49152
	ds_read_b128 v[194:197], v157 offset:50176
	ds_read_b128 v[198:201], v157 offset:51200
	ds_read_b128 v[202:205], v157 offset:52224
	ds_read_b128 v[210:213], v157 offset:53248
	ds_read_b128 v[214:217], v157 offset:54272
	ds_read_b128 v[218:221], v157 offset:55296
	ds_read_b128 v[222:225], v157 offset:56320
	global_load_lds_dwordx4 v[150:151], off
	s_add_i32 m0, s22, 0x2000
	s_add_u32 s8, s8, 0x18080
	v_lshl_add_u64 v[150:151], v[206:207], 0, s[14:15]
	s_addc_u32 s9, s9, 0
	s_add_i32 s22, s50, s81
	global_load_lds_dwordx4 v[150:151], off
	v_lshl_add_u64 v[150:151], s[8:9], 0, v[130:131]
	s_mov_b32 m0, s22
	s_nop 0
	global_load_lds_dwordx4 v[150:151], off
	v_lshl_add_u64 v[150:151], s[8:9], 0, v[134:135]
	s_add_i32 m0, s22, 0x2000
	s_nop 0
	global_load_lds_dwordx4 v[150:151], off
	v_lshl_add_u64 v[150:151], v[226:227], 0, s[14:15]
	s_mov_b32 m0, s33
	s_nop 0
	global_load_lds_dwordx4 v[150:151], off
	v_lshl_add_u64 v[150:151], v[228:229], 0, s[14:15]
	s_mov_b32 m0, s34
	s_nop 0
	global_load_lds_dwordx4 v[150:151], off
	s_waitcnt vmcnt(8) lgkmcnt(0)
	s_barrier
	s_setprio 1
	v_mfma_f32_16x16x32_bf16 v[60:63], v[158:161], v[190:193], v[60:63]
	v_mfma_f32_16x16x32_bf16 v[56:59], v[166:169], v[190:193], v[56:59]
	v_mfma_f32_16x16x32_bf16 v[44:47], v[158:161], v[198:201], v[44:47]
	v_mfma_f32_16x16x32_bf16 v[40:43], v[166:169], v[198:201], v[40:43]
	v_mfma_f32_16x16x32_bf16 v[28:31], v[158:161], v[210:213], v[28:31]
	v_mfma_f32_16x16x32_bf16 v[24:27], v[166:169], v[210:213], v[24:27]
	v_mfma_f32_16x16x32_bf16 v[12:15], v[158:161], v[218:221], v[12:15]
	v_mfma_f32_16x16x32_bf16 v[8:11], v[166:169], v[218:221], v[8:11]
	v_mfma_f32_16x16x32_bf16 v[60:63], v[162:165], v[194:197], v[60:63]
	v_mfma_f32_16x16x32_bf16 v[56:59], v[170:173], v[194:197], v[56:59]
	v_mfma_f32_16x16x32_bf16 v[44:47], v[162:165], v[202:205], v[44:47]
	v_mfma_f32_16x16x32_bf16 v[40:43], v[170:173], v[202:205], v[40:43]
	v_mfma_f32_16x16x32_bf16 v[28:31], v[162:165], v[214:217], v[28:31]
	v_mfma_f32_16x16x32_bf16 v[24:27], v[170:173], v[214:217], v[24:27]
	v_mfma_f32_16x16x32_bf16 v[12:15], v[162:165], v[222:225], v[12:15]
	v_mfma_f32_16x16x32_bf16 v[8:11], v[170:173], v[222:225], v[8:11]
	s_setprio 0
	s_setprio 1
	v_mfma_f32_16x16x32_bf16 v[52:55], v[174:177], v[190:193], v[52:55]
	v_mfma_f32_16x16x32_bf16 v[48:51], v[182:185], v[190:193], v[48:51]
	v_mfma_f32_16x16x32_bf16 v[36:39], v[174:177], v[198:201], v[36:39]
	v_mfma_f32_16x16x32_bf16 v[32:35], v[182:185], v[198:201], v[32:35]
	v_mfma_f32_16x16x32_bf16 v[20:23], v[174:177], v[210:213], v[20:23]
	v_mfma_f32_16x16x32_bf16 v[16:19], v[182:185], v[210:213], v[16:19]
	v_mfma_f32_16x16x32_bf16 v[4:7], v[174:177], v[218:221], v[4:7]
	v_mfma_f32_16x16x32_bf16 v[0:3], v[182:185], v[218:221], v[0:3]
	v_mfma_f32_16x16x32_bf16 v[52:55], v[178:181], v[194:197], v[52:55]
	v_mfma_f32_16x16x32_bf16 v[48:51], v[186:189], v[194:197], v[48:51]
	v_mfma_f32_16x16x32_bf16 v[36:39], v[178:181], v[202:205], v[36:39]
	v_mfma_f32_16x16x32_bf16 v[32:35], v[186:189], v[202:205], v[32:35]
	v_mfma_f32_16x16x32_bf16 v[20:23], v[178:181], v[214:217], v[20:23]
	v_mfma_f32_16x16x32_bf16 v[16:19], v[186:189], v[214:217], v[16:19]
	v_mfma_f32_16x16x32_bf16 v[4:7], v[178:181], v[222:225], v[4:7]
	v_mfma_f32_16x16x32_bf16 v[0:3], v[186:189], v[222:225], v[0:3]
	s_setprio 0
	s_barrier
	s_add_i32 s48, s48, 2
	s_add_u32 s46, s46, 0x100
	s_addc_u32 s47, s47, 0
	s_cmp_gt_u32 s48, 3
	s_mov_b64 s[22:23], s[4:5]
	s_cbranch_scc0 .LBB0_375
	s_and_b64 vcc, exec, s[16:17]
	s_cbranch_vccz .LBB0_378
	s_barrier

; #define PG8_STAGE(bufoff, gbase, voff) do { _Pragma("unroll") for (int _i = 0; _i < 2; ++_i) \
;         __builtin_amdgcn_global_load_lds((const unsigned*)((const char*)(gbase) + (voff)[_i]), (LAS unsigned*)(lds + (bufoff) + ldsw + _i * 8192), 16, 0, 0); } while (0)
; #define PG8_LDA(dst, b, h) do { _Pragma("unroll") for (int m = 0; m < 4; ++m) _Pragma("unroll") for (int k = 0; k < 2; ++k) dst[m][k] = *(const LAS bf16x8*)(lds + PG8_SA(b, h) + aoff + m * 2048 + k * 1024); } while (0)
; #define PG8_LDB(dst, b, h) do { _Pragma("unroll") for (int n = 0; n < 2; ++n) _Pragma("unroll") for (int k = 0; k < 2; ++k) dst[n][k] = *(const LAS bf16x8*)(lds + PG8_SB(b, h) + boff + n * 2048 + k * 1024); } while (0)
; #define PG8_MMA(ai, bj, At, Bt) do { __builtin_amdgcn_s_setprio(1); _Pragma("unroll") for (int m = 0; m < 4; ++m) _Pragma("unroll") for (int n = 0; n < 2; ++n) _Pragma("unroll") for (int k = 0; k < 2; ++k) \
;         acc[ai][bj][m][n] = __builtin_amdgcn_mfma_f32_16x16x32_bf16(Bt[n][k], At[m][k], acc[ai][bj][m][n], 0, 0, 0); __builtin_amdgcn_s_setprio(0); } while (0)
; #define PG8_WAIT_V(n) asm volatile("s_waitcnt vmcnt(" #n ")" ::: "memory")
; #define PG8_WAIT_L(n) asm volatile("s_waitcnt lgkmcnt(" #n ")" ::: "memory")
; #define PG8_BAR __builtin_amdgcn_s_barrier()
; #define PG8_SCHED __builtin_amdgcn_sched_barrier(0)
; template <class Epi, class Sched>
; __device__ __forceinline__ void gemm_phase(LAS unsigned char* lds, const Gemm g, const Sched& S, const Epi& E, const int wave_s) {
;     ...
;             const bool last = (t == nt - 2);
;             const char* a1 = cA + (size_t)(t + 1) * kstep;
;             const char* a2 = last ? nA : cA + (size_t)(t + 2) * kstep; const char* b2 = last ? nB : cB + (size_t)(t + 2) * kstep;
;             const char* a3 = a2 + kstep; const char* b3 = b2 + kstep;
;             PG8_LDB(B0, 0, 0); PG8_LDB(B1, 0, 1); PG8_SCHED; PG8_LDA(At, 0, 0); PG8_STAGE(PG8_SA(1, 1), a1 + hstepA, voffA);
;             PG8_WAIT_V(8); PG8_WAIT_L(0); PG8_BAR; PG8_MMA(0, 0, At, B0); PG8_MMA(0, 1, At, B1); PG8_BAR; PG8_SCHED;
;             PG8_LDA(At, 0, 1); PG8_STAGE(PG8_SB(0, 0), b2, voffB); PG8_STAGE(PG8_SB(0, 1), b2 + hstepB, voffB); PG8_STAGE(PG8_SA(0, 0), a2, voffA);
;             PG8_WAIT_V(8); PG8_WAIT_L(0); PG8_BAR; PG8_MMA(1, 0, At, B0); PG8_MMA(1, 1, At, B1); PG8_BAR; PG8_SCHED;
.LBB0_417:
	s_add_u32 s39, s36, s38
	s_addc_u32 s44, s37, 0
	s_add_u32 s42, s39, 0x100
	s_addc_u32 s43, s44, 0
	s_and_b64 s[40:41], s[4:5], exec
	s_cselect_b32 s41, s29, s43
	s_cselect_b32 s40, s28, s42
	s_add_u32 s38, s34, s38
	s_addc_u32 s42, s35, 0
	s_add_u32 s38, s38, 0x100
	s_addc_u32 s42, s42, 0
	s_and_b64 s[4:5], s[4:5], exec
	s_cselect_b32 s43, s27, s42
	s_cselect_b32 s42, s68, s38
	s_add_u32 s46, s39, 0xf0080
	ds_read_b128 v[148:151], v145
	ds_read_b128 v[152:155], v145 offset:1024
	ds_read_b128 v[156:159], v145 offset:2048
	ds_read_b128 v[160:163], v145 offset:3072
	ds_read_b128 v[164:167], v146
	ds_read_b128 v[168:171], v146 offset:1024
	ds_read_b128 v[172:175], v146 offset:2048
	ds_read_b128 v[176:179], v146 offset:3072
	s_addc_u32 s47, s44, 0
	s_add_i32 s76, s59, s81
	s_add_i32 m0, s49, 0xc000
	s_add_i32 s79, s49, 0xe000
	s_add_i32 s73, s76, 0x2000
	s_add_u32 s44, s42, 0x10000
	s_addc_u32 s45, s43, 0
	s_add_i32 s75, s60, s81
	s_add_i32 s74, s75, 0x2000
	s_add_i32 s72, 0, 0x18000
	s_add_i32 s71, 0, 0x1c000
	s_add_u32 s38, s40, 0xf0000
	s_addc_u32 s39, s41, 0
	s_add_i32 s70, s72, s81
	s_add_i32 s69, s70, 0x2000
	s_add_u32 s4, s42, 0x10080
	s_addc_u32 s5, s43, 0
	s_add_i32 s78, s71, s81
	s_add_i32 s77, s78, 0x2000
	v_lshl_add_u64 v[140:141], s[46:47], 0, v[128:129]
	ds_read_b128 v[180:183], v147
	ds_read_b128 v[184:187], v147 offset:1024
	ds_read_b128 v[188:191], v147 offset:2048
	ds_read_b128 v[192:195], v147 offset:3072
	ds_read_b128 v[196:199], v147 offset:4096
	ds_read_b128 v[200:203], v147 offset:5120
	ds_read_b128 v[204:207], v147 offset:6144
	ds_read_b128 v[210:213], v147 offset:7168
	global_load_lds_dwordx4 v[140:141], off
	v_lshl_add_u64 v[140:141], s[46:47], 0, v[132:133]
	s_mov_b32 m0, s79
	s_nop 0
	global_load_lds_dwordx4 v[140:141], off
	s_waitcnt vmcnt(8) lgkmcnt(0)
	s_barrier
	s_setprio 1
	v_mfma_f32_16x16x32_bf16 v[124:127], v[148:151], v[180:183], v[124:127]
	v_mfma_f32_16x16x32_bf16 v[120:123], v[156:159], v[180:183], v[120:123]
	v_mfma_f32_16x16x32_bf16 v[116:119], v[148:151], v[188:191], v[116:119]
	v_mfma_f32_16x16x32_bf16 v[108:111], v[156:159], v[188:191], v[108:111]
	v_mfma_f32_16x16x32_bf16 v[100:103], v[148:151], v[196:199], v[100:103]
	v_mfma_f32_16x16x32_bf16 v[92:95], v[156:159], v[196:199], v[92:95]
	v_mfma_f32_16x16x32_bf16 v[84:87], v[148:151], v[204:207], v[84:87]
	v_mfma_f32_16x16x32_bf16 v[76:79], v[156:159], v[204:207], v[76:79]
	v_mfma_f32_16x16x32_bf16 v[124:127], v[152:155], v[184:187], v[124:127]
	v_mfma_f32_16x16x32_bf16 v[120:123], v[160:163], v[184:187], v[120:123]
	v_mfma_f32_16x16x32_bf16 v[116:119], v[152:155], v[192:195], v[116:119]
	v_mfma_f32_16x16x32_bf16 v[108:111], v[160:163], v[192:195], v[108:111]
	v_mfma_f32_16x16x32_bf16 v[100:103], v[152:155], v[200:203], v[100:103]
	v_mfma_f32_16x16x32_bf16 v[92:95], v[160:163], v[200:203], v[92:95]
	v_mfma_f32_16x16x32_bf16 v[84:87], v[152:155], v[210:213], v[84:87]
	v_mfma_f32_16x16x32_bf16 v[76:79], v[160:163], v[210:213], v[76:79]
	s_setprio 0
	s_setprio 1
	v_mfma_f32_16x16x32_bf16 v[112:115], v[164:167], v[180:183], v[112:115]
	v_mfma_f32_16x16x32_bf16 v[104:107], v[172:175], v[180:183], v[104:107]
	v_mfma_f32_16x16x32_bf16 v[96:99], v[164:167], v[188:191], v[96:99]
	v_mfma_f32_16x16x32_bf16 v[88:91], v[172:175], v[188:191], v[88:91]
	v_mfma_f32_16x16x32_bf16 v[80:83], v[164:167], v[196:199], v[80:83]
	v_mfma_f32_16x16x32_bf16 v[72:75], v[172:175], v[196:199], v[72:75]
	v_mfma_f32_16x16x32_bf16 v[68:71], v[164:167], v[204:207], v[68:71]
	v_mfma_f32_16x16x32_bf16 v[64:67], v[172:175], v[204:207], v[64:67]
	v_mfma_f32_16x16x32_bf16 v[112:115], v[168:171], v[184:187], v[112:115]
	v_mfma_f32_16x16x32_bf16 v[104:107], v[176:179], v[184:187], v[104:107]
	v_mfma_f32_16x16x32_bf16 v[96:99], v[168:171], v[192:195], v[96:99]
	v_mfma_f32_16x16x32_bf16 v[88:91], v[176:179], v[192:195], v[88:91]
	v_mfma_f32_16x16x32_bf16 v[80:83], v[168:171], v[200:203], v[80:83]
	v_mfma_f32_16x16x32_bf16 v[72:75], v[176:179], v[200:203], v[72:75]
	v_mfma_f32_16x16x32_bf16 v[68:71], v[168:171], v[210:213], v[68:71]
	v_mfma_f32_16x16x32_bf16 v[64:67], v[176:179], v[210:213], v[64:67]
	s_setprio 0
	s_barrier
	s_mov_b32 m0, s76
	v_lshl_add_u64 v[140:141], s[42:43], 0, v[130:131]
	ds_read_b128 v[180:183], v147 offset:16384
	ds_read_b128 v[184:187], v147 offset:17408
	ds_read_b128 v[188:191], v147 offset:18432
	ds_read_b128 v[192:195], v147 offset:19456
	ds_read_b128 v[196:199], v147 offset:20480
	ds_read_b128 v[200:203], v147 offset:21504
	ds_read_b128 v[204:207], v147 offset:22528
	ds_read_b128 v[210:213], v147 offset:23552
	global_load_lds_dwordx4 v[140:141], off
	v_lshl_add_u64 v[214:215], s[42:43], 0, v[134:135]
	s_mov_b32 m0, s73
	v_lshl_add_u64 v[216:217], s[44:45], 0, v[130:131]
	global_load_lds_dwordx4 v[214:215], off
	s_mov_b32 m0, s75
	v_lshl_add_u64 v[218:219], s[40:41], 0, v[132:133]
	global_load_lds_dwordx4 v[216:217], off
	v_lshl_add_u64 v[216:217], s[44:45], 0, v[134:135]
	s_mov_b32 m0, s74
	s_nop 0
	global_load_lds_dwordx4 v[216:217], off
	v_lshl_add_u64 v[216:217], s[40:41], 0, v[128:129]
	s_mov_b32 m0, s49
	s_nop 0
	global_load_lds_dwordx4 v[216:217], off
	s_mov_b32 m0, s50
	s_nop 0
	global_load_lds_dwordx4 v[218:219], off
	s_waitcnt vmcnt(8) lgkmcnt(0)
	s_barrier
; #define PG8_STAGE(bufoff, gbase, voff) do { _Pragma("unroll") for (int _i = 0; _i < 2; ++_i) \
;         __builtin_amdgcn_global_load_lds((const unsigned*)((const char*)(gbase) + (voff)[_i]), (LAS unsigned*)(lds + (bufoff) + ldsw + _i * 8192), 16, 0, 0); } while (0)
; #define PG8_LDA(dst, b, h) do { _Pragma("unroll") for (int m = 0; m < 4; ++m) _Pragma("unroll") for (int k = 0; k < 2; ++k) dst[m][k] = *(const LAS bf16x8*)(lds + PG8_SA(b, h) + aoff + m * 2048 + k * 1024); } while (0)
; #define PG8_LDB(dst, b, h) do { _Pragma("unroll") for (int n = 0; n < 2; ++n) _Pragma("unroll") for (int k = 0; k < 2; ++k) dst[n][k] = *(const LAS bf16x8*)(lds + PG8_SB(b, h) + boff + n * 2048 + k * 1024); } while (0)
; #define PG8_MMA(ai, bj, At, Bt) do { __builtin_amdgcn_s_setprio(1); _Pragma("unroll") for (int m = 0; m < 4; ++m) _Pragma("unroll") for (int n = 0; n < 2; ++n) _Pragma("unroll") for (int k = 0; k < 2; ++k) \
;         acc[ai][bj][m][n] = __builtin_amdgcn_mfma_f32_16x16x32_bf16(Bt[n][k], At[m][k], acc[ai][bj][m][n], 0, 0, 0); __builtin_amdgcn_s_setprio(0); } while (0)
; #define PG8_WAIT_V(n) asm volatile("s_waitcnt vmcnt(" #n ")" ::: "memory")
; #define PG8_WAIT_L(n) asm volatile("s_waitcnt lgkmcnt(" #n ")" ::: "memory")
; #define PG8_BAR __builtin_amdgcn_s_barrier()
; #define PG8_SCHED __builtin_amdgcn_sched_barrier(0)
; template <class Epi, class Sched>
; __device__ __forceinline__ void gemm_phase(LAS unsigned char* lds, const Gemm g, const Sched& S, const Epi& E, const int wave_s) {
;     ...
;             PG8_WAIT_V(8); PG8_WAIT_L(0); PG8_BAR; PG8_MMA(1, 0, At, B0); PG8_MMA(1, 1, At, B1); PG8_BAR; PG8_SCHED;
;             PG8_LDB(B0, 1, 0); PG8_LDB(B1, 1, 1); PG8_SCHED; PG8_LDA(At, 1, 0); PG8_STAGE(PG8_SA(0, 1), a2 + hstepA, voffA);
;             PG8_WAIT_V(8); PG8_WAIT_L(0); PG8_BAR; PG8_MMA(0, 0, At, B0); PG8_MMA(0, 1, At, B1); PG8_BAR; PG8_SCHED;
	s_setprio 1
	v_mfma_f32_16x16x32_bf16 v[60:63], v[148:151], v[180:183], v[60:63]
	v_mfma_f32_16x16x32_bf16 v[56:59], v[156:159], v[180:183], v[56:59]
	v_mfma_f32_16x16x32_bf16 v[52:55], v[148:151], v[188:191], v[52:55]
	v_mfma_f32_16x16x32_bf16 v[44:47], v[156:159], v[188:191], v[44:47]
	v_mfma_f32_16x16x32_bf16 v[36:39], v[148:151], v[196:199], v[36:39]
	v_mfma_f32_16x16x32_bf16 v[28:31], v[156:159], v[196:199], v[28:31]
	v_mfma_f32_16x16x32_bf16 v[20:23], v[148:151], v[204:207], v[20:23]
	v_mfma_f32_16x16x32_bf16 v[12:15], v[156:159], v[204:207], v[12:15]
	v_mfma_f32_16x16x32_bf16 v[60:63], v[152:155], v[184:187], v[60:63]
	v_mfma_f32_16x16x32_bf16 v[56:59], v[160:163], v[184:187], v[56:59]
	v_mfma_f32_16x16x32_bf16 v[52:55], v[152:155], v[192:195], v[52:55]
	v_mfma_f32_16x16x32_bf16 v[44:47], v[160:163], v[192:195], v[44:47]
	v_mfma_f32_16x16x32_bf16 v[36:39], v[152:155], v[200:203], v[36:39]
	v_mfma_f32_16x16x32_bf16 v[28:31], v[160:163], v[200:203], v[28:31]
	v_mfma_f32_16x16x32_bf16 v[20:23], v[152:155], v[210:213], v[20:23]
	v_mfma_f32_16x16x32_bf16 v[12:15], v[160:163], v[210:213], v[12:15]
	s_setprio 0
	s_setprio 1
	v_mfma_f32_16x16x32_bf16 v[48:51], v[164:167], v[180:183], v[48:51]
	v_mfma_f32_16x16x32_bf16 v[40:43], v[172:175], v[180:183], v[40:43]
	v_mfma_f32_16x16x32_bf16 v[32:35], v[164:167], v[188:191], v[32:35]
	v_mfma_f32_16x16x32_bf16 v[24:27], v[172:175], v[188:191], v[24:27]
	v_mfma_f32_16x16x32_bf16 v[16:19], v[164:167], v[196:199], v[16:19]
	v_mfma_f32_16x16x32_bf16 v[8:11], v[172:175], v[196:199], v[8:11]
	v_mfma_f32_16x16x32_bf16 v[4:7], v[164:167], v[204:207], v[4:7]
	v_mfma_f32_16x16x32_bf16 v[0:3], v[172:175], v[204:207], v[0:3]
	v_mfma_f32_16x16x32_bf16 v[48:51], v[168:171], v[184:187], v[48:51]
	v_mfma_f32_16x16x32_bf16 v[40:43], v[176:179], v[184:187], v[40:43]
	v_mfma_f32_16x16x32_bf16 v[32:35], v[168:171], v[192:195], v[32:35]
	v_mfma_f32_16x16x32_bf16 v[24:27], v[176:179], v[192:195], v[24:27]
	v_mfma_f32_16x16x32_bf16 v[16:19], v[168:171], v[200:203], v[16:19]
	v_mfma_f32_16x16x32_bf16 v[8:11], v[176:179], v[200:203], v[8:11]
	v_mfma_f32_16x16x32_bf16 v[4:7], v[168:171], v[210:213], v[4:7]
	v_mfma_f32_16x16x32_bf16 v[0:3], v[176:179], v[210:213], v[0:3]
	s_setprio 0
	s_barrier
	v_add_u32_e32 v160, s72, v143
	v_add_u32_e32 v176, s71, v143
	ds_read_b128 v[148:151], v160
	ds_read_b128 v[152:155], v160 offset:1024
	ds_read_b128 v[156:159], v160 offset:2048
	ds_read_b128 v[160:163], v160 offset:3072
	ds_read_b128 v[164:167], v176
	ds_read_b128 v[168:171], v176 offset:1024
	ds_read_b128 v[172:175], v176 offset:2048
	ds_read_b128 v[176:179], v176 offset:3072
	s_mov_b32 m0, s51
	v_lshl_add_u64 v[220:221], s[38:39], 0, v[128:129]
	ds_read_b128 v[180:183], v147 offset:32768
	ds_read_b128 v[184:187], v147 offset:33792
	ds_read_b128 v[188:191], v147 offset:34816
	ds_read_b128 v[192:195], v147 offset:35840
	ds_read_b128 v[196:199], v147 offset:36864
	ds_read_b128 v[200:203], v147 offset:37888
	ds_read_b128 v[204:207], v147 offset:38912
	ds_read_b128 v[210:213], v147 offset:39936
	global_load_lds_dwordx4 v[220:221], off
	v_lshl_add_u64 v[220:221], s[38:39], 0, v[132:133]
	s_mov_b32 m0, s52
	s_nop 0
	global_load_lds_dwordx4 v[220:221], off
	s_waitcnt vmcnt(8) lgkmcnt(0)
	s_barrier
	s_setprio 1
	v_mfma_f32_16x16x32_bf16 v[124:127], v[148:151], v[180:183], v[124:127]
	v_mfma_f32_16x16x32_bf16 v[120:123], v[156:159], v[180:183], v[120:123]
	v_mfma_f32_16x16x32_bf16 v[116:119], v[148:151], v[188:191], v[116:119]
	v_mfma_f32_16x16x32_bf16 v[108:111], v[156:159], v[188:191], v[108:111]
	v_mfma_f32_16x16x32_bf16 v[100:103], v[148:151], v[196:199], v[100:103]
	v_mfma_f32_16x16x32_bf16 v[92:95], v[156:159], v[196:199], v[92:95]
	v_mfma_f32_16x16x32_bf16 v[84:87], v[148:151], v[204:207], v[84:87]
	v_mfma_f32_16x16x32_bf16 v[76:79], v[156:159], v[204:207], v[76:79]
	v_mfma_f32_16x16x32_bf16 v[124:127], v[152:155], v[184:187], v[124:127]
	v_mfma_f32_16x16x32_bf16 v[120:123], v[160:163], v[184:187], v[120:123]
	v_mfma_f32_16x16x32_bf16 v[116:119], v[152:155], v[192:195], v[116:119]
	v_mfma_f32_16x16x32_bf16 v[108:111], v[160:163], v[192:195], v[108:111]
	v_mfma_f32_16x16x32_bf16 v[100:103], v[152:155], v[200:203], v[100:103]
	v_mfma_f32_16x16x32_bf16 v[92:95], v[160:163], v[200:203], v[92:95]
	v_mfma_f32_16x16x32_bf16 v[84:87], v[152:155], v[210:213], v[84:87]
	v_mfma_f32_16x16x32_bf16 v[76:79], v[160:163], v[210:213], v[76:79]
	s_setprio 0
	s_setprio 1
	v_mfma_f32_16x16x32_bf16 v[112:115], v[164:167], v[180:183], v[112:115]
	v_mfma_f32_16x16x32_bf16 v[104:107], v[172:175], v[180:183], v[104:107]
	v_mfma_f32_16x16x32_bf16 v[96:99], v[164:167], v[188:191], v[96:99]
	v_mfma_f32_16x16x32_bf16 v[88:91], v[172:175], v[188:191], v[88:91]
	v_mfma_f32_16x16x32_bf16 v[80:83], v[164:167], v[196:199], v[80:83]
	v_mfma_f32_16x16x32_bf16 v[72:75], v[172:175], v[196:199], v[72:75]
	v_mfma_f32_16x16x32_bf16 v[68:71], v[164:167], v[204:207], v[68:71]
	v_mfma_f32_16x16x32_bf16 v[64:67], v[172:175], v[204:207], v[64:67]
	v_mfma_f32_16x16x32_bf16 v[112:115], v[168:171], v[184:187], v[112:115]
	v_mfma_f32_16x16x32_bf16 v[104:107], v[176:179], v[184:187], v[104:107]
	v_mfma_f32_16x16x32_bf16 v[96:99], v[168:171], v[192:195], v[96:99]
	v_mfma_f32_16x16x32_bf16 v[88:91], v[176:179], v[192:195], v[88:91]
	v_mfma_f32_16x16x32_bf16 v[80:83], v[168:171], v[200:203], v[80:83]
	v_mfma_f32_16x16x32_bf16 v[72:75], v[176:179], v[200:203], v[72:75]
	v_mfma_f32_16x16x32_bf16 v[68:71], v[168:171], v[210:213], v[68:71]
	v_mfma_f32_16x16x32_bf16 v[64:67], v[176:179], v[210:213], v[64:67]
	s_setprio 0
	s_barrier
; #define PG8_STAGE(bufoff, gbase, voff) do { _Pragma("unroll") for (int _i = 0; _i < 2; ++_i) \
;         __builtin_amdgcn_global_load_lds((const unsigned*)((const char*)(gbase) + (voff)[_i]), (LAS unsigned*)(lds + (bufoff) + ldsw + _i * 8192), 16, 0, 0); } while (0)
; #define PG8_LDA(dst, b, h) do { _Pragma("unroll") for (int m = 0; m < 4; ++m) _Pragma("unroll") for (int k = 0; k < 2; ++k) dst[m][k] = *(const LAS bf16x8*)(lds + PG8_SA(b, h) + aoff + m * 2048 + k * 1024); } while (0)
; #define PG8_MMA(ai, bj, At, Bt) do { __builtin_amdgcn_s_setprio(1); _Pragma("unroll") for (int m = 0; m < 4; ++m) _Pragma("unroll") for (int n = 0; n < 2; ++n) _Pragma("unroll") for (int k = 0; k < 2; ++k) \
;         acc[ai][bj][m][n] = __builtin_amdgcn_mfma_f32_16x16x32_bf16(Bt[n][k], At[m][k], acc[ai][bj][m][n], 0, 0, 0); __builtin_amdgcn_s_setprio(0); } while (0)
; #define PG8_WAIT_V(n) asm volatile("s_waitcnt vmcnt(" #n ")" ::: "memory")
; #define PG8_WAIT_L(n) asm volatile("s_waitcnt lgkmcnt(" #n ")" ::: "memory")
; #define PG8_BAR __builtin_amdgcn_s_barrier()
; #define PG8_SCHED __builtin_amdgcn_sched_barrier(0)
; template <class Epi, class Sched>
; __device__ __forceinline__ void gemm_phase(LAS unsigned char* lds, const Gemm g, const Sched& S, const Epi& E, const int wave_s) {
;     ...
;             PG8_LDA(At, 1, 1); PG8_STAGE(PG8_SB(1, 0), b3, voffB); PG8_STAGE(PG8_SB(1, 1), b3 + hstepB, voffB); PG8_STAGE(PG8_SA(1, 0), a3, voffA);
;             PG8_WAIT_V(8); PG8_WAIT_L(0); PG8_BAR; PG8_MMA(1, 0, At, B0); PG8_MMA(1, 1, At, B1); PG8_BAR; PG8_SCHED;
;         }
;         if (wr == 0) PG8_BAR;
	s_mov_b32 m0, s70
	v_lshl_add_u64 v[140:141], v[140:141], 0, s[14:15]
	ds_read_b128 v[180:183], v147 offset:49152
	ds_read_b128 v[184:187], v147 offset:50176
	ds_read_b128 v[188:191], v147 offset:51200
	ds_read_b128 v[192:195], v147 offset:52224
	ds_read_b128 v[196:199], v147 offset:53248
	ds_read_b128 v[200:203], v147 offset:54272
	ds_read_b128 v[204:207], v147 offset:55296
	ds_read_b128 v[210:213], v147 offset:56320
	global_load_lds_dwordx4 v[140:141], off
	v_lshl_add_u64 v[140:141], v[214:215], 0, s[14:15]
	s_mov_b32 m0, s69
	s_nop 0
	global_load_lds_dwordx4 v[140:141], off
	v_lshl_add_u64 v[140:141], s[4:5], 0, v[130:131]
	s_mov_b32 m0, s78
	s_nop 0
	global_load_lds_dwordx4 v[140:141], off
	v_lshl_add_u64 v[140:141], s[4:5], 0, v[134:135]
	s_mov_b32 m0, s77
	s_nop 0
	global_load_lds_dwordx4 v[140:141], off
	v_lshl_add_u64 v[140:141], v[216:217], 0, s[14:15]
	s_mov_b32 m0, s54
	s_nop 0
	global_load_lds_dwordx4 v[140:141], off
	v_lshl_add_u64 v[140:141], v[218:219], 0, s[14:15]
	s_mov_b32 m0, s55
	s_nop 0
	global_load_lds_dwordx4 v[140:141], off
	s_waitcnt vmcnt(8) lgkmcnt(0)
	s_barrier
	s_setprio 1
	v_mfma_f32_16x16x32_bf16 v[60:63], v[148:151], v[180:183], v[60:63]
	v_mfma_f32_16x16x32_bf16 v[56:59], v[156:159], v[180:183], v[56:59]
	v_mfma_f32_16x16x32_bf16 v[52:55], v[148:151], v[188:191], v[52:55]
	v_mfma_f32_16x16x32_bf16 v[44:47], v[156:159], v[188:191], v[44:47]
	v_mfma_f32_16x16x32_bf16 v[36:39], v[148:151], v[196:199], v[36:39]
	v_mfma_f32_16x16x32_bf16 v[28:31], v[156:159], v[196:199], v[28:31]
	v_mfma_f32_16x16x32_bf16 v[20:23], v[148:151], v[204:207], v[20:23]
	v_mfma_f32_16x16x32_bf16 v[12:15], v[156:159], v[204:207], v[12:15]
	v_mfma_f32_16x16x32_bf16 v[60:63], v[152:155], v[184:187], v[60:63]
	v_mfma_f32_16x16x32_bf16 v[56:59], v[160:163], v[184:187], v[56:59]
	v_mfma_f32_16x16x32_bf16 v[52:55], v[152:155], v[192:195], v[52:55]
	v_mfma_f32_16x16x32_bf16 v[44:47], v[160:163], v[192:195], v[44:47]
	v_mfma_f32_16x16x32_bf16 v[36:39], v[152:155], v[200:203], v[36:39]
	v_mfma_f32_16x16x32_bf16 v[28:31], v[160:163], v[200:203], v[28:31]
	v_mfma_f32_16x16x32_bf16 v[20:23], v[152:155], v[210:213], v[20:23]
	v_mfma_f32_16x16x32_bf16 v[12:15], v[160:163], v[210:213], v[12:15]
	s_setprio 0
	s_setprio 1
	v_mfma_f32_16x16x32_bf16 v[48:51], v[164:167], v[180:183], v[48:51]
	v_mfma_f32_16x16x32_bf16 v[40:43], v[172:175], v[180:183], v[40:43]
	v_mfma_f32_16x16x32_bf16 v[32:35], v[164:167], v[188:191], v[32:35]
	v_mfma_f32_16x16x32_bf16 v[24:27], v[172:175], v[188:191], v[24:27]
	v_mfma_f32_16x16x32_bf16 v[16:19], v[164:167], v[196:199], v[16:19]
	v_mfma_f32_16x16x32_bf16 v[8:11], v[172:175], v[196:199], v[8:11]
	v_mfma_f32_16x16x32_bf16 v[4:7], v[164:167], v[204:207], v[4:7]
	v_mfma_f32_16x16x32_bf16 v[0:3], v[172:175], v[204:207], v[0:3]
	v_mfma_f32_16x16x32_bf16 v[48:51], v[168:171], v[184:187], v[48:51]
	v_mfma_f32_16x16x32_bf16 v[40:43], v[176:179], v[184:187], v[40:43]
	v_mfma_f32_16x16x32_bf16 v[32:35], v[168:171], v[192:195], v[32:35]
	v_mfma_f32_16x16x32_bf16 v[24:27], v[176:179], v[192:195], v[24:27]
	v_mfma_f32_16x16x32_bf16 v[16:19], v[168:171], v[200:203], v[16:19]
	v_mfma_f32_16x16x32_bf16 v[8:11], v[176:179], v[200:203], v[8:11]
	v_mfma_f32_16x16x32_bf16 v[4:7], v[168:171], v[210:213], v[4:7]
	v_mfma_f32_16x16x32_bf16 v[0:3], v[176:179], v[210:213], v[0:3]
	s_setprio 0
	s_barrier
	s_movk_i32 s38, 0x100
	s_andn2_b64 vcc, exec, s[8:9]
	s_mov_b64 s[4:5], -1
	s_mov_b64 s[8:9], 0
	s_cbranch_vccz .LBB0_417
	s_and_b64 vcc, exec, s[16:17]
	s_cbranch_vccz .LBB0_420
	s_barrier

; #define LAS __attribute__((address_space(3)))
; #define SBAR() __builtin_amdgcn_sched_barrier(0)
; __device__ __forceinline__ int v_rd_base(int lane) { return ((lane & 3) << 3) | (((lane >> 2) & 3) << 6) | (((lane >> 4) & 1) << 5) | (((lane >> 5) & 1) << 8); }
; #define VMW() asm volatile("s_waitcnt vmcnt(0)" ::: "memory")
; #define SWRITE_HV(bf) do { int t_ = tid; LAUNDER(t_); const int vst0_ = v_st(t_ >> 4, (t_ & 15) * 8), vst1_ = v_st(32 + (t_ >> 4), (t_ & 15) * 8); \
;                            *(LAS bf16x8*)(lds + OFF_V + (bf) * SHM_V + vst0_) = S.st_v0; *(LAS bf16x8*)(lds + OFF_V + (bf) * SHM_V + vst1_) = S.st_v1; } while (0)
; #define SWRITE_H(bf) do { SWRITE_HV(bf); SWRITE_HK(bf); } while (0)
; #define Kh R_K(cur)
; #define Vh R_V(cur)
; #define Rh R_R(cur)
; #define MASKT(P0_, P1_, t) do { const int kb_ = KBASE(t); if (kb_ + KVBLK - 1 > qlo) mask_tile(P0_, P1_, qm - kb_); } while (0)
; __device__ __forceinline__ void attn_block(const Bases& B, const BlockRef& cur, const BlockRef& nxt, LAS char* lds, Seam& S, int tid) {
;     const int wid = __builtin_amdgcn_readfirstlane(tid >> 6), lane = tid & 63, r32 = lane & 31, hi = lane >> 5;
;     const int P0 = cur.qb * QB, NT = (P0 + QB - 1) / KVBLK + 1;
;     const int qlo = P0 + wid * QBLK, qm = qlo + r32 - 4 * hi;
;     LAS float* ws = (LAS float*)(lds + OFF_WS) + wid * 64; LAS float* li_l = ws; LAS float* al_l = ws + 32;
;     float m_reg = -1e30f, l_reg = 0; f32x16 o[4] = {};
;     const int vb0 = (int)(unsigned)(uintptr_t)lds + v_rd_base(lane);
;     LAS char* qrb = lds + OFF_QR + wid * 4096 + lane * 16;
;     ...
;     f32x16 pA0, pA1, pB0, pB1; float mnA, mnB, alA, alB; bf16x8 pa0, pa1, pa2, pa3;
;     SWRITE_HV(0); SBAR();
;     if (NT > 1) { SLOAD_H(Kh, Vh, Rh, KBASE(1)); }
;     SBAR(); qkt<0>(pA0, pA1, lds, r32, hi, S.qr, qrb);
;     MASKT(pA0, pA1, 0); partialSM(pA0, pA1, m_reg, mnA, alA);
;     if (NT > 1) { VMW(); SWRITE_H(1); }
;     __syncthreads();
.LBB0_505:
	s_nop 8
	v_max_f32_e32 v0, v19, v19
	v_max_f32_e32 v54, v18, v18
	v_max_f32_e32 v0, v54, v0
	v_max3_f32 v0, v0, v20, v21
	v_max3_f32 v0, v0, v22, v23
	v_max3_f32 v0, v0, v24, v25
	v_max3_f32 v0, v0, v26, v27
	v_max3_f32 v0, v0, v28, v29
	v_max3_f32 v0, v0, v30, v31
	v_max3_f32 v0, v0, v32, v33
	v_max3_f32 v0, v0, v2, v3
	v_max3_f32 v0, v0, v4, v5
	v_max3_f32 v0, v0, v6, v7
	v_max3_f32 v0, v0, v8, v9
	v_max3_f32 v0, v0, v10, v11
	v_max3_f32 v0, v0, v12, v13
	v_max3_f32 v0, v0, v14, v15
	v_max3_f32 v0, v0, v16, v17
	v_mov_b32_e32 v54, v0
	s_nop 1
	v_permlane32_swap_b32_e32 v0, v54
	v_max_f32_e32 v54, v54, v54
	v_max_f32_e32 v0, v0, v0
	v_max_f32_e32 v0, v0, v54
	s_and_b32 s4, s4, 0x3fffffc0
	v_add_f32_e32 v54, 0x7149f2ca, v0
	s_lshl_b32 s4, s4, 2
	v_mul_f32_e32 v54, 0x3d93cd3a, v54
	v_max_f32_e32 v0, 0xf149f2ca, v0
	s_lshl_b32 s5, s86, 2
	s_add_i32 s4, s4, 0
	v_cmp_ge_f32_e32 vcc, s73, v54
	v_sub_f32_e32 v54, 0xf149f2ca, v0
	s_or_b32 s87, s5, 3
	s_add_i32 s4, s4, 0x19000
	v_mul_f32_e32 v54, 0x3dd53b94, v54
	v_exp_f32_e32 v54, v54
	s_cmp_eq_u64 vcc, exec
	s_cselect_b64 vcc, -1, 0
	v_cndmask_b32_e32 v185, v0, v175, vcc
	v_mul_f32_e32 v0, 0xbdd53b94, v185
	v_cndmask_b32_e64 v183, v54, 1.0, vcc
	v_fmamk_f32 v18, v18, 0x3dd53b94, v0
	v_fmamk_f32 v19, v19, 0x3dd53b94, v0
	v_fmamk_f32 v20, v20, 0x3dd53b94, v0
	v_fmamk_f32 v21, v21, 0x3dd53b94, v0
	v_fmamk_f32 v22, v22, 0x3dd53b94, v0
	v_fmamk_f32 v23, v23, 0x3dd53b94, v0
	v_fmamk_f32 v24, v24, 0x3dd53b94, v0
	v_fmamk_f32 v25, v25, 0x3dd53b94, v0
	v_fmamk_f32 v26, v26, 0x3dd53b94, v0
	v_fmamk_f32 v27, v27, 0x3dd53b94, v0
	v_fmamk_f32 v28, v28, 0x3dd53b94, v0
	v_fmamk_f32 v29, v29, 0x3dd53b94, v0
	v_fmamk_f32 v30, v30, 0x3dd53b94, v0
	v_fmamk_f32 v31, v31, 0x3dd53b94, v0
	v_fmamk_f32 v32, v32, 0x3dd53b94, v0
	v_mov_b32_e32 v54, v0
	v_pk_fma_f32 v[150:151], v[16:17], s[80:81], v[0:1] op_sel_hi:[1,0,0]
	v_pk_fma_f32 v[152:153], v[14:15], s[80:81], v[0:1] op_sel_hi:[1,0,0]
	v_pk_fma_f32 v[154:155], v[12:13], s[80:81], v[0:1] op_sel_hi:[1,0,0]
	v_pk_fma_f32 v[156:157], v[10:11], s[80:81], v[0:1] op_sel_hi:[1,0,0]
	v_pk_fma_f32 v[158:159], v[8:9], s[80:81], v[0:1] op_sel_hi:[1,0,0]
	v_pk_fma_f32 v[160:161], v[6:7], s[80:81], v[0:1] op_sel_hi:[1,0,0]
	v_pk_fma_f32 v[162:163], v[4:5], s[80:81], v[0:1] op_sel_hi:[1,0,0]
	v_pk_fma_f32 v[164:165], v[2:3], s[80:81], v[0:1] op_sel_hi:[1,0,0]
	v_mov_b32_e32 v0, v166
	s_waitcnt vmcnt(0)
	v_fmac_f32_e32 v54, 0x3dd53b94, v33
	v_ashrrev_i32_e32 v2, 4, v0
	v_and_b32_e32 v3, 0xfffff0, v2
	v_lshlrev_b32_e32 v4, 1, v2
	v_and_or_b32 v3, v4, 8, v3
	v_lshrrev_b32_e32 v4, 1, v2
	v_and_b32_e32 v6, 3, v2
	v_add_u32_e32 v2, 32, v2
	v_and_or_b32 v4, v4, 4, v6
	v_and_b32_e32 v6, 0xfffff0, v2
	v_lshlrev_b32_e32 v2, 1, v2
	v_and_or_b32 v2, v2, 8, v6
	v_lshrrev_b32_e32 v3, 1, v3
	v_bfe_u32 v5, v0, 2, 2
	v_lshrrev_b32_e32 v2, 1, v2
	v_or_b32_e32 v3, v3, v5
	v_lshlrev_b32_e32 v0, 4, v0
	v_or_b32_e32 v2, v2, v5
	v_lshlrev_b32_e32 v3, 9, v3
	v_and_b32_e32 v0, 48, v0
	v_lshlrev_b32_e32 v2, 9, v2
	v_lshl_add_u32 v4, v4, 6, 0
	v_add3_u32 v3, v4, v3, v0
	v_add3_u32 v0, v4, v2, v0
	s_waitcnt vmcnt(4)
	ds_write_b128 v3, v[42:45] offset:16384
	s_waitcnt vmcnt(2)
	ds_write_b128 v0, v[46:49] offset:16384
	v_mov_b32_e32 v0, v166
	v_exp_f32_e32 v205, v18
	v_lshrrev_b32_e32 v2, 4, v0
	v_lshlrev_b32_e32 v3, 4, v0
	v_lshrrev_b32_e32 v0, 3, v0
	v_mul_lo_u32 v2, v2, s1
	v_and_b32_e32 v4, 0xf0, v3
	v_mul_lo_u32 v0, v0, s0
	v_and_b32_e32 v3, 0x70, v3
	v_exp_f32_e32 v207, v19
	v_exp_f32_e32 v203, v20
	v_exp_f32_e32 v206, v21
	v_exp_f32_e32 v202, v22
	v_exp_f32_e32 v204, v23
	v_exp_f32_e32 v200, v24
	v_exp_f32_e32 v201, v25
	v_exp_f32_e32 v197, v26
	v_exp_f32_e32 v199, v27
	v_exp_f32_e32 v196, v28
	v_exp_f32_e32 v198, v29
	v_exp_f32_e32 v193, v30
	v_exp_f32_e32 v195, v31
	v_exp_f32_e32 v192, v32
	v_exp_f32_e32 v194, v54
	v_add3_u32 v2, s77, v2, v4
	v_add3_u32 v0, s72, v0, v3
	v_mov_b32_e32 v14, v1
	v_mov_b32_e32 v15, v1
	ds_write_b128 v2, v[34:37]
	s_waitcnt vmcnt(1)
	ds_write_b128 v2, v[38:41] offset:8704
	s_waitcnt vmcnt(0)
	ds_write_b128 v0, v[50:53]
	v_mov_b32_e32 v0, v1
	v_mov_b32_e32 v2, v1
	v_mov_b32_e32 v3, v1
	v_mov_b32_e32 v4, v1
	v_mov_b32_e32 v5, v1
	v_mov_b32_e32 v6, v1
	v_mov_b32_e32 v7, v1
	v_mov_b32_e32 v8, v1
	v_mov_b32_e32 v9, v1
	v_mov_b32_e32 v10, v1
	v_mov_b32_e32 v11, v1
	v_mov_b32_e32 v12, v1
	v_mov_b32_e32 v13, v1
	v_mov_b64_e32 v[64:65], v[14:15]
	v_mov_b64_e32 v[48:49], v[14:15]
	v_mov_b64_e32 v[32:33], v[14:15]
	v_mov_b64_e32 v[62:63], v[12:13]
	v_mov_b64_e32 v[60:61], v[10:11]
	v_mov_b64_e32 v[58:59], v[8:9]
	v_mov_b64_e32 v[56:57], v[6:7]
	v_mov_b64_e32 v[54:55], v[4:5]
	v_mov_b64_e32 v[52:53], v[2:3]
	v_mov_b64_e32 v[50:51], v[0:1]
	v_mov_b64_e32 v[46:47], v[12:13]
	v_mov_b64_e32 v[44:45], v[10:11]
	v_mov_b64_e32 v[42:43], v[8:9]
	v_mov_b64_e32 v[40:41], v[6:7]
	v_mov_b64_e32 v[38:39], v[4:5]
	v_mov_b64_e32 v[36:37], v[2:3]
	v_mov_b64_e32 v[34:35], v[0:1]
	v_mov_b64_e32 v[30:31], v[12:13]
	v_mov_b64_e32 v[28:29], v[10:11]
	v_mov_b64_e32 v[26:27], v[8:9]
	v_mov_b64_e32 v[24:25], v[6:7]
	v_mov_b64_e32 v[22:23], v[4:5]
	v_mov_b64_e32 v[20:21], v[2:3]
	v_mov_b64_e32 v[18:19], v[0:1]
	v_mov_b64_e32 v[16:17], v[14:15]
	s_mov_b32 s75, 1
	v_lshl_add_u32 v180, v167, 2, s4
	v_lshl_add_u32 v179, v168, 2, s4
	v_add_u32_e32 v184, s85, v171
	s_mov_b32 s74, 0
	v_mov_b32_e32 v181, 0
	s_movk_i32 s96, 0xe0
	v_mov_b64_e32 v[14:15], v[12:13]
	v_mov_b64_e32 v[12:13], v[10:11]
	v_mov_b64_e32 v[10:11], v[8:9]
	v_mov_b64_e32 v[8:9], v[6:7]
	v_mov_b64_e32 v[6:7], v[4:5]
	v_mov_b64_e32 v[4:5], v[2:3]
	v_mov_b64_e32 v[2:3], v[0:1]
	v_lshlrev_b32_e32 v242, 8, v166
	v_lshlrev_b32_e32 v243, 4, v166
	v_and_b32_e32 v243, 0xf0, v243
	v_and_or_b32 v254, v242, s33, v243
	s_add_i32 s98, s96, 0xffffffa0
	s_mov_b32 s99, 0
	s_lshl_b64 s[100:101], s[98:99], 7
	s_lshl_b64 s[98:99], s[98:99], 12
	s_add_u32 s98, s92, s98
	s_addc_u32 s99, s93, s99
	s_add_u32 s100, s94, s100
	s_addc_u32 s101, s95, s101
	v_lshrrev_b32_e32 v243, 4, v166
	v_lshlrev_b32_e32 v244, 4, v166
	v_lshrrev_b32_e32 v242, 3, v166
	v_mul_u32_u24_e32 v243, 0x110, v243
	v_and_b32_e32 v245, 0xf0, v244
	v_mul_u32_u24_e32 v242, 0x90, v242
	v_and_b32_e32 v244, 0x70, v244
	v_add_u32_e32 v250, v243, v245
	v_add_u32_e32 v251, v242, v244
	v_mov_b32_e32 v242, v166
	v_ashrrev_i32_e32 v243, 4, v242
	v_and_b32_e32 v244, 0xfffff0, v243
	v_lshlrev_b32_e32 v245, 1, v243
	v_and_or_b32 v244, v245, 8, v244
	v_lshrrev_b32_e32 v245, 1, v243
	v_and_b32_e32 v247, 3, v243
	v_add_u32_e32 v243, 32, v243
	v_and_or_b32 v245, v245, 4, v247
	v_and_b32_e32 v247, 0xfffff0, v243
	v_lshlrev_b32_e32 v243, 1, v243
	v_and_or_b32 v243, v243, 8, v247
	v_lshrrev_b32_e32 v244, 1, v244
	v_bfe_u32 v246, v242, 2, 2
	v_lshrrev_b32_e32 v243, 1, v243
	v_or_b32_e32 v244, v244, v246
	v_lshlrev_b32_e32 v242, 4, v242
	v_or_b32_e32 v243, v243, v246
	v_lshlrev_b32_e32 v244, 9, v244
	v_and_b32_e32 v242, 48, v242
	v_lshlrev_b32_e32 v243, 9, v243
	v_lshlrev_b32_e32 v245, 6, v245
	v_add3_u32 v252, v245, v244, v242
	v_add3_u32 v253, v245, v243, v242
	s_waitcnt lgkmcnt(0)
; #define LAS __attribute__((address_space(3)))
; __device__ __forceinline__ void finishSM(f32x16& p0, f32x16& p1, float alpha, float& l_reg, bf16x8& pa0, bf16x8& pa1, bf16x8& pa2, bf16x8& pa3) {
; #pragma unroll
;     for (int r = 0; r < 16; ++r) p1[r] = __builtin_amdgcn_exp2f(p1[r]);
;     float ps = 0;
; #pragma unroll
;     for (int r = 0; r < 16; ++r) ps += p0[r];
; #pragma unroll
;     for (int r = 0; r < 16; ++r) ps += p1[r];
;     { auto rr = __builtin_amdgcn_permlane32_swap(__float_as_uint(ps), __float_as_uint(ps), false, false);
;       ps = __uint_as_float(rr[0]) + __uint_as_float(rr[1]); }
;     l_reg = l_reg * alpha + ps;
;     ...
;     PK4(p0, 0, pa0); PK4(p0, 8, pa1); PK4(p1, 0, pa2); PK4(p1, 8, pa3);
;     ...
; }
; template <int KB>
; __device__ __forceinline__ void qkt(f32x16& p0, f32x16& p1, const LAS char* lds, int r32, int hi, const bf16x8* qr, const LAS char* qrb) {
;     p0 = f32x16{}; p1 = f32x16{};
;     { const LAS char* kbp = lds + OFF_K + KB * SHM_K + KSWZ(r32, hi * 16);
; #pragma unroll
;     for (int d0 = 0; d0 < 8; ++d0) { const LAS char* a = kbp + d0 * 32;
;         const bf16x8 b0 = *reinterpret_cast<const LAS bf16x8*>(a);
;         const bf16x8 b1 = *reinterpret_cast<const LAS bf16x8*>(a + 32 * 272);
;         p0 = __builtin_amdgcn_mfma_f32_32x32x16_bf16(b0, qr[d0], p0, 0, 0, 0);
;         p1 = __builtin_amdgcn_mfma_f32_32x32x16_bf16(b1, qr[d0], p1, 0, 0, 0); } }
;     { const LAS char* rb = lds + OFF_R + KB * SHM_R + RSWZ(r32, hi * 16);
; #pragma unroll
;     for (int d0 = 0; d0 < 4; ++d0) { const LAS char* a = rb + d0 * 32;
;         const bf16x8 b0 = *reinterpret_cast<const LAS bf16x8*>(a);
;         const bf16x8 b1 = *reinterpret_cast<const LAS bf16x8*>(a + 32 * 144);
;         const bf16x8 qv = *reinterpret_cast<const LAS bf16x8*>(qrb + d0 * 1024);
;         p0 = __builtin_amdgcn_mfma_f32_32x32x16_bf16(b0, qv, p0, 0, 0, 0);
;         p1 = __builtin_amdgcn_mfma_f32_32x32x16_bf16(b1, qv, p1, 0, 0, 0); } }
; }
	s_barrier
.LBB0_506:
	ds_read_b128 v[210:213], v176
	ds_read_b128 v[214:217], v176 offset:8704
	ds_read_b128 v[218:221], v176 offset:32
	ds_read_b128 v[222:225], v176 offset:8736
	ds_read_b128 v[226:229], v176 offset:64
	ds_read_b128 v[230:233], v176 offset:8768
	ds_read_b128 v[234:237], v176 offset:96
	ds_read_b128 v[238:241], v176 offset:8800
	ds_read_b128 v[242:245], v176 offset:128
	ds_read_b128 v[246:249], v176 offset:8832
	v_exp_f32_e32 v0, v164
	v_exp_f32_e32 v164, v165
	v_exp_f32_e32 v162, v162
	v_exp_f32_e32 v163, v163
	s_waitcnt lgkmcnt(6)
	v_mfma_f32_32x32x16_bf16 v[82:97], v[210:213], v[126:129], 0
	ds_read_b128 v[210:213], v176 offset:160
	v_exp_f32_e32 v160, v160
	v_exp_f32_e32 v165, v157
	v_mfma_f32_32x32x16_bf16 v[66:81], v[214:217], v[126:129], 0
	ds_read_b128 v[214:217], v176 offset:8864
	v_exp_f32_e32 v190, v154
	v_mfma_f32_32x32x16_bf16 v[82:97], v[218:221], v[122:125], v[82:97]
	ds_read_b128 v[218:221], v176 offset:192
	v_exp_f32_e32 v191, v155
	v_exp_f32_e32 v130, v161
	v_mfma_f32_32x32x16_bf16 v[66:81], v[222:225], v[122:125], v[66:81]
	ds_read_b128 v[222:225], v176 offset:8896
	v_exp_f32_e32 v131, v158
	v_exp_f32_e32 v132, v159
	s_waitcnt lgkmcnt(6)
	v_mfma_f32_32x32x16_bf16 v[82:97], v[226:229], v[118:121], v[82:97]
	ds_read_b128 v[226:229], v176 offset:224
	v_exp_f32_e32 v133, v156
	v_exp_f32_e32 v148, v150
	v_mfma_f32_32x32x16_bf16 v[66:81], v[230:233], v[118:121], v[66:81]
	ds_read_b128 v[230:233], v176 offset:8928
	v_add_f32_e32 v150, 0, v205
	v_add_f32_e32 v150, v207, v150
	v_mfma_f32_32x32x16_bf16 v[82:97], v[234:237], v[114:117], v[82:97]
	ds_read_b128 v[234:237], v178
	v_add_f32_e32 v150, v203, v150
	v_exp_f32_e32 v146, v152
	v_exp_f32_e32 v147, v153
	v_mfma_f32_32x32x16_bf16 v[66:81], v[238:241], v[114:117], v[66:81]
	ds_read_b128 v[238:241], v177
	v_exp_f32_e32 v149, v151
	s_waitcnt lgkmcnt(6)
	v_mfma_f32_32x32x16_bf16 v[82:97], v[242:245], v[110:113], v[82:97]
	ds_read_b128 v[242:245], v177 offset:4608
	v_add_f32_e32 v142, v206, v150
	v_add_f32_e32 v142, v202, v142
	v_add_f32_e32 v142, v204, v142
	v_add_f32_e32 v142, v200, v142
	v_mfma_f32_32x32x16_bf16 v[66:81], v[246:249], v[110:113], v[66:81]
	ds_read_b128 v[246:249], v178 offset:1024
	v_add_f32_e32 v142, v201, v142
	v_add_f32_e32 v142, v197, v142
	v_add_f32_e32 v142, v199, v142
	v_mfma_f32_32x32x16_bf16 v[82:97], v[210:213], v[106:109], v[82:97]
	ds_read_b128 v[210:213], v177 offset:32
	v_add_f32_e32 v142, v196, v142
	v_add_f32_e32 v142, v198, v142
	v_add_f32_e32 v142, v193, v142
	v_add_f32_e32 v142, v195, v142
	v_mfma_f32_32x32x16_bf16 v[66:81], v[214:217], v[106:109], v[66:81]
	ds_read_b128 v[214:217], v177 offset:4640
	v_add_f32_e32 v142, v192, v142
	v_add_f32_e32 v142, v194, v142
	v_add_f32_e32 v142, v0, v142
	s_waitcnt lgkmcnt(6)
	v_mfma_f32_32x32x16_bf16 v[82:97], v[218:221], v[102:105], v[82:97]
	ds_read_b128 v[218:221], v178 offset:2048
	v_add_f32_e32 v142, v164, v142
	v_add_f32_e32 v142, v162, v142
	v_add_f32_e32 v142, v163, v142
	v_add_f32_e32 v142, v160, v142
	v_mfma_f32_32x32x16_bf16 v[66:81], v[222:225], v[102:105], v[66:81]
	ds_read_b128 v[222:225], v177 offset:64
	v_add_f32_e32 v142, v130, v142
	v_add_f32_e32 v142, v131, v142
	v_add_f32_e32 v142, v132, v142
	v_mfma_f32_32x32x16_bf16 v[82:97], v[226:229], v[98:101], v[82:97]
	ds_read_b128 v[226:229], v177 offset:4672
	v_add_f32_e32 v134, v133, v142
	v_add_f32_e32 v134, v165, v134
	v_add_f32_e32 v134, v190, v134
	v_add_f32_e32 v134, v191, v134
	v_mfma_f32_32x32x16_bf16 v[66:81], v[230:233], v[98:101], v[66:81]
	ds_read_b128 v[230:233], v178 offset:3072
	v_add_f32_e32 v134, v146, v134
	v_add_f32_e32 v134, v147, v134
	v_add_f32_e32 v134, v148, v134
	s_waitcnt lgkmcnt(5)
	v_mfma_f32_32x32x16_bf16 v[82:97], v[238:241], v[234:237], v[82:97]
	ds_read_b128 v[238:241], v177 offset:96
	v_add_f32_e32 v186, v149, v134
	v_mov_b32_e32 v187, v186
	s_nop 1
	v_permlane32_swap_b32_e32 v186, v187
	v_mfma_f32_32x32x16_bf16 v[66:81], v[242:245], v[234:237], v[66:81]
	ds_read_b128 v[242:245], v177 offset:4704
	v_cvt_pk_bf16_f32 v150, v205, v207
	v_cvt_pk_bf16_f32 v151, v203, v206
	v_cvt_pk_bf16_f32 v152, v202, v204
	v_cvt_pk_bf16_f32 v153, v200, v201
	v_mfma_f32_32x32x16_bf16 v[82:97], v[210:213], v[246:249], v[82:97]
	v_cvt_pk_bf16_f32 v154, v197, v199
	v_cvt_pk_bf16_f32 v155, v196, v198
	v_cvt_pk_bf16_f32 v156, v193, v195
	s_waitcnt lgkmcnt(3)
	v_mfma_f32_32x32x16_bf16 v[66:81], v[214:217], v[246:249], v[66:81]
	v_cvt_pk_bf16_f32 v157, v192, v194
	v_cvt_pk_bf16_f32 v158, v0, v164
	v_cvt_pk_bf16_f32 v159, v162, v163
	v_cvt_pk_bf16_f32 v160, v160, v130
	v_mfma_f32_32x32x16_bf16 v[82:97], v[222:225], v[218:221], v[82:97]
	v_cvt_pk_bf16_f32 v161, v131, v132
	v_cvt_pk_bf16_f32 v162, v133, v165
	v_cvt_pk_bf16_f32 v163, v190, v191
	v_mfma_f32_32x32x16_bf16 v[66:81], v[226:229], v[218:221], v[66:81]
	v_cvt_pk_bf16_f32 v164, v146, v147
	v_cvt_pk_bf16_f32 v165, v148, v149
	v_permlane32_swap_b32_e32 v150, v152
	v_permlane32_swap_b32_e32 v151, v153
	s_waitcnt lgkmcnt(0)
	v_mfma_f32_32x32x16_bf16 v[82:97], v[238:241], v[230:233], v[82:97]
	v_permlane32_swap_b32_e32 v154, v156
	v_permlane32_swap_b32_e32 v155, v157
	v_permlane32_swap_b32_e32 v158, v160
	v_mfma_f32_32x32x16_bf16 v[66:81], v[242:245], v[230:233], v[66:81]
	v_permlane32_swap_b32_e32 v159, v161
	v_permlane32_swap_b32_e32 v162, v164
	v_permlane32_swap_b32_e32 v163, v165
	v_add_u32_e32 v0, 0x20000, v254
	global_load_dwordx4 v[130:133], v254, s[98:99] offset:256
	global_load_dwordx4 v[138:141], v254, s[98:99]
	global_load_dwordx4 v[134:137], v0, s[98:99] offset:256
	global_load_dwordx4 v[142:145], v0, s[98:99]
	v_lshlrev_b32_e32 v0, 4, v166
	global_load_dwordx4 v[146:149], v0, s[100:101]
	s_add_u32 s98, s98, 0x40000
	s_addc_u32 s99, s99, 0
	s_add_u32 s100, s100, 0x2000
	s_addc_u32 s101, s101, 0
	s_add_i32 s5, s96, 0xffffff9f
	s_cmp_le_i32 s5, s85
	s_cbranch_scc0 .Lattn_slow1
; __device__ __forceinline__ void partialSM(f32x16& p0, f32x16& p1, float& m_reg, float& mn, float& alpha) {
;     float pmax = p0[0];
; #pragma unroll
;     for (int r = 1; r < 16; ++r) pmax = fmaxf(pmax, p0[r]);
; #pragma unroll
;     for (int r = 0; r < 16; ++r) pmax = fmaxf(pmax, p1[r]);
;     { auto rr = __builtin_amdgcn_permlane32_swap(__float_as_uint(pmax), __float_as_uint(pmax), false, false);
;       pmax = fmaxf(__uint_as_float(rr[0]), __uint_as_float(rr[1])); }
;     constexpr float C2 = 1.4426950408889634f * ATT_SCALE;
;     if (__builtin_expect(__all((pmax - m_reg) * ATT_SCALE <= THR), 1)) { mn = m_reg; alpha = 1.f; }
;     else { mn = fmaxf(m_reg, pmax); alpha = __builtin_amdgcn_exp2f((m_reg - mn) * C2); m_reg = mn; }
;     const float mnL = -mn * C2;
; #pragma unroll
;     for (int r = 0; r < 16; ++r) p0[r] = fmaf(p0[r], C2, mnL);
; #pragma unroll
;     for (int r = 0; r < 16; ++r) p1[r] = fmaf(p1[r], C2, mnL);
; #pragma unroll
;     for (int r = 0; r < 16; ++r) p0[r] = __builtin_amdgcn_exp2f(p0[r]);
; }
; template <int VB>
; __device__ __forceinline__ void pv_tile(f32x16* o, int vb0, bf16x8 pa0, bf16x8 pa1, bf16x8 pa2, bf16x8 pa3) {
;     ...
;     PV_D0(0); PV_D0(1); PV_D0(2); PV_D0(3);
;     ...
; }
	s_lshl_b32 s4, s74, 14
	v_add_u32_e32 v242, s4, v169
	ds_read_b64_tr_b16 v[222:223], v242 offset:0
	ds_read_b64_tr_b16 v[224:225], v242 offset:0x800
	ds_read_b64_tr_b16 v[226:227], v242 offset:0x1000
	ds_read_b64_tr_b16 v[228:229], v242 offset:0x1800
	ds_read_b64_tr_b16 v[230:231], v242 offset:0x2000
	ds_read_b64_tr_b16 v[232:233], v242 offset:0x2800
	ds_read_b64_tr_b16 v[234:235], v242 offset:0x3000
	ds_read_b64_tr_b16 v[236:237], v242 offset:0x3800
	v_max_f32_e32 v0, v82, v83
	v_max3_f32 v0, v0, v84, v85
	v_max3_f32 v0, v0, v86, v87
	v_max3_f32 v0, v0, v88, v89
	s_waitcnt lgkmcnt(0)
	s_nop 0
	v_mfma_f32_32x32x16_bf16 v[50:65], v[150:153], v[222:225], v[50:65]
	ds_read_b64_tr_b16 v[222:223], v242 offset:0x200
	ds_read_b64_tr_b16 v[224:225], v242 offset:0xa00
	v_max3_f32 v0, v0, v90, v91
	v_max3_f32 v0, v0, v92, v93
	v_max3_f32 v0, v0, v94, v95
	v_max3_f32 v0, v0, v96, v97
	v_max3_f32 v0, v0, v66, v67
	v_max3_f32 v0, v0, v68, v69
	v_mfma_f32_32x32x16_bf16 v[50:65], v[154:157], v[226:229], v[50:65]
	ds_read_b64_tr_b16 v[226:227], v242 offset:0x1200
	ds_read_b64_tr_b16 v[228:229], v242 offset:0x1a00
	v_max3_f32 v0, v0, v70, v71
	v_max3_f32 v0, v0, v72, v73
	v_max3_f32 v0, v0, v74, v75
	v_max3_f32 v0, v0, v76, v77
	v_max3_f32 v0, v0, v78, v79
	v_max3_f32 v0, v0, v80, v81
	v_mfma_f32_32x32x16_bf16 v[50:65], v[158:161], v[230:233], v[50:65]
	ds_read_b64_tr_b16 v[230:231], v242 offset:0x2200
	ds_read_b64_tr_b16 v[232:233], v242 offset:0x2a00
	ds_read_b64_tr_b16 v[238:239], v242 offset:0x3200
	ds_read_b64_tr_b16 v[240:241], v242 offset:0x3a00
	v_mov_b32_e32 v243, v0
	s_nop 1
	v_permlane32_swap_b32_e32 v0, v243
	v_max_f32_e32 v0, v0, v243
	v_sub_f32_e32 v243, v0, v185
	v_max_f32_e32 v0, v185, v0
	v_sub_f32_e32 v244, v185, v0
	s_waitcnt lgkmcnt(0)
	v_mfma_f32_32x32x16_bf16 v[50:65], v[162:165], v[234:237], v[50:65]
	v_mul_f32_e32 v244, 0x3dd53b94, v244
	v_mul_f32_e32 v243, 0x3d93cd3a, v243
	v_exp_f32_e32 v244, v244
	v_cmp_ge_f32_e32 vcc, s73, v243
	s_cmp_eq_u64 vcc, exec
	s_cselect_b64 s[10:11], -1, 0
	v_mfma_f32_32x32x16_bf16 v[34:49], v[150:153], v[222:225], v[34:49]
	ds_read_b64_tr_b16 v[222:223], v242 offset:0x400
	ds_read_b64_tr_b16 v[224:225], v242 offset:0xc00
	v_cndmask_b32_e64 v189, v244, 1.0, s[10:11]
	v_cndmask_b32_e64 v0, v0, v185, s[10:11]
	v_mul_f32_e32 v185, 0xbdd53b94, v0
	v_fmamk_f32 v82, v82, 0x3dd53b94, v185
	v_fmamk_f32 v83, v83, 0x3dd53b94, v185
	v_fmamk_f32 v84, v84, 0x3dd53b94, v185
	v_mfma_f32_32x32x16_bf16 v[34:49], v[154:157], v[226:229], v[34:49]
	ds_read_b64_tr_b16 v[226:227], v242 offset:0x1400
	ds_read_b64_tr_b16 v[228:229], v242 offset:0x1c00
	v_fmamk_f32 v85, v85, 0x3dd53b94, v185
	v_fmamk_f32 v86, v86, 0x3dd53b94, v185
	v_fmamk_f32 v87, v87, 0x3dd53b94, v185
	v_fmamk_f32 v88, v88, 0x3dd53b94, v185
	v_fmamk_f32 v89, v89, 0x3dd53b94, v185
	v_fmamk_f32 v90, v90, 0x3dd53b94, v185
	v_mfma_f32_32x32x16_bf16 v[34:49], v[158:161], v[230:233], v[34:49]
	ds_read_b64_tr_b16 v[230:231], v242 offset:0x2400
	ds_read_b64_tr_b16 v[232:233], v242 offset:0x2c00
	ds_read_b64_tr_b16 v[234:235], v242 offset:0x3400
	ds_read_b64_tr_b16 v[236:237], v242 offset:0x3c00
	v_fmamk_f32 v91, v91, 0x3dd53b94, v185
	v_fmamk_f32 v92, v92, 0x3dd53b94, v185
	v_fmamk_f32 v93, v93, 0x3dd53b94, v185
	v_fmamk_f32 v94, v94, 0x3dd53b94, v185
	v_fmamk_f32 v95, v95, 0x3dd53b94, v185
	v_fmamk_f32 v96, v96, 0x3dd53b94, v185
	v_fmamk_f32 v97, v97, 0x3dd53b94, v185
	s_waitcnt lgkmcnt(0)
	v_mfma_f32_32x32x16_bf16 v[34:49], v[162:165], v[238:241], v[34:49]
	v_fmamk_f32 v190, v67, 0x3dd53b94, v185
	v_fmamk_f32 v191, v68, 0x3dd53b94, v185
	v_fmamk_f32 v188, v66, 0x3dd53b94, v185
	v_fmamk_f32 v192, v69, 0x3dd53b94, v185
	v_fmamk_f32 v193, v70, 0x3dd53b94, v185
	v_fmamk_f32 v194, v71, 0x3dd53b94, v185
	v_mfma_f32_32x32x16_bf16 v[18:33], v[150:153], v[222:225], v[18:33]
	ds_read_b64_tr_b16 v[222:223], v242 offset:0x600
	ds_read_b64_tr_b16 v[224:225], v242 offset:0xe00
	v_fmamk_f32 v195, v72, 0x3dd53b94, v185
	v_fmamk_f32 v196, v73, 0x3dd53b94, v185
	v_fmamk_f32 v197, v74, 0x3dd53b94, v185
	v_fmamk_f32 v198, v75, 0x3dd53b94, v185
	v_fmamk_f32 v199, v76, 0x3dd53b94, v185
	v_fmamk_f32 v200, v77, 0x3dd53b94, v185
	v_mfma_f32_32x32x16_bf16 v[18:33], v[154:157], v[226:229], v[18:33]
	ds_read_b64_tr_b16 v[226:227], v242 offset:0x1600
	ds_read_b64_tr_b16 v[228:229], v242 offset:0x1e00
	v_fmamk_f32 v201, v78, 0x3dd53b94, v185
	v_fmamk_f32 v202, v79, 0x3dd53b94, v185
	v_fmamk_f32 v203, v80, 0x3dd53b94, v185
	v_fmac_f32_e32 v185, 0x3dd53b94, v81
	v_exp_f32_e32 v204, v82
	v_mfma_f32_32x32x16_bf16 v[18:33], v[158:161], v[230:233], v[18:33]
	ds_read_b64_tr_b16 v[230:231], v242 offset:0x2600
	ds_read_b64_tr_b16 v[232:233], v242 offset:0x2e00
	ds_read_b64_tr_b16 v[238:239], v242 offset:0x3600
	ds_read_b64_tr_b16 v[240:241], v242 offset:0x3e00
	v_exp_f32_e32 v205, v83
	v_exp_f32_e32 v206, v84
	v_exp_f32_e32 v207, v85
	s_waitcnt lgkmcnt(0)
	v_mfma_f32_32x32x16_bf16 v[18:33], v[162:165], v[234:237], v[18:33]
	v_exp_f32_e32 v209, v86
	v_exp_f32_e32 v210, v87
	v_exp_f32_e32 v211, v88
	v_mfma_f32_32x32x16_bf16 v[2:17], v[150:153], v[222:225], v[2:17]
	v_exp_f32_e32 v212, v89
	v_exp_f32_e32 v213, v90
	v_exp_f32_e32 v214, v91
	v_mfma_f32_32x32x16_bf16 v[2:17], v[154:157], v[226:229], v[2:17]
	v_exp_f32_e32 v215, v92
	v_exp_f32_e32 v216, v93
	v_exp_f32_e32 v217, v94
	v_mfma_f32_32x32x16_bf16 v[2:17], v[158:161], v[230:233], v[2:17]
	v_exp_f32_e32 v218, v95
	v_exp_f32_e32 v219, v96
	v_exp_f32_e32 v220, v97
	v_mfma_f32_32x32x16_bf16 v[2:17], v[162:165], v[238:241], v[2:17]
	s_waitcnt vmcnt(3)
	ds_write_b128 v250, v[138:141] offset:49152
	s_waitcnt vmcnt(1)
	ds_write_b128 v250, v[142:145] offset:57856
	s_waitcnt vmcnt(0)
	v_add_u32_e32 v150, s76, v251
	ds_write_b128 v150, v[146:149]
	s_addk_i32 s4, 0xc000
	s_cmp_lg_u32 s74, 0
	s_cselect_b32 s4, s4, 0x8000
	v_add_u32_e32 v151, s4, v252
	v_add_u32_e32 v152, s4, v253
	v_cmp_gt_f32_e32 vcc, 1.0, v189
	ds_write_b128 v151, v[130:133]
	ds_write_b128 v152, v[134:137]
	s_cbranch_vccz .Lattn_f1_norsc
	s_and_saveexec_b64 s[4:5], s[8:9]
	ds_write_b32 v180, v189 offset:128
	s_or_b64 exec, exec, s[4:5]
	s_waitcnt lgkmcnt(0)
	ds_read_b128 v[150:153], v179 offset:224
	ds_read_b128 v[154:157], v179 offset:192
	ds_read_b128 v[158:161], v179 offset:160
	ds_read_b128 v[162:165], v179 offset:128
	s_waitcnt lgkmcnt(3)
	v_pk_mul_f32 v[64:65], v[64:65], v[152:153]
	s_waitcnt lgkmcnt(2)
	v_pk_mul_f32 v[60:61], v[60:61], v[156:157]
	s_waitcnt lgkmcnt(1)
	v_pk_mul_f32 v[56:57], v[56:57], v[160:161]
	s_waitcnt lgkmcnt(0)
	v_pk_mul_f32 v[52:53], v[52:53], v[164:165]
	v_pk_mul_f32 v[62:63], v[62:63], v[150:151]
	v_pk_mul_f32 v[58:59], v[58:59], v[154:155]
	v_pk_mul_f32 v[54:55], v[54:55], v[158:159]
	v_pk_mul_f32 v[50:51], v[50:51], v[162:163]
	v_pk_mul_f32 v[48:49], v[48:49], v[152:153]
	v_pk_mul_f32 v[44:45], v[44:45], v[156:157]
	v_pk_mul_f32 v[40:41], v[40:41], v[160:161]
	v_pk_mul_f32 v[36:37], v[36:37], v[164:165]
	v_pk_mul_f32 v[46:47], v[46:47], v[150:151]
	v_pk_mul_f32 v[42:43], v[42:43], v[154:155]
	v_pk_mul_f32 v[38:39], v[38:39], v[158:159]
	v_pk_mul_f32 v[34:35], v[34:35], v[162:163]
	v_pk_mul_f32 v[32:33], v[32:33], v[152:153]
	v_pk_mul_f32 v[28:29], v[28:29], v[156:157]
	v_pk_mul_f32 v[24:25], v[24:25], v[160:161]
	v_pk_mul_f32 v[20:21], v[20:21], v[164:165]
	v_pk_mul_f32 v[30:31], v[30:31], v[150:151]
	v_pk_mul_f32 v[26:27], v[26:27], v[154:155]
	v_pk_mul_f32 v[22:23], v[22:23], v[158:159]
	v_pk_mul_f32 v[18:19], v[18:19], v[162:163]
	v_pk_mul_f32 v[16:17], v[16:17], v[152:153]
	v_pk_mul_f32 v[12:13], v[12:13], v[156:157]
	v_pk_mul_f32 v[8:9], v[8:9], v[160:161]
	v_pk_mul_f32 v[4:5], v[4:5], v[164:165]
	v_pk_mul_f32 v[14:15], v[14:15], v[150:151]
	v_pk_mul_f32 v[10:11], v[10:11], v[154:155]
	v_pk_mul_f32 v[6:7], v[6:7], v[158:159]
	v_pk_mul_f32 v[2:3], v[2:3], v[162:163]

; #define LAS __attribute__((address_space(3)))
; __device__ __forceinline__ void finishSM(f32x16& p0, f32x16& p1, float alpha, float& l_reg, bf16x8& pa0, bf16x8& pa1, bf16x8& pa2, bf16x8& pa3) {
; #pragma unroll
;     for (int r = 0; r < 16; ++r) p1[r] = __builtin_amdgcn_exp2f(p1[r]);
;     float ps = 0;
; #pragma unroll
;     for (int r = 0; r < 16; ++r) ps += p0[r];
; #pragma unroll
;     for (int r = 0; r < 16; ++r) ps += p1[r];
;     { auto rr = __builtin_amdgcn_permlane32_swap(__float_as_uint(ps), __float_as_uint(ps), false, false);
;       ps = __uint_as_float(rr[0]) + __uint_as_float(rr[1]); }
;     l_reg = l_reg * alpha + ps;
;     ...
;     PK4(p0, 0, pa0); PK4(p0, 8, pa1); PK4(p1, 0, pa2); PK4(p1, 8, pa3);
;     ...
; }
; template <int KB>
; __device__ __forceinline__ void qkt(f32x16& p0, f32x16& p1, const LAS char* lds, int r32, int hi, const bf16x8* qr, const LAS char* qrb) {
;     p0 = f32x16{}; p1 = f32x16{};
;     { const LAS char* kbp = lds + OFF_K + KB * SHM_K + KSWZ(r32, hi * 16);
; #pragma unroll
;     for (int d0 = 0; d0 < 8; ++d0) { const LAS char* a = kbp + d0 * 32;
;         const bf16x8 b0 = *reinterpret_cast<const LAS bf16x8*>(a);
;         const bf16x8 b1 = *reinterpret_cast<const LAS bf16x8*>(a + 32 * 272);
;         p0 = __builtin_amdgcn_mfma_f32_32x32x16_bf16(b0, qr[d0], p0, 0, 0, 0);
;         p1 = __builtin_amdgcn_mfma_f32_32x32x16_bf16(b1, qr[d0], p1, 0, 0, 0); } }
;     { const LAS char* rb = lds + OFF_R + KB * SHM_R + RSWZ(r32, hi * 16);
; #pragma unroll
;     for (int d0 = 0; d0 < 4; ++d0) { const LAS char* a = rb + d0 * 32;
;         const bf16x8 b0 = *reinterpret_cast<const LAS bf16x8*>(a);
;         const bf16x8 b1 = *reinterpret_cast<const LAS bf16x8*>(a + 32 * 144);
;         const bf16x8 qv = *reinterpret_cast<const LAS bf16x8*>(qrb + d0 * 1024);
;         p0 = __builtin_amdgcn_mfma_f32_32x32x16_bf16(b0, qv, p0, 0, 0, 0);
;         p1 = __builtin_amdgcn_mfma_f32_32x32x16_bf16(b1, qv, p1, 0, 0, 0); } }
; }
.Lattn_s1b:
	ds_read_b128 v[222:225], v172 offset:49152
	ds_read_b128 v[226:229], v172 offset:57856
	ds_read_b128 v[230:233], v172 offset:49184
	ds_read_b128 v[234:237], v172 offset:57888
	ds_read_b128 v[238:241], v172 offset:49216
	ds_read_b128 v[242:245], v172 offset:57920
	ds_read_b128 v[246:249], v172 offset:49248
	ds_read_b128 v[130:133], v172 offset:57952
	ds_read_b128 v[134:137], v172 offset:49280
	ds_read_b128 v[138:141], v172 offset:57984
	ds_read_b128 v[142:145], v172 offset:49312
	ds_read_b128 v[146:149], v172 offset:58016
	v_exp_f32_e32 v185, v185
	v_exp_f32_e32 v162, v193
	v_exp_f32_e32 v163, v194
	v_exp_f32_e32 v164, v195
	s_waitcnt lgkmcnt(8)
	v_mfma_f32_32x32x16_bf16 v[82:97], v[222:225], v[126:129], 0
	ds_read_b128 v[222:225], v172 offset:49344
	v_exp_f32_e32 v165, v196
	v_exp_f32_e32 v193, v199
	v_mfma_f32_32x32x16_bf16 v[66:81], v[226:229], v[126:129], 0
	ds_read_b128 v[226:229], v172 offset:58048
	v_exp_f32_e32 v194, v200
	v_mfma_f32_32x32x16_bf16 v[82:97], v[230:233], v[122:125], v[82:97]
	ds_read_b128 v[230:233], v172 offset:49376
	v_exp_f32_e32 v195, v201
	v_exp_f32_e32 v196, v202
	v_mfma_f32_32x32x16_bf16 v[66:81], v[234:237], v[122:125], v[66:81]
	ds_read_b128 v[234:237], v172 offset:58080
	v_add_f32_e32 v150, 0, v204
	v_add_f32_e32 v150, v205, v150
	v_add_f32_e32 v150, v206, v150
	s_waitcnt lgkmcnt(8)
	v_mfma_f32_32x32x16_bf16 v[82:97], v[238:241], v[118:121], v[82:97]
	ds_read_b128 v[238:241], v178
	v_add_f32_e32 v150, v207, v150
	v_add_f32_e32 v150, v209, v150
	v_add_f32_e32 v150, v210, v150
	v_add_f32_e32 v150, v211, v150
	v_mfma_f32_32x32x16_bf16 v[66:81], v[242:245], v[118:121], v[66:81]
	ds_read_b128 v[242:245], v173
	v_add_f32_e32 v150, v212, v150
	v_add_f32_e32 v150, v213, v150
	v_add_f32_e32 v150, v214, v150
	v_mfma_f32_32x32x16_bf16 v[82:97], v[246:249], v[114:117], v[82:97]
	ds_read_b128 v[246:249], v173 offset:4608
	v_add_f32_e32 v150, v215, v150
	v_add_f32_e32 v150, v216, v150
	v_exp_f32_e32 v158, v188
	v_mfma_f32_32x32x16_bf16 v[66:81], v[130:133], v[114:117], v[66:81]
	ds_read_b128 v[130:133], v178 offset:1024
	v_add_f32_e32 v150, v217, v150
	v_exp_f32_e32 v159, v190
	s_waitcnt lgkmcnt(8)
	v_mfma_f32_32x32x16_bf16 v[82:97], v[134:137], v[110:113], v[82:97]
	ds_read_b128 v[134:137], v173 offset:32
	v_add_f32_e32 v150, v218, v150
	v_exp_f32_e32 v160, v191
	v_add_f32_e32 v150, v219, v150
	v_mfma_f32_32x32x16_bf16 v[66:81], v[138:141], v[110:113], v[66:81]
	ds_read_b128 v[138:141], v173 offset:4640
	v_exp_f32_e32 v161, v192
	v_add_f32_e32 v150, v220, v150
	v_mfma_f32_32x32x16_bf16 v[82:97], v[142:145], v[106:109], v[82:97]
	ds_read_b128 v[142:145], v178 offset:2048
	v_add_f32_e32 v150, v158, v150
	v_add_f32_e32 v150, v159, v150
	v_add_f32_e32 v150, v160, v150
	v_add_f32_e32 v150, v161, v150
	v_mfma_f32_32x32x16_bf16 v[66:81], v[146:149], v[106:109], v[66:81]
	ds_read_b128 v[146:149], v173 offset:64
	v_exp_f32_e32 v188, v197
	v_add_f32_e32 v150, v162, v150
	s_waitcnt lgkmcnt(8)
	v_mfma_f32_32x32x16_bf16 v[82:97], v[222:225], v[102:105], v[82:97]
	ds_read_b128 v[222:225], v173 offset:4672
	v_exp_f32_e32 v192, v198
	v_add_f32_e32 v150, v163, v150
	v_add_f32_e32 v150, v164, v150
	v_mfma_f32_32x32x16_bf16 v[66:81], v[226:229], v[102:105], v[66:81]
	ds_read_b128 v[226:229], v178 offset:3072
	v_add_f32_e32 v150, v165, v150
	v_add_f32_e32 v150, v188, v150
	v_add_f32_e32 v150, v192, v150
	v_mfma_f32_32x32x16_bf16 v[82:97], v[230:233], v[98:101], v[82:97]
	ds_read_b128 v[230:233], v173 offset:96
	v_exp_f32_e32 v197, v203
	v_add_f32_e32 v150, v193, v150
	v_add_f32_e32 v150, v194, v150
	v_mfma_f32_32x32x16_bf16 v[66:81], v[234:237], v[98:101], v[66:81]
	ds_read_b128 v[234:237], v173 offset:4704
	v_add_f32_e32 v150, v195, v150
	v_add_f32_e32 v150, v196, v150
	v_add_f32_e32 v150, v197, v150
	s_waitcnt lgkmcnt(7)
	v_mfma_f32_32x32x16_bf16 v[82:97], v[242:245], v[238:241], v[82:97]
	v_add_f32_e32 v190, v185, v150
	v_mov_b32_e32 v191, v190
	v_cvt_pk_bf16_f32 v150, v204, v205
	v_cvt_pk_bf16_f32 v151, v206, v207
	v_mfma_f32_32x32x16_bf16 v[66:81], v[246:249], v[238:241], v[66:81]
	v_cvt_pk_bf16_f32 v152, v209, v210
	v_cvt_pk_bf16_f32 v153, v211, v212
	v_cvt_pk_bf16_f32 v154, v213, v214
	v_mfma_f32_32x32x16_bf16 v[82:97], v[134:137], v[130:133], v[82:97]
	v_cvt_pk_bf16_f32 v155, v215, v216
	v_cvt_pk_bf16_f32 v156, v217, v218
	v_cvt_pk_bf16_f32 v157, v219, v220
	v_cvt_pk_bf16_f32 v158, v158, v159
	s_waitcnt lgkmcnt(3)
	v_mfma_f32_32x32x16_bf16 v[66:81], v[138:141], v[130:133], v[66:81]
	v_cvt_pk_bf16_f32 v159, v160, v161
	v_cvt_pk_bf16_f32 v160, v162, v163
	v_cvt_pk_bf16_f32 v161, v164, v165
	v_mfma_f32_32x32x16_bf16 v[82:97], v[146:149], v[142:145], v[82:97]
	v_cvt_pk_bf16_f32 v162, v188, v192
	v_cvt_pk_bf16_f32 v163, v193, v194
	v_cvt_pk_bf16_f32 v164, v195, v196
	v_cvt_pk_bf16_f32 v165, v197, v185
	v_mfma_f32_32x32x16_bf16 v[66:81], v[222:225], v[142:145], v[66:81]
	s_nop 1
	v_permlane32_swap_b32_e32 v190, v191
	v_permlane32_swap_b32_e32 v150, v152
	v_permlane32_swap_b32_e32 v151, v153
	s_waitcnt lgkmcnt(0)
	v_mfma_f32_32x32x16_bf16 v[82:97], v[230:233], v[226:229], v[82:97]
	v_permlane32_swap_b32_e32 v154, v156
	v_permlane32_swap_b32_e32 v155, v157
	v_permlane32_swap_b32_e32 v158, v160
	v_mfma_f32_32x32x16_bf16 v[66:81], v[234:237], v[226:229], v[66:81]
	v_permlane32_swap_b32_e32 v159, v161
	v_permlane32_swap_b32_e32 v162, v164
	v_permlane32_swap_b32_e32 v163, v165
	s_add_i32 s75, s75, 2
	s_cmp_le_u32 s75, s87
	s_cselect_b64 s[4:5], -1, 0
	s_cmp_gt_u32 s75, s87
	s_cbranch_scc1 .LBB0_514
	v_add_u32_e32 v146, 0x20000, v254
	global_load_dwordx4 v[130:133], v254, s[98:99] offset:256
	global_load_dwordx4 v[138:141], v254, s[98:99]
	global_load_dwordx4 v[134:137], v146, s[98:99] offset:256
	global_load_dwordx4 v[142:145], v146, s[98:99]
	v_lshlrev_b32_e32 v146, 4, v166
	global_load_dwordx4 v[146:149], v146, s[100:101]
	s_add_u32 s98, s98, 0x40000
	s_addc_u32 s99, s99, 0
	s_add_u32 s100, s100, 0x2000
	s_addc_u32 s101, s101, 0
; __device__ __forceinline__ void partialSM(f32x16& p0, f32x16& p1, float& m_reg, float& mn, float& alpha) {
;     float pmax = p0[0];
; #pragma unroll
;     for (int r = 1; r < 16; ++r) pmax = fmaxf(pmax, p0[r]);
; #pragma unroll
;     for (int r = 0; r < 16; ++r) pmax = fmaxf(pmax, p1[r]);
;     { auto rr = __builtin_amdgcn_permlane32_swap(__float_as_uint(pmax), __float_as_uint(pmax), false, false);
;       pmax = fmaxf(__uint_as_float(rr[0]), __uint_as_float(rr[1])); }
;     constexpr float C2 = 1.4426950408889634f * ATT_SCALE;
;     if (__builtin_expect(__all((pmax - m_reg) * ATT_SCALE <= THR), 1)) { mn = m_reg; alpha = 1.f; }
;     else { mn = fmaxf(m_reg, pmax); alpha = __builtin_amdgcn_exp2f((m_reg - mn) * C2); m_reg = mn; }
;     const float mnL = -mn * C2;
; #pragma unroll
;     for (int r = 0; r < 16; ++r) p0[r] = fmaf(p0[r], C2, mnL);
; #pragma unroll
;     for (int r = 0; r < 16; ++r) p1[r] = fmaf(p1[r], C2, mnL);
; #pragma unroll
;     for (int r = 0; r < 16; ++r) p0[r] = __builtin_amdgcn_exp2f(p0[r]);
; }
; template <int VB>
; __device__ __forceinline__ void pv_tile(f32x16* o, int vb0, bf16x8 pa0, bf16x8 pa1, bf16x8 pa2, bf16x8 pa3) {
;     ...
;     PV_D0(0); PV_D0(1); PV_D0(2); PV_D0(3);
;     ...
; }
.LBB0_514:
	s_sub_i32 s10, s96, 33
	s_cmp_le_i32 s10, s85
	s_cbranch_scc0 .Lattn_slow2
	s_add_i32 s10, s74, 1
	s_cmp_lg_u32 s74, 2
	s_cselect_b32 s74, s10, 0
	s_lshl_b32 s78, s74, 14
	v_add_u32_e32 v242, s78, v169
	ds_read_b64_tr_b16 v[222:223], v242 offset:0
	ds_read_b64_tr_b16 v[224:225], v242 offset:0x800
	ds_read_b64_tr_b16 v[226:227], v242 offset:0x1000
	ds_read_b64_tr_b16 v[228:229], v242 offset:0x1800
	ds_read_b64_tr_b16 v[230:231], v242 offset:0x2000
	ds_read_b64_tr_b16 v[232:233], v242 offset:0x2800
	ds_read_b64_tr_b16 v[234:235], v242 offset:0x3000
	ds_read_b64_tr_b16 v[236:237], v242 offset:0x3800
	v_max_f32_e32 v243, v82, v83
	v_max3_f32 v243, v243, v84, v85
	v_max3_f32 v243, v243, v86, v87
	v_max3_f32 v243, v243, v88, v89
	s_waitcnt lgkmcnt(0)
	s_nop 0
	v_mfma_f32_32x32x16_bf16 v[50:65], v[150:153], v[222:225], v[50:65]
	ds_read_b64_tr_b16 v[222:223], v242 offset:0x200
	ds_read_b64_tr_b16 v[224:225], v242 offset:0xa00
	v_max3_f32 v243, v243, v90, v91
	v_max3_f32 v243, v243, v92, v93
	v_max3_f32 v243, v243, v94, v95
	v_max3_f32 v243, v243, v96, v97
	v_max3_f32 v243, v243, v66, v67
	v_mfma_f32_32x32x16_bf16 v[50:65], v[154:157], v[226:229], v[50:65]
	ds_read_b64_tr_b16 v[226:227], v242 offset:0x1200
	ds_read_b64_tr_b16 v[228:229], v242 offset:0x1a00
	v_max3_f32 v243, v243, v68, v69
	v_max3_f32 v243, v243, v70, v71
	v_max3_f32 v243, v243, v72, v73
	v_max3_f32 v243, v243, v74, v75
	v_max3_f32 v243, v243, v76, v77
	v_max3_f32 v243, v243, v78, v79
	v_mfma_f32_32x32x16_bf16 v[50:65], v[158:161], v[230:233], v[50:65]
	ds_read_b64_tr_b16 v[230:231], v242 offset:0x2200
	ds_read_b64_tr_b16 v[232:233], v242 offset:0x2a00
	ds_read_b64_tr_b16 v[238:239], v242 offset:0x3200
	ds_read_b64_tr_b16 v[240:241], v242 offset:0x3a00
	v_max3_f32 v243, v243, v80, v81
	v_mov_b32_e32 v244, v243
	s_nop 1
	v_permlane32_swap_b32_e32 v243, v244
	v_max_f32_e32 v243, v243, v244
	v_sub_f32_e32 v244, v243, v0
	s_waitcnt lgkmcnt(0)
	v_mfma_f32_32x32x16_bf16 v[50:65], v[162:165], v[234:237], v[50:65]
	v_mul_f32_e32 v244, 0x3d93cd3a, v244
	v_cmp_ge_f32_e32 vcc, s73, v244
	s_cmp_eq_u64 vcc, exec
	s_cselect_b64 s[10:11], -1, 0
	v_max_f32_e32 v245, v0, v243
	v_sub_f32_e32 v246, v0, v245
	v_mfma_f32_32x32x16_bf16 v[34:49], v[150:153], v[222:225], v[34:49]
	ds_read_b64_tr_b16 v[222:223], v242 offset:0x400
	ds_read_b64_tr_b16 v[224:225], v242 offset:0xc00
	v_mul_f32_e32 v246, 0x3dd53b94, v246
	v_exp_f32_e32 v246, v246
	s_nop 0
	v_cndmask_b32_e64 v188, v246, 1.0, s[10:11]
	v_cndmask_b32_e64 v185, v245, v0, s[10:11]
	v_mfma_f32_32x32x16_bf16 v[34:49], v[154:157], v[226:229], v[34:49]
	ds_read_b64_tr_b16 v[226:227], v242 offset:0x1400
	ds_read_b64_tr_b16 v[228:229], v242 offset:0x1c00
	v_mul_f32_e32 v0, 0xbdd53b94, v185
	v_fmamk_f32 v82, v82, 0x3dd53b94, v0
	v_fmamk_f32 v83, v83, 0x3dd53b94, v0
	v_fmamk_f32 v84, v84, 0x3dd53b94, v0
	v_fmamk_f32 v85, v85, 0x3dd53b94, v0
	v_mfma_f32_32x32x16_bf16 v[34:49], v[158:161], v[230:233], v[34:49]
	ds_read_b64_tr_b16 v[230:231], v242 offset:0x2400
	ds_read_b64_tr_b16 v[232:233], v242 offset:0x2c00
	ds_read_b64_tr_b16 v[234:235], v242 offset:0x3400
	ds_read_b64_tr_b16 v[236:237], v242 offset:0x3c00
	v_fmamk_f32 v86, v86, 0x3dd53b94, v0
	v_fmamk_f32 v87, v87, 0x3dd53b94, v0
	v_fmamk_f32 v88, v88, 0x3dd53b94, v0
	v_fmamk_f32 v89, v89, 0x3dd53b94, v0
	v_fmamk_f32 v90, v90, 0x3dd53b94, v0
	v_fmamk_f32 v91, v91, 0x3dd53b94, v0
	s_waitcnt lgkmcnt(0)
	v_mfma_f32_32x32x16_bf16 v[34:49], v[162:165], v[238:241], v[34:49]
	v_fmamk_f32 v92, v92, 0x3dd53b94, v0
	v_fmamk_f32 v93, v93, 0x3dd53b94, v0
	v_fmamk_f32 v94, v94, 0x3dd53b94, v0
	v_fmamk_f32 v95, v95, 0x3dd53b94, v0
	v_fmamk_f32 v96, v96, 0x3dd53b94, v0
	v_mfma_f32_32x32x16_bf16 v[18:33], v[150:153], v[222:225], v[18:33]
	ds_read_b64_tr_b16 v[222:223], v242 offset:0x600
	ds_read_b64_tr_b16 v[224:225], v242 offset:0xe00
	v_fmamk_f32 v97, v97, 0x3dd53b94, v0
	v_exp_f32_e32 v205, v82
	v_exp_f32_e32 v207, v83
	v_exp_f32_e32 v203, v84
	v_mfma_f32_32x32x16_bf16 v[18:33], v[154:157], v[226:229], v[18:33]
	ds_read_b64_tr_b16 v[226:227], v242 offset:0x1600
	ds_read_b64_tr_b16 v[228:229], v242 offset:0x1e00
	v_exp_f32_e32 v206, v85
	v_exp_f32_e32 v202, v86
	v_mfma_f32_32x32x16_bf16 v[18:33], v[158:161], v[230:233], v[18:33]
	ds_read_b64_tr_b16 v[230:231], v242 offset:0x2600
	ds_read_b64_tr_b16 v[232:233], v242 offset:0x2e00
	ds_read_b64_tr_b16 v[238:239], v242 offset:0x3600
	ds_read_b64_tr_b16 v[240:241], v242 offset:0x3e00
	v_exp_f32_e32 v204, v87
	v_exp_f32_e32 v200, v88
	v_exp_f32_e32 v201, v89
	s_waitcnt lgkmcnt(0)
	v_mfma_f32_32x32x16_bf16 v[18:33], v[162:165], v[234:237], v[18:33]
	v_exp_f32_e32 v197, v90
	v_exp_f32_e32 v199, v91
	v_exp_f32_e32 v196, v92
	v_mfma_f32_32x32x16_bf16 v[2:17], v[150:153], v[222:225], v[2:17]
	v_pk_fma_f32 v[152:153], v[78:79], s[80:81], v[0:1] op_sel_hi:[1,0,0]
	v_pk_fma_f32 v[150:151], v[80:81], s[80:81], v[0:1] op_sel_hi:[1,0,0]
	v_exp_f32_e32 v198, v93
	v_exp_f32_e32 v193, v94
	v_exp_f32_e32 v195, v95
	v_mfma_f32_32x32x16_bf16 v[2:17], v[154:157], v[226:229], v[2:17]
	v_pk_fma_f32 v[156:157], v[74:75], s[80:81], v[0:1] op_sel_hi:[1,0,0]
	v_pk_fma_f32 v[154:155], v[76:77], s[80:81], v[0:1] op_sel_hi:[1,0,0]
	v_exp_f32_e32 v192, v96
	v_exp_f32_e32 v194, v97
	v_mfma_f32_32x32x16_bf16 v[2:17], v[158:161], v[230:233], v[2:17]
	v_pk_fma_f32 v[160:161], v[70:71], s[80:81], v[0:1] op_sel_hi:[1,0,0]
	v_pk_fma_f32 v[158:159], v[72:73], s[80:81], v[0:1] op_sel_hi:[1,0,0]
	v_add_f32_e32 v247, v186, v187
	v_fmac_f32_e32 v247, v183, v181
	v_add_f32_e32 v181, v190, v191
	v_fmac_f32_e32 v181, v247, v189
	v_add_u32_e32 v184, 0xffffff80, v184
	v_mfma_f32_32x32x16_bf16 v[2:17], v[162:165], v[238:241], v[2:17]
	v_pk_fma_f32 v[164:165], v[66:67], s[80:81], v[0:1] op_sel_hi:[1,0,0]
	v_pk_fma_f32 v[162:163], v[68:69], s[80:81], v[0:1] op_sel_hi:[1,0,0]
	s_andn2_b64 vcc, exec, s[4:5]
	s_cbranch_vccnz .Lattn_f2_nostage
	s_waitcnt vmcnt(3)
	v_add_u32_e32 v243, s77, v250
	ds_write_b128 v243, v[138:141]
	s_waitcnt vmcnt(1)
	ds_write_b128 v243, v[142:145] offset:8704
	s_waitcnt vmcnt(0)
	v_add_u32_e32 v244, s72, v251
	ds_write_b128 v244, v[146:149]
	s_addk_i32 s78, 0xc000
	s_cmp_lg_u32 s74, 0
	s_cselect_b32 s4, s78, 0x8000
	v_add_u32_e32 v245, s4, v252
	v_add_u32_e32 v246, s4, v253
	ds_write_b128 v245, v[130:133]
	ds_write_b128 v246, v[134:137]

; #define PG8_STAGE(bufoff, gbase, voff) do { _Pragma("unroll") for (int _i = 0; _i < 2; ++_i) \
;         __builtin_amdgcn_global_load_lds((const unsigned*)((const char*)(gbase) + (voff)[_i]), (LAS unsigned*)(lds + (bufoff) + ldsw + _i * 8192), 16, 0, 0); } while (0)
; #define PG8_LDA(dst, b, h) do { _Pragma("unroll") for (int m = 0; m < 4; ++m) _Pragma("unroll") for (int k = 0; k < 2; ++k) dst[m][k] = *(const LAS bf16x8*)(lds + PG8_SA(b, h) + aoff + m * 2048 + k * 1024); } while (0)
; #define PG8_LDB(dst, b, h) do { _Pragma("unroll") for (int n = 0; n < 2; ++n) _Pragma("unroll") for (int k = 0; k < 2; ++k) dst[n][k] = *(const LAS bf16x8*)(lds + PG8_SB(b, h) + boff + n * 2048 + k * 1024); } while (0)
; #define PG8_MMA(ai, bj, At, Bt) do { __builtin_amdgcn_s_setprio(1); _Pragma("unroll") for (int m = 0; m < 4; ++m) _Pragma("unroll") for (int n = 0; n < 2; ++n) _Pragma("unroll") for (int k = 0; k < 2; ++k) \
;         acc[ai][bj][m][n] = __builtin_amdgcn_mfma_f32_16x16x32_bf16(Bt[n][k], At[m][k], acc[ai][bj][m][n], 0, 0, 0); __builtin_amdgcn_s_setprio(0); } while (0)
; #define PG8_WAIT_V(n) asm volatile("s_waitcnt vmcnt(" #n ")" ::: "memory")
; #define PG8_WAIT_L(n) asm volatile("s_waitcnt lgkmcnt(" #n ")" ::: "memory")
; #define PG8_BAR __builtin_amdgcn_s_barrier()
; #define PG8_SCHED __builtin_amdgcn_sched_barrier(0)
; template <class Epi, class Sched>
; __device__ __forceinline__ void gemm_phase(LAS unsigned char* lds, const Gemm g, const Sched& S, const Epi& E, const int wave_s) {
;     ...
;             PG8_LDB(B0, 0, 0); PG8_LDB(B1, 0, 1); PG8_SCHED; PG8_LDA(At, 0, 0); PG8_STAGE(PG8_SA(1, 1), a1 + hstepA, voffA);
;             PG8_WAIT_V(8); PG8_WAIT_L(0); PG8_BAR; PG8_MMA(0, 0, At, B0); PG8_MMA(0, 1, At, B1); PG8_BAR; PG8_SCHED;
;             PG8_LDA(At, 0, 1); PG8_STAGE(PG8_SB(0, 0), b2, voffB); PG8_STAGE(PG8_SB(0, 1), b2 + hstepB, voffB); PG8_STAGE(PG8_SA(0, 0), a2, voffA);
;             PG8_WAIT_V(8); PG8_WAIT_L(0); PG8_BAR; PG8_MMA(1, 0, At, B0); PG8_MMA(1, 1, At, B1); PG8_BAR; PG8_SCHED;
.LBB0_860:
	ds_read_b128 v[100:103], v212
	ds_read_b128 v[108:111], v212 offset:1024
	ds_read_b128 v[136:139], v212 offset:2048
	ds_read_b128 v[140:143], v212 offset:3072
	ds_read_b128 v[144:147], v213
	ds_read_b128 v[148:151], v213 offset:1024
	ds_read_b128 v[152:155], v213 offset:2048
	ds_read_b128 v[156:159], v213 offset:3072
	s_add_u32 s4, s40, 0xfffc0080
	s_addc_u32 s5, s41, -1
	s_cmp_eq_u32 s54, 12
	s_cselect_b32 s43, s9, s5
	s_cselect_b32 s42, s27, s4
	s_cselect_b32 s5, s29, s53
	s_cselect_b32 s4, s31, s39
	v_lshl_add_u64 v[206:207], s[40:41], 0, v[178:179]
	s_add_i32 m0, s3, 0xc000
	ds_read_b128 v[160:163], v214
	ds_read_b128 v[164:167], v214 offset:1024
	ds_read_b128 v[186:189], v214 offset:2048
	ds_read_b128 v[190:193], v214 offset:3072
	ds_read_b128 v[194:197], v214 offset:4096
	ds_read_b128 v[198:201], v214 offset:5120
	ds_read_b128 v[202:205], v214 offset:6144
	ds_read_b128 v[216:219], v214 offset:7168
	global_load_lds_dwordx4 v[206:207], off
	v_lshl_add_u64 v[206:207], s[40:41], 0, v[180:181]
	s_add_i32 m0, s3, 0xe000
	s_nop 0
	global_load_lds_dwordx4 v[206:207], off
	s_waitcnt vmcnt(8) lgkmcnt(0)
	s_barrier
	s_setprio 1
	v_mfma_f32_16x16x32_bf16 v[132:135], v[100:103], v[160:163], v[132:135]
	v_mfma_f32_16x16x32_bf16 v[128:131], v[136:139], v[160:163], v[128:131]
	v_mfma_f32_16x16x32_bf16 v[124:127], v[100:103], v[186:189], v[124:127]
	v_mfma_f32_16x16x32_bf16 v[120:123], v[136:139], v[186:189], v[120:123]
	v_mfma_f32_16x16x32_bf16 v[116:119], v[100:103], v[194:197], v[116:119]
	v_mfma_f32_16x16x32_bf16 v[112:115], v[136:139], v[194:197], v[112:115]
	v_mfma_f32_16x16x32_bf16 v[104:107], v[100:103], v[202:205], v[104:107]
	v_mfma_f32_16x16x32_bf16 v[96:99], v[136:139], v[202:205], v[96:99]
	v_mfma_f32_16x16x32_bf16 v[132:135], v[108:111], v[164:167], v[132:135]
	v_mfma_f32_16x16x32_bf16 v[128:131], v[140:143], v[164:167], v[128:131]
	v_mfma_f32_16x16x32_bf16 v[124:127], v[108:111], v[190:193], v[124:127]
	v_mfma_f32_16x16x32_bf16 v[120:123], v[140:143], v[190:193], v[120:123]
	v_mfma_f32_16x16x32_bf16 v[116:119], v[108:111], v[198:201], v[116:119]
	v_mfma_f32_16x16x32_bf16 v[112:115], v[140:143], v[198:201], v[112:115]
	v_mfma_f32_16x16x32_bf16 v[104:107], v[108:111], v[216:219], v[104:107]
	v_mfma_f32_16x16x32_bf16 v[96:99], v[140:143], v[216:219], v[96:99]
	s_setprio 0
	s_setprio 1
	v_mfma_f32_16x16x32_bf16 v[60:63], v[144:147], v[160:163], v[60:63]
	v_mfma_f32_16x16x32_bf16 v[56:59], v[152:155], v[160:163], v[56:59]
	v_mfma_f32_16x16x32_bf16 v[52:55], v[144:147], v[186:189], v[52:55]
	v_mfma_f32_16x16x32_bf16 v[48:51], v[152:155], v[186:189], v[48:51]
	v_mfma_f32_16x16x32_bf16 v[44:47], v[144:147], v[194:197], v[44:47]
	v_mfma_f32_16x16x32_bf16 v[40:43], v[152:155], v[194:197], v[40:43]
	v_mfma_f32_16x16x32_bf16 v[36:39], v[144:147], v[202:205], v[36:39]
	v_mfma_f32_16x16x32_bf16 v[32:35], v[152:155], v[202:205], v[32:35]
	v_mfma_f32_16x16x32_bf16 v[60:63], v[148:151], v[164:167], v[60:63]
	v_mfma_f32_16x16x32_bf16 v[56:59], v[156:159], v[164:167], v[56:59]
	v_mfma_f32_16x16x32_bf16 v[52:55], v[148:151], v[190:193], v[52:55]
	v_mfma_f32_16x16x32_bf16 v[48:51], v[156:159], v[190:193], v[48:51]
	v_mfma_f32_16x16x32_bf16 v[44:47], v[148:151], v[198:201], v[44:47]
	v_mfma_f32_16x16x32_bf16 v[40:43], v[156:159], v[198:201], v[40:43]
	v_mfma_f32_16x16x32_bf16 v[36:39], v[148:151], v[216:219], v[36:39]
	v_mfma_f32_16x16x32_bf16 v[32:35], v[156:159], v[216:219], v[32:35]
	s_setprio 0
	s_barrier
	s_add_i32 s55, s50, s81
	v_lshl_add_u64 v[206:207], s[4:5], 0, v[170:171]
	s_mov_b32 m0, s55
	ds_read_b128 v[160:163], v214 offset:16384
	ds_read_b128 v[164:167], v214 offset:17408
	ds_read_b128 v[186:189], v214 offset:18432
	ds_read_b128 v[190:193], v214 offset:19456
	ds_read_b128 v[194:197], v214 offset:20480
	ds_read_b128 v[198:201], v214 offset:21504
	ds_read_b128 v[202:205], v214 offset:22528
	ds_read_b128 v[216:219], v214 offset:23552
	global_load_lds_dwordx4 v[206:207], off
	s_add_i32 m0, s55, 0x2000
	s_add_u32 s56, s4, 0x40000
	v_lshl_add_u64 v[220:221], s[4:5], 0, v[174:175]
	s_addc_u32 s57, s5, 0
	s_add_i32 s55, s51, s81
	global_load_lds_dwordx4 v[220:221], off
	v_lshl_add_u64 v[222:223], s[56:57], 0, v[170:171]
	s_mov_b32 m0, s55
	v_lshl_add_u64 v[224:225], s[42:43], 0, v[172:173]
	global_load_lds_dwordx4 v[222:223], off
	v_lshl_add_u64 v[222:223], s[56:57], 0, v[174:175]
	s_add_i32 m0, s55, 0x2000
	s_nop 0
	global_load_lds_dwordx4 v[222:223], off
	v_lshl_add_u64 v[222:223], s[42:43], 0, v[168:169]
	s_mov_b32 m0, s3
	s_nop 0
	global_load_lds_dwordx4 v[222:223], off
	s_mov_b32 m0, s33
	s_nop 0
	global_load_lds_dwordx4 v[224:225], off
	s_waitcnt vmcnt(8) lgkmcnt(0)
	s_barrier
; #define PG8_STAGE(bufoff, gbase, voff) do { _Pragma("unroll") for (int _i = 0; _i < 2; ++_i) \
;         __builtin_amdgcn_global_load_lds((const unsigned*)((const char*)(gbase) + (voff)[_i]), (LAS unsigned*)(lds + (bufoff) + ldsw + _i * 8192), 16, 0, 0); } while (0)
; #define PG8_LDA(dst, b, h) do { _Pragma("unroll") for (int m = 0; m < 4; ++m) _Pragma("unroll") for (int k = 0; k < 2; ++k) dst[m][k] = *(const LAS bf16x8*)(lds + PG8_SA(b, h) + aoff + m * 2048 + k * 1024); } while (0)
; #define PG8_LDB(dst, b, h) do { _Pragma("unroll") for (int n = 0; n < 2; ++n) _Pragma("unroll") for (int k = 0; k < 2; ++k) dst[n][k] = *(const LAS bf16x8*)(lds + PG8_SB(b, h) + boff + n * 2048 + k * 1024); } while (0)
; #define PG8_MMA(ai, bj, At, Bt) do { __builtin_amdgcn_s_setprio(1); _Pragma("unroll") for (int m = 0; m < 4; ++m) _Pragma("unroll") for (int n = 0; n < 2; ++n) _Pragma("unroll") for (int k = 0; k < 2; ++k) \
;         acc[ai][bj][m][n] = __builtin_amdgcn_mfma_f32_16x16x32_bf16(Bt[n][k], At[m][k], acc[ai][bj][m][n], 0, 0, 0); __builtin_amdgcn_s_setprio(0); } while (0)
; #define PG8_WAIT_V(n) asm volatile("s_waitcnt vmcnt(" #n ")" ::: "memory")
; #define PG8_WAIT_L(n) asm volatile("s_waitcnt lgkmcnt(" #n ")" ::: "memory")
; #define PG8_BAR __builtin_amdgcn_s_barrier()
; #define PG8_SCHED __builtin_amdgcn_sched_barrier(0)
; template <class Epi, class Sched>
; __device__ __forceinline__ void gemm_phase(LAS unsigned char* lds, const Gemm g, const Sched& S, const Epi& E, const int wave_s) {
;     ...
;             PG8_WAIT_V(8); PG8_WAIT_L(0); PG8_BAR; PG8_MMA(1, 0, At, B0); PG8_MMA(1, 1, At, B1); PG8_BAR; PG8_SCHED;
;             PG8_LDB(B0, 1, 0); PG8_LDB(B1, 1, 1); PG8_SCHED; PG8_LDA(At, 1, 0); PG8_STAGE(PG8_SA(0, 1), a2 + hstepA, voffA);
;             PG8_WAIT_V(8); PG8_WAIT_L(0); PG8_BAR; PG8_MMA(0, 0, At, B0); PG8_MMA(0, 1, At, B1); PG8_BAR; PG8_SCHED;
	s_setprio 1
	v_mfma_f32_16x16x32_bf16 v[92:95], v[100:103], v[160:163], v[92:95]
	v_mfma_f32_16x16x32_bf16 v[88:91], v[136:139], v[160:163], v[88:91]
	v_mfma_f32_16x16x32_bf16 v[84:87], v[100:103], v[186:189], v[84:87]
	v_mfma_f32_16x16x32_bf16 v[80:83], v[136:139], v[186:189], v[80:83]
	v_mfma_f32_16x16x32_bf16 v[76:79], v[100:103], v[194:197], v[76:79]
	v_mfma_f32_16x16x32_bf16 v[72:75], v[136:139], v[194:197], v[72:75]
	v_mfma_f32_16x16x32_bf16 v[68:71], v[100:103], v[202:205], v[68:71]
	v_mfma_f32_16x16x32_bf16 v[64:67], v[136:139], v[202:205], v[64:67]
	v_mfma_f32_16x16x32_bf16 v[92:95], v[108:111], v[164:167], v[92:95]
	v_mfma_f32_16x16x32_bf16 v[88:91], v[140:143], v[164:167], v[88:91]
	v_mfma_f32_16x16x32_bf16 v[84:87], v[108:111], v[190:193], v[84:87]
	v_mfma_f32_16x16x32_bf16 v[80:83], v[140:143], v[190:193], v[80:83]
	v_mfma_f32_16x16x32_bf16 v[76:79], v[108:111], v[198:201], v[76:79]
	v_mfma_f32_16x16x32_bf16 v[72:75], v[140:143], v[198:201], v[72:75]
	v_mfma_f32_16x16x32_bf16 v[68:71], v[108:111], v[216:219], v[68:71]
	v_mfma_f32_16x16x32_bf16 v[64:67], v[140:143], v[216:219], v[64:67]
	s_setprio 0
	s_setprio 1
	v_mfma_f32_16x16x32_bf16 v[28:31], v[144:147], v[160:163], v[28:31]
	v_mfma_f32_16x16x32_bf16 v[24:27], v[152:155], v[160:163], v[24:27]
	v_mfma_f32_16x16x32_bf16 v[20:23], v[144:147], v[186:189], v[20:23]
	v_mfma_f32_16x16x32_bf16 v[16:19], v[152:155], v[186:189], v[16:19]
	v_mfma_f32_16x16x32_bf16 v[12:15], v[144:147], v[194:197], v[12:15]
	v_mfma_f32_16x16x32_bf16 v[8:11], v[152:155], v[194:197], v[8:11]
	v_mfma_f32_16x16x32_bf16 v[4:7], v[144:147], v[202:205], v[4:7]
	v_mfma_f32_16x16x32_bf16 v[0:3], v[152:155], v[202:205], v[0:3]
	v_mfma_f32_16x16x32_bf16 v[28:31], v[148:151], v[164:167], v[28:31]
	v_mfma_f32_16x16x32_bf16 v[24:27], v[156:159], v[164:167], v[24:27]
	v_mfma_f32_16x16x32_bf16 v[20:23], v[148:151], v[190:193], v[20:23]
	v_mfma_f32_16x16x32_bf16 v[16:19], v[156:159], v[190:193], v[16:19]
	v_mfma_f32_16x16x32_bf16 v[12:15], v[148:151], v[198:201], v[12:15]
	v_mfma_f32_16x16x32_bf16 v[8:11], v[156:159], v[198:201], v[8:11]
	v_mfma_f32_16x16x32_bf16 v[4:7], v[148:151], v[216:219], v[4:7]
	v_mfma_f32_16x16x32_bf16 v[0:3], v[156:159], v[216:219], v[0:3]
	s_setprio 0
	s_barrier
	s_add_i32 s55, 0, 0x18000
	s_add_i32 s56, 0, 0x1c000
	v_add_u32_e32 v140, s55, v210
	v_add_u32_e32 v156, s56, v210
	ds_read_b128 v[100:103], v140
	ds_read_b128 v[108:111], v140 offset:1024
	ds_read_b128 v[136:139], v140 offset:2048
	ds_read_b128 v[140:143], v140 offset:3072
	ds_read_b128 v[144:147], v156
	ds_read_b128 v[148:151], v156 offset:1024
	ds_read_b128 v[152:155], v156 offset:2048
	ds_read_b128 v[156:159], v156 offset:3072
	s_add_u32 s42, s42, 0x40000
	s_addc_u32 s43, s43, 0
	s_mov_b32 m0, s44
	v_lshl_add_u64 v[226:227], s[42:43], 0, v[168:169]
	ds_read_b128 v[160:163], v214 offset:32768
	ds_read_b128 v[164:167], v214 offset:33792
	ds_read_b128 v[186:189], v214 offset:34816
	ds_read_b128 v[190:193], v214 offset:35840
	ds_read_b128 v[194:197], v214 offset:36864
	ds_read_b128 v[198:201], v214 offset:37888
	ds_read_b128 v[202:205], v214 offset:38912
	ds_read_b128 v[216:219], v214 offset:39936
	global_load_lds_dwordx4 v[226:227], off
	v_lshl_add_u64 v[226:227], s[42:43], 0, v[172:173]
	s_mov_b32 m0, s45
	s_nop 0
	global_load_lds_dwordx4 v[226:227], off
	s_waitcnt vmcnt(8) lgkmcnt(0)
	s_barrier
	s_setprio 1
	v_mfma_f32_16x16x32_bf16 v[132:135], v[100:103], v[160:163], v[132:135]
	v_mfma_f32_16x16x32_bf16 v[128:131], v[136:139], v[160:163], v[128:131]
	v_mfma_f32_16x16x32_bf16 v[124:127], v[100:103], v[186:189], v[124:127]
	v_mfma_f32_16x16x32_bf16 v[120:123], v[136:139], v[186:189], v[120:123]
	v_mfma_f32_16x16x32_bf16 v[116:119], v[100:103], v[194:197], v[116:119]
	v_mfma_f32_16x16x32_bf16 v[112:115], v[136:139], v[194:197], v[112:115]
	v_mfma_f32_16x16x32_bf16 v[104:107], v[100:103], v[202:205], v[104:107]
	v_mfma_f32_16x16x32_bf16 v[96:99], v[136:139], v[202:205], v[96:99]
	v_mfma_f32_16x16x32_bf16 v[132:135], v[108:111], v[164:167], v[132:135]
	v_mfma_f32_16x16x32_bf16 v[128:131], v[140:143], v[164:167], v[128:131]
	v_mfma_f32_16x16x32_bf16 v[124:127], v[108:111], v[190:193], v[124:127]
	v_mfma_f32_16x16x32_bf16 v[120:123], v[140:143], v[190:193], v[120:123]
	v_mfma_f32_16x16x32_bf16 v[116:119], v[108:111], v[198:201], v[116:119]
	v_mfma_f32_16x16x32_bf16 v[112:115], v[140:143], v[198:201], v[112:115]
	v_mfma_f32_16x16x32_bf16 v[104:107], v[108:111], v[216:219], v[104:107]
	v_mfma_f32_16x16x32_bf16 v[96:99], v[140:143], v[216:219], v[96:99]
	s_setprio 0
	s_setprio 1
	v_mfma_f32_16x16x32_bf16 v[60:63], v[144:147], v[160:163], v[60:63]
	v_mfma_f32_16x16x32_bf16 v[56:59], v[152:155], v[160:163], v[56:59]
	v_mfma_f32_16x16x32_bf16 v[52:55], v[144:147], v[186:189], v[52:55]
	v_mfma_f32_16x16x32_bf16 v[48:51], v[152:155], v[186:189], v[48:51]
	v_mfma_f32_16x16x32_bf16 v[44:47], v[144:147], v[194:197], v[44:47]
	v_mfma_f32_16x16x32_bf16 v[40:43], v[152:155], v[194:197], v[40:43]
	v_mfma_f32_16x16x32_bf16 v[36:39], v[144:147], v[202:205], v[36:39]
	v_mfma_f32_16x16x32_bf16 v[32:35], v[152:155], v[202:205], v[32:35]
	v_mfma_f32_16x16x32_bf16 v[60:63], v[148:151], v[164:167], v[60:63]
	v_mfma_f32_16x16x32_bf16 v[56:59], v[156:159], v[164:167], v[56:59]
	v_mfma_f32_16x16x32_bf16 v[52:55], v[148:151], v[190:193], v[52:55]
	v_mfma_f32_16x16x32_bf16 v[48:51], v[156:159], v[190:193], v[48:51]
	v_mfma_f32_16x16x32_bf16 v[44:47], v[148:151], v[198:201], v[44:47]
	v_mfma_f32_16x16x32_bf16 v[40:43], v[156:159], v[198:201], v[40:43]
	v_mfma_f32_16x16x32_bf16 v[36:39], v[148:151], v[216:219], v[36:39]
	v_mfma_f32_16x16x32_bf16 v[32:35], v[156:159], v[216:219], v[32:35]
	s_setprio 0
	s_barrier
; #define PG8_STAGE(bufoff, gbase, voff) do { _Pragma("unroll") for (int _i = 0; _i < 2; ++_i) \
;         __builtin_amdgcn_global_load_lds((const unsigned*)((const char*)(gbase) + (voff)[_i]), (LAS unsigned*)(lds + (bufoff) + ldsw + _i * 8192), 16, 0, 0); } while (0)
; #define PG8_LDA(dst, b, h) do { _Pragma("unroll") for (int m = 0; m < 4; ++m) _Pragma("unroll") for (int k = 0; k < 2; ++k) dst[m][k] = *(const LAS bf16x8*)(lds + PG8_SA(b, h) + aoff + m * 2048 + k * 1024); } while (0)
; #define PG8_MMA(ai, bj, At, Bt) do { __builtin_amdgcn_s_setprio(1); _Pragma("unroll") for (int m = 0; m < 4; ++m) _Pragma("unroll") for (int n = 0; n < 2; ++n) _Pragma("unroll") for (int k = 0; k < 2; ++k) \
;         acc[ai][bj][m][n] = __builtin_amdgcn_mfma_f32_16x16x32_bf16(Bt[n][k], At[m][k], acc[ai][bj][m][n], 0, 0, 0); __builtin_amdgcn_s_setprio(0); } while (0)
; #define PG8_WAIT_V(n) asm volatile("s_waitcnt vmcnt(" #n ")" ::: "memory")
; #define PG8_WAIT_L(n) asm volatile("s_waitcnt lgkmcnt(" #n ")" ::: "memory")
; #define PG8_BAR __builtin_amdgcn_s_barrier()
; #define PG8_SCHED __builtin_amdgcn_sched_barrier(0)
; template <class Epi, class Sched>
; __device__ __forceinline__ void gemm_phase(LAS unsigned char* lds, const Gemm g, const Sched& S, const Epi& E, const int wave_s) {
;     ...
;             PG8_LDA(At, 1, 1); PG8_STAGE(PG8_SB(1, 0), b3, voffB); PG8_STAGE(PG8_SB(1, 1), b3 + hstepB, voffB); PG8_STAGE(PG8_SA(1, 0), a3, voffA);
;             PG8_WAIT_V(8); PG8_WAIT_L(0); PG8_BAR; PG8_MMA(1, 0, At, B0); PG8_MMA(1, 1, At, B1); PG8_BAR; PG8_SCHED;
;         }
;         if (wr == 0) PG8_BAR;
	s_add_i32 s42, s55, s81
	v_lshl_add_u64 v[206:207], v[206:207], 0, s[22:23]
	s_mov_b32 m0, s42
	ds_read_b128 v[160:163], v214 offset:49152
	ds_read_b128 v[164:167], v214 offset:50176
	ds_read_b128 v[186:189], v214 offset:51200
	ds_read_b128 v[190:193], v214 offset:52224
	ds_read_b128 v[194:197], v214 offset:53248
	ds_read_b128 v[198:201], v214 offset:54272
	ds_read_b128 v[202:205], v214 offset:55296
	ds_read_b128 v[216:219], v214 offset:56320
	global_load_lds_dwordx4 v[206:207], off
	s_add_i32 m0, s42, 0x2000
	s_add_u32 s4, s4, 0x40080
	v_lshl_add_u64 v[206:207], v[220:221], 0, s[22:23]
	s_addc_u32 s5, s5, 0
	s_add_i32 s42, s56, s81
	global_load_lds_dwordx4 v[206:207], off
	v_lshl_add_u64 v[206:207], s[4:5], 0, v[170:171]
	s_mov_b32 m0, s42
	s_nop 0
	global_load_lds_dwordx4 v[206:207], off
	v_lshl_add_u64 v[206:207], s[4:5], 0, v[174:175]
	s_add_i32 m0, s42, 0x2000
	s_nop 0
	global_load_lds_dwordx4 v[206:207], off
	v_lshl_add_u64 v[206:207], v[222:223], 0, s[22:23]
	s_mov_b32 m0, s47
	s_nop 0
	global_load_lds_dwordx4 v[206:207], off
	v_lshl_add_u64 v[206:207], v[224:225], 0, s[22:23]
	s_mov_b32 m0, s48
	s_nop 0
	global_load_lds_dwordx4 v[206:207], off
	s_waitcnt vmcnt(8) lgkmcnt(0)
	s_barrier
	s_setprio 1
	v_mfma_f32_16x16x32_bf16 v[92:95], v[100:103], v[160:163], v[92:95]
	v_mfma_f32_16x16x32_bf16 v[88:91], v[136:139], v[160:163], v[88:91]
	v_mfma_f32_16x16x32_bf16 v[84:87], v[100:103], v[186:189], v[84:87]
	v_mfma_f32_16x16x32_bf16 v[80:83], v[136:139], v[186:189], v[80:83]
	v_mfma_f32_16x16x32_bf16 v[76:79], v[100:103], v[194:197], v[76:79]
	v_mfma_f32_16x16x32_bf16 v[72:75], v[136:139], v[194:197], v[72:75]
	v_mfma_f32_16x16x32_bf16 v[68:71], v[100:103], v[202:205], v[68:71]
	v_mfma_f32_16x16x32_bf16 v[64:67], v[136:139], v[202:205], v[64:67]
	v_mfma_f32_16x16x32_bf16 v[92:95], v[108:111], v[164:167], v[92:95]
	v_mfma_f32_16x16x32_bf16 v[88:91], v[140:143], v[164:167], v[88:91]
	v_mfma_f32_16x16x32_bf16 v[84:87], v[108:111], v[190:193], v[84:87]
	v_mfma_f32_16x16x32_bf16 v[80:83], v[140:143], v[190:193], v[80:83]
	v_mfma_f32_16x16x32_bf16 v[76:79], v[108:111], v[198:201], v[76:79]
	v_mfma_f32_16x16x32_bf16 v[72:75], v[140:143], v[198:201], v[72:75]
	v_mfma_f32_16x16x32_bf16 v[68:71], v[108:111], v[216:219], v[68:71]
	v_mfma_f32_16x16x32_bf16 v[64:67], v[140:143], v[216:219], v[64:67]
	s_setprio 0
	s_setprio 1
	v_mfma_f32_16x16x32_bf16 v[28:31], v[144:147], v[160:163], v[28:31]
	v_mfma_f32_16x16x32_bf16 v[24:27], v[152:155], v[160:163], v[24:27]
	v_mfma_f32_16x16x32_bf16 v[20:23], v[144:147], v[186:189], v[20:23]
	v_mfma_f32_16x16x32_bf16 v[16:19], v[152:155], v[186:189], v[16:19]
	v_mfma_f32_16x16x32_bf16 v[12:15], v[144:147], v[194:197], v[12:15]
	v_mfma_f32_16x16x32_bf16 v[8:11], v[152:155], v[194:197], v[8:11]
	v_mfma_f32_16x16x32_bf16 v[4:7], v[144:147], v[202:205], v[4:7]
	v_mfma_f32_16x16x32_bf16 v[0:3], v[152:155], v[202:205], v[0:3]
	v_mfma_f32_16x16x32_bf16 v[28:31], v[148:151], v[164:167], v[28:31]
	v_mfma_f32_16x16x32_bf16 v[24:27], v[156:159], v[164:167], v[24:27]
	v_mfma_f32_16x16x32_bf16 v[20:23], v[148:151], v[190:193], v[20:23]
	v_mfma_f32_16x16x32_bf16 v[16:19], v[156:159], v[190:193], v[16:19]
	v_mfma_f32_16x16x32_bf16 v[12:15], v[148:151], v[198:201], v[12:15]
	v_mfma_f32_16x16x32_bf16 v[8:11], v[156:159], v[198:201], v[8:11]
	v_mfma_f32_16x16x32_bf16 v[4:7], v[148:151], v[216:219], v[4:7]
	v_mfma_f32_16x16x32_bf16 v[0:3], v[156:159], v[216:219], v[0:3]
	s_setprio 0
	s_barrier
	s_add_i32 s54, s54, 2
	s_add_u32 s40, s40, 0x100
	s_addc_u32 s41, s41, 0
	s_add_u32 s39, s39, 0x100
	s_addc_u32 s53, s53, 0
	s_cmp_gt_u32 s54, 13
	s_cbranch_scc0 .LBB0_860
	s_and_b64 vcc, exec, s[24:25]
	s_cbranch_vccz .LBB0_863
	s_barrier

; #define PG8_STAGE(bufoff, gbase, voff) do { _Pragma("unroll") for (int _i = 0; _i < 2; ++_i) \
;         __builtin_amdgcn_global_load_lds((const unsigned*)((const char*)(gbase) + (voff)[_i]), (LAS unsigned*)(lds + (bufoff) + ldsw + _i * 8192), 16, 0, 0); } while (0)
; #define PG8_LDA(dst, b, h) do { _Pragma("unroll") for (int m = 0; m < 4; ++m) _Pragma("unroll") for (int k = 0; k < 2; ++k) dst[m][k] = *(const LAS bf16x8*)(lds + PG8_SA(b, h) + aoff + m * 2048 + k * 1024); } while (0)
; #define PG8_LDB(dst, b, h) do { _Pragma("unroll") for (int n = 0; n < 2; ++n) _Pragma("unroll") for (int k = 0; k < 2; ++k) dst[n][k] = *(const LAS bf16x8*)(lds + PG8_SB(b, h) + boff + n * 2048 + k * 1024); } while (0)
; #define PG8_MMA(ai, bj, At, Bt) do { __builtin_amdgcn_s_setprio(1); _Pragma("unroll") for (int m = 0; m < 4; ++m) _Pragma("unroll") for (int n = 0; n < 2; ++n) _Pragma("unroll") for (int k = 0; k < 2; ++k) \
;         acc[ai][bj][m][n] = __builtin_amdgcn_mfma_f32_16x16x32_bf16(Bt[n][k], At[m][k], acc[ai][bj][m][n], 0, 0, 0); __builtin_amdgcn_s_setprio(0); } while (0)
; #define PG8_WAIT_V(n) asm volatile("s_waitcnt vmcnt(" #n ")" ::: "memory")
; #define PG8_WAIT_L(n) asm volatile("s_waitcnt lgkmcnt(" #n ")" ::: "memory")
; #define PG8_BAR __builtin_amdgcn_s_barrier()
; #define PG8_SCHED __builtin_amdgcn_sched_barrier(0)
; template <class Epi, class Sched>
; __device__ __forceinline__ void gemm_phase(LAS unsigned char* lds, const Gemm g, const Sched& S, const Epi& E, const int wave_s) {
;     ...
;             PG8_LDB(B0, 0, 0); PG8_LDB(B1, 0, 1); PG8_SCHED; PG8_LDA(At, 0, 0); PG8_STAGE(PG8_SA(1, 1), a1 + hstepA, voffA);
;             PG8_WAIT_V(8); PG8_WAIT_L(0); PG8_BAR; PG8_MMA(0, 0, At, B0); PG8_MMA(0, 1, At, B1); PG8_BAR; PG8_SCHED;
;             PG8_LDA(At, 0, 1); PG8_STAGE(PG8_SB(0, 0), b2, voffB); PG8_STAGE(PG8_SB(0, 1), b2 + hstepB, voffB); PG8_STAGE(PG8_SA(0, 0), a2, voffA);
;             PG8_WAIT_V(8); PG8_WAIT_L(0); PG8_BAR; PG8_MMA(1, 0, At, B0); PG8_MMA(1, 1, At, B1); PG8_BAR; PG8_SCHED;
.LBB0_1024:
	s_add_u32 s48, s64, s46
	s_addc_u32 s49, s65, s47
	s_add_u32 s48, s48, 0x99a5200
	s_addc_u32 s49, s49, 0
	s_add_u32 s73, s70, s46
	s_addc_u32 s74, s71, s47
	s_add_i32 s75, 0, 0x10000
	s_cmpk_eq_i32 s46, 0x700
	s_cselect_b32 s51, s11, s49
	s_cselect_b32 s50, s10, s48
	v_add_u32_e32 v128, s75, v178
	s_cselect_b32 s49, s68, s74
	s_cselect_b32 s48, s69, s73
	s_add_i32 s73, 0, 0x14000
	ds_read_b128 v[170:173], v128
	ds_read_b128 v[182:185], v128 offset:1024
	ds_read_b128 v[186:189], v128 offset:2048
	ds_read_b128 v[190:193], v128 offset:3072
	v_add_u32_e32 v128, s73, v178
	ds_read_b128 v[194:197], v128
	ds_read_b128 v[198:201], v128 offset:1024
	ds_read_b128 v[202:205], v128 offset:2048
	ds_read_b128 v[206:209], v128 offset:3072
	v_lshl_add_u64 v[242:243], v[166:167], 0, s[46:47]
	s_add_i32 m0, s52, 0xc000
	ds_read_b128 v[210:213], v180
	ds_read_b128 v[214:217], v180 offset:1024
	ds_read_b128 v[218:221], v180 offset:2048
	ds_read_b128 v[222:225], v180 offset:3072
	ds_read_b128 v[226:229], v180 offset:4096
	ds_read_b128 v[230:233], v180 offset:5120
	ds_read_b128 v[234:237], v180 offset:6144
	ds_read_b128 v[238:241], v180 offset:7168
	global_load_lds_dwordx4 v[242:243], off
	v_lshl_add_u64 v[242:243], v[168:169], 0, s[46:47]
	s_add_i32 m0, s52, 0xe000
	s_nop 0
	global_load_lds_dwordx4 v[242:243], off
	s_waitcnt vmcnt(8) lgkmcnt(0)
	s_barrier
	s_setprio 1
	v_mfma_f32_16x16x32_bf16 v[124:127], v[170:173], v[210:213], v[124:127]
	v_mfma_f32_16x16x32_bf16 v[120:123], v[186:189], v[210:213], v[120:123]
	v_mfma_f32_16x16x32_bf16 v[116:119], v[170:173], v[218:221], v[116:119]
	v_mfma_f32_16x16x32_bf16 v[112:115], v[186:189], v[218:221], v[112:115]
	v_mfma_f32_16x16x32_bf16 v[108:111], v[170:173], v[226:229], v[108:111]
	v_mfma_f32_16x16x32_bf16 v[100:103], v[186:189], v[226:229], v[100:103]
	v_mfma_f32_16x16x32_bf16 v[92:95], v[170:173], v[234:237], v[92:95]
	v_mfma_f32_16x16x32_bf16 v[84:87], v[186:189], v[234:237], v[84:87]
	v_mfma_f32_16x16x32_bf16 v[124:127], v[182:185], v[214:217], v[124:127]
	v_mfma_f32_16x16x32_bf16 v[120:123], v[190:193], v[214:217], v[120:123]
	v_mfma_f32_16x16x32_bf16 v[116:119], v[182:185], v[222:225], v[116:119]
	v_mfma_f32_16x16x32_bf16 v[112:115], v[190:193], v[222:225], v[112:115]
	v_mfma_f32_16x16x32_bf16 v[108:111], v[182:185], v[230:233], v[108:111]
	v_mfma_f32_16x16x32_bf16 v[100:103], v[190:193], v[230:233], v[100:103]
	v_mfma_f32_16x16x32_bf16 v[92:95], v[182:185], v[238:241], v[92:95]
	v_mfma_f32_16x16x32_bf16 v[84:87], v[190:193], v[238:241], v[84:87]
	s_setprio 0
	s_setprio 1
	v_mfma_f32_16x16x32_bf16 v[104:107], v[194:197], v[210:213], v[104:107]
	v_mfma_f32_16x16x32_bf16 v[96:99], v[202:205], v[210:213], v[96:99]
	v_mfma_f32_16x16x32_bf16 v[88:91], v[194:197], v[218:221], v[88:91]
	v_mfma_f32_16x16x32_bf16 v[80:83], v[202:205], v[218:221], v[80:83]
	v_mfma_f32_16x16x32_bf16 v[76:79], v[194:197], v[226:229], v[76:79]
	v_mfma_f32_16x16x32_bf16 v[72:75], v[202:205], v[226:229], v[72:75]
	v_mfma_f32_16x16x32_bf16 v[68:71], v[194:197], v[234:237], v[68:71]
	v_mfma_f32_16x16x32_bf16 v[64:67], v[202:205], v[234:237], v[64:67]
	v_mfma_f32_16x16x32_bf16 v[104:107], v[198:201], v[214:217], v[104:107]
	v_mfma_f32_16x16x32_bf16 v[96:99], v[206:209], v[214:217], v[96:99]
	v_mfma_f32_16x16x32_bf16 v[88:91], v[198:201], v[222:225], v[88:91]
	v_mfma_f32_16x16x32_bf16 v[80:83], v[206:209], v[222:225], v[80:83]
	v_mfma_f32_16x16x32_bf16 v[76:79], v[198:201], v[230:233], v[76:79]
	v_mfma_f32_16x16x32_bf16 v[72:75], v[206:209], v[230:233], v[72:75]
	v_mfma_f32_16x16x32_bf16 v[68:71], v[198:201], v[238:241], v[68:71]
	v_mfma_f32_16x16x32_bf16 v[64:67], v[206:209], v[238:241], v[64:67]
	s_setprio 0
	s_barrier
	s_add_i32 s74, s75, s81
	v_lshl_add_u64 v[242:243], s[48:49], 0, v[130:131]
	s_mov_b32 m0, s74
	ds_read_b128 v[210:213], v180 offset:16384
	ds_read_b128 v[214:217], v180 offset:17408
	ds_read_b128 v[218:221], v180 offset:18432
	ds_read_b128 v[222:225], v180 offset:19456
	ds_read_b128 v[226:229], v180 offset:20480
	ds_read_b128 v[230:233], v180 offset:21504
	ds_read_b128 v[234:237], v180 offset:22528
	ds_read_b128 v[238:241], v180 offset:23552
	global_load_lds_dwordx4 v[242:243], off
	s_add_i32 m0, s74, 0x2000
	s_add_u32 s74, s48, 0x40000
	v_lshl_add_u64 v[244:245], s[48:49], 0, v[132:133]
	s_addc_u32 s75, s49, 0
	s_add_i32 s73, s73, s81
	global_load_lds_dwordx4 v[244:245], off
	v_lshl_add_u64 v[246:247], s[74:75], 0, v[130:131]
	s_mov_b32 m0, s73
	v_lshl_add_u64 v[248:249], s[50:51], 0, v[132:133]
	global_load_lds_dwordx4 v[246:247], off
	v_lshl_add_u64 v[246:247], s[74:75], 0, v[132:133]
	s_add_i32 m0, s73, 0x2000
	s_nop 0
	global_load_lds_dwordx4 v[246:247], off
	v_lshl_add_u64 v[246:247], s[50:51], 0, v[130:131]
	s_mov_b32 m0, s52
	s_nop 0
	global_load_lds_dwordx4 v[246:247], off
	s_mov_b32 m0, s57
	s_nop 0
	global_load_lds_dwordx4 v[248:249], off
	s_waitcnt vmcnt(8) lgkmcnt(0)
	s_barrier
; #define PG8_STAGE(bufoff, gbase, voff) do { _Pragma("unroll") for (int _i = 0; _i < 2; ++_i) \
;         __builtin_amdgcn_global_load_lds((const unsigned*)((const char*)(gbase) + (voff)[_i]), (LAS unsigned*)(lds + (bufoff) + ldsw + _i * 8192), 16, 0, 0); } while (0)
; #define PG8_LDA(dst, b, h) do { _Pragma("unroll") for (int m = 0; m < 4; ++m) _Pragma("unroll") for (int k = 0; k < 2; ++k) dst[m][k] = *(const LAS bf16x8*)(lds + PG8_SA(b, h) + aoff + m * 2048 + k * 1024); } while (0)
; #define PG8_LDB(dst, b, h) do { _Pragma("unroll") for (int n = 0; n < 2; ++n) _Pragma("unroll") for (int k = 0; k < 2; ++k) dst[n][k] = *(const LAS bf16x8*)(lds + PG8_SB(b, h) + boff + n * 2048 + k * 1024); } while (0)
; #define PG8_MMA(ai, bj, At, Bt) do { __builtin_amdgcn_s_setprio(1); _Pragma("unroll") for (int m = 0; m < 4; ++m) _Pragma("unroll") for (int n = 0; n < 2; ++n) _Pragma("unroll") for (int k = 0; k < 2; ++k) \
;         acc[ai][bj][m][n] = __builtin_amdgcn_mfma_f32_16x16x32_bf16(Bt[n][k], At[m][k], acc[ai][bj][m][n], 0, 0, 0); __builtin_amdgcn_s_setprio(0); } while (0)
; #define PG8_WAIT_V(n) asm volatile("s_waitcnt vmcnt(" #n ")" ::: "memory")
; #define PG8_WAIT_L(n) asm volatile("s_waitcnt lgkmcnt(" #n ")" ::: "memory")
; #define PG8_BAR __builtin_amdgcn_s_barrier()
; #define PG8_SCHED __builtin_amdgcn_sched_barrier(0)
; template <class Epi, class Sched>
; __device__ __forceinline__ void gemm_phase(LAS unsigned char* lds, const Gemm g, const Sched& S, const Epi& E, const int wave_s) {
;     ...
;             PG8_WAIT_V(8); PG8_WAIT_L(0); PG8_BAR; PG8_MMA(1, 0, At, B0); PG8_MMA(1, 1, At, B1); PG8_BAR; PG8_SCHED;
;             PG8_LDB(B0, 1, 0); PG8_LDB(B1, 1, 1); PG8_SCHED; PG8_LDA(At, 1, 0); PG8_STAGE(PG8_SA(0, 1), a2 + hstepA, voffA);
;             PG8_WAIT_V(8); PG8_WAIT_L(0); PG8_BAR; PG8_MMA(0, 0, At, B0); PG8_MMA(0, 1, At, B1); PG8_BAR; PG8_SCHED;
	s_setprio 1
	v_mfma_f32_16x16x32_bf16 v[60:63], v[170:173], v[210:213], v[60:63]
	v_mfma_f32_16x16x32_bf16 v[56:59], v[186:189], v[210:213], v[56:59]
	v_mfma_f32_16x16x32_bf16 v[52:55], v[170:173], v[218:221], v[52:55]
	v_mfma_f32_16x16x32_bf16 v[48:51], v[186:189], v[218:221], v[48:51]
	v_mfma_f32_16x16x32_bf16 v[44:47], v[170:173], v[226:229], v[44:47]
	v_mfma_f32_16x16x32_bf16 v[36:39], v[186:189], v[226:229], v[36:39]
	v_mfma_f32_16x16x32_bf16 v[28:31], v[170:173], v[234:237], v[28:31]
	v_mfma_f32_16x16x32_bf16 v[20:23], v[186:189], v[234:237], v[20:23]
	v_mfma_f32_16x16x32_bf16 v[60:63], v[182:185], v[214:217], v[60:63]
	v_mfma_f32_16x16x32_bf16 v[56:59], v[190:193], v[214:217], v[56:59]
	v_mfma_f32_16x16x32_bf16 v[52:55], v[182:185], v[222:225], v[52:55]
	v_mfma_f32_16x16x32_bf16 v[48:51], v[190:193], v[222:225], v[48:51]
	v_mfma_f32_16x16x32_bf16 v[44:47], v[182:185], v[230:233], v[44:47]
	v_mfma_f32_16x16x32_bf16 v[36:39], v[190:193], v[230:233], v[36:39]
	v_mfma_f32_16x16x32_bf16 v[28:31], v[182:185], v[238:241], v[28:31]
	v_mfma_f32_16x16x32_bf16 v[20:23], v[190:193], v[238:241], v[20:23]
	s_setprio 0
	s_setprio 1
	v_mfma_f32_16x16x32_bf16 v[40:43], v[194:197], v[210:213], v[40:43]
	v_mfma_f32_16x16x32_bf16 v[32:35], v[202:205], v[210:213], v[32:35]
	v_mfma_f32_16x16x32_bf16 v[24:27], v[194:197], v[218:221], v[24:27]
	v_mfma_f32_16x16x32_bf16 v[16:19], v[202:205], v[218:221], v[16:19]
	v_mfma_f32_16x16x32_bf16 v[12:15], v[194:197], v[226:229], v[12:15]
	v_mfma_f32_16x16x32_bf16 v[8:11], v[202:205], v[226:229], v[8:11]
	v_mfma_f32_16x16x32_bf16 v[4:7], v[194:197], v[234:237], v[4:7]
	v_mfma_f32_16x16x32_bf16 v[0:3], v[202:205], v[234:237], v[0:3]
	v_mfma_f32_16x16x32_bf16 v[40:43], v[198:201], v[214:217], v[40:43]
	v_mfma_f32_16x16x32_bf16 v[32:35], v[206:209], v[214:217], v[32:35]
	v_mfma_f32_16x16x32_bf16 v[24:27], v[198:201], v[222:225], v[24:27]
	v_mfma_f32_16x16x32_bf16 v[16:19], v[206:209], v[222:225], v[16:19]
	v_mfma_f32_16x16x32_bf16 v[12:15], v[198:201], v[230:233], v[12:15]
	v_mfma_f32_16x16x32_bf16 v[8:11], v[206:209], v[230:233], v[8:11]
	v_mfma_f32_16x16x32_bf16 v[4:7], v[198:201], v[238:241], v[4:7]
	v_mfma_f32_16x16x32_bf16 v[0:3], v[206:209], v[238:241], v[0:3]
	s_setprio 0
	s_barrier
	s_add_i32 s73, 0, 0x18000
	v_add_u32_e32 v128, s73, v178
	s_add_i32 s74, 0, 0x1c000
	ds_read_b128 v[170:173], v128
	ds_read_b128 v[182:185], v128 offset:1024
	ds_read_b128 v[186:189], v128 offset:2048
	ds_read_b128 v[190:193], v128 offset:3072
	v_add_u32_e32 v128, s74, v178
	ds_read_b128 v[194:197], v128
	ds_read_b128 v[198:201], v128 offset:1024
	ds_read_b128 v[202:205], v128 offset:2048
	ds_read_b128 v[206:209], v128 offset:3072
	s_add_u32 s50, s50, 0x40000
	s_addc_u32 s51, s51, 0
	s_mov_b32 m0, s58
	v_lshl_add_u64 v[250:251], s[50:51], 0, v[130:131]
	ds_read_b128 v[210:213], v180 offset:32768
	ds_read_b128 v[214:217], v180 offset:33792
	ds_read_b128 v[218:221], v180 offset:34816
	ds_read_b128 v[222:225], v180 offset:35840
	ds_read_b128 v[226:229], v180 offset:36864
	ds_read_b128 v[230:233], v180 offset:37888
	ds_read_b128 v[234:237], v180 offset:38912
	ds_read_b128 v[238:241], v180 offset:39936
	global_load_lds_dwordx4 v[250:251], off
	v_lshl_add_u64 v[250:251], s[50:51], 0, v[132:133]
	s_mov_b32 m0, s59
	s_nop 0
	global_load_lds_dwordx4 v[250:251], off
	s_waitcnt vmcnt(8) lgkmcnt(0)
	s_barrier
	s_setprio 1
	v_mfma_f32_16x16x32_bf16 v[124:127], v[170:173], v[210:213], v[124:127]
	v_mfma_f32_16x16x32_bf16 v[120:123], v[186:189], v[210:213], v[120:123]
	v_mfma_f32_16x16x32_bf16 v[116:119], v[170:173], v[218:221], v[116:119]
	v_mfma_f32_16x16x32_bf16 v[112:115], v[186:189], v[218:221], v[112:115]
	v_mfma_f32_16x16x32_bf16 v[108:111], v[170:173], v[226:229], v[108:111]
	v_mfma_f32_16x16x32_bf16 v[100:103], v[186:189], v[226:229], v[100:103]
	v_mfma_f32_16x16x32_bf16 v[92:95], v[170:173], v[234:237], v[92:95]
	v_mfma_f32_16x16x32_bf16 v[84:87], v[186:189], v[234:237], v[84:87]
	v_mfma_f32_16x16x32_bf16 v[124:127], v[182:185], v[214:217], v[124:127]
	v_mfma_f32_16x16x32_bf16 v[120:123], v[190:193], v[214:217], v[120:123]
	v_mfma_f32_16x16x32_bf16 v[116:119], v[182:185], v[222:225], v[116:119]
	v_mfma_f32_16x16x32_bf16 v[112:115], v[190:193], v[222:225], v[112:115]
	v_mfma_f32_16x16x32_bf16 v[108:111], v[182:185], v[230:233], v[108:111]
	v_mfma_f32_16x16x32_bf16 v[100:103], v[190:193], v[230:233], v[100:103]
	v_mfma_f32_16x16x32_bf16 v[92:95], v[182:185], v[238:241], v[92:95]
	v_mfma_f32_16x16x32_bf16 v[84:87], v[190:193], v[238:241], v[84:87]
	s_setprio 0
	s_setprio 1
	v_mfma_f32_16x16x32_bf16 v[104:107], v[194:197], v[210:213], v[104:107]
	v_mfma_f32_16x16x32_bf16 v[96:99], v[202:205], v[210:213], v[96:99]
	v_mfma_f32_16x16x32_bf16 v[88:91], v[194:197], v[218:221], v[88:91]
	v_mfma_f32_16x16x32_bf16 v[80:83], v[202:205], v[218:221], v[80:83]
	v_mfma_f32_16x16x32_bf16 v[76:79], v[194:197], v[226:229], v[76:79]
	v_mfma_f32_16x16x32_bf16 v[72:75], v[202:205], v[226:229], v[72:75]
	v_mfma_f32_16x16x32_bf16 v[68:71], v[194:197], v[234:237], v[68:71]
	v_mfma_f32_16x16x32_bf16 v[64:67], v[202:205], v[234:237], v[64:67]
	v_mfma_f32_16x16x32_bf16 v[104:107], v[198:201], v[214:217], v[104:107]
	v_mfma_f32_16x16x32_bf16 v[96:99], v[206:209], v[214:217], v[96:99]
	v_mfma_f32_16x16x32_bf16 v[88:91], v[198:201], v[222:225], v[88:91]
	v_mfma_f32_16x16x32_bf16 v[80:83], v[206:209], v[222:225], v[80:83]
	v_mfma_f32_16x16x32_bf16 v[76:79], v[198:201], v[230:233], v[76:79]
	v_mfma_f32_16x16x32_bf16 v[72:75], v[206:209], v[230:233], v[72:75]
	v_mfma_f32_16x16x32_bf16 v[68:71], v[198:201], v[238:241], v[68:71]
	v_mfma_f32_16x16x32_bf16 v[64:67], v[206:209], v[238:241], v[64:67]
	s_setprio 0
	s_barrier
; #define PG8_STAGE(bufoff, gbase, voff) do { _Pragma("unroll") for (int _i = 0; _i < 2; ++_i) \
;         __builtin_amdgcn_global_load_lds((const unsigned*)((const char*)(gbase) + (voff)[_i]), (LAS unsigned*)(lds + (bufoff) + ldsw + _i * 8192), 16, 0, 0); } while (0)
; #define PG8_LDA(dst, b, h) do { _Pragma("unroll") for (int m = 0; m < 4; ++m) _Pragma("unroll") for (int k = 0; k < 2; ++k) dst[m][k] = *(const LAS bf16x8*)(lds + PG8_SA(b, h) + aoff + m * 2048 + k * 1024); } while (0)
; #define PG8_MMA(ai, bj, At, Bt) do { __builtin_amdgcn_s_setprio(1); _Pragma("unroll") for (int m = 0; m < 4; ++m) _Pragma("unroll") for (int n = 0; n < 2; ++n) _Pragma("unroll") for (int k = 0; k < 2; ++k) \
;         acc[ai][bj][m][n] = __builtin_amdgcn_mfma_f32_16x16x32_bf16(Bt[n][k], At[m][k], acc[ai][bj][m][n], 0, 0, 0); __builtin_amdgcn_s_setprio(0); } while (0)
; #define PG8_WAIT_V(n) asm volatile("s_waitcnt vmcnt(" #n ")" ::: "memory")
; #define PG8_WAIT_L(n) asm volatile("s_waitcnt lgkmcnt(" #n ")" ::: "memory")
; #define PG8_BAR __builtin_amdgcn_s_barrier()
; #define PG8_SCHED __builtin_amdgcn_sched_barrier(0)
; template <class Epi, class Sched>
; __device__ __forceinline__ void gemm_phase(LAS unsigned char* lds, const Gemm g, const Sched& S, const Epi& E, const int wave_s) {
;     ...
;             PG8_LDA(At, 1, 1); PG8_STAGE(PG8_SB(1, 0), b3, voffB); PG8_STAGE(PG8_SB(1, 1), b3 + hstepB, voffB); PG8_STAGE(PG8_SA(1, 0), a3, voffA);
;             PG8_WAIT_V(8); PG8_WAIT_L(0); PG8_BAR; PG8_MMA(1, 0, At, B0); PG8_MMA(1, 1, At, B1); PG8_BAR; PG8_SCHED;
;         }
;         if (wr == 0) PG8_BAR;
	s_add_i32 s50, s73, s81
	v_lshl_add_u64 v[242:243], v[242:243], 0, s[22:23]
	s_mov_b32 m0, s50
	ds_read_b128 v[210:213], v180 offset:49152
	ds_read_b128 v[214:217], v180 offset:50176
	ds_read_b128 v[218:221], v180 offset:51200
	ds_read_b128 v[222:225], v180 offset:52224
	ds_read_b128 v[226:229], v180 offset:53248
	ds_read_b128 v[230:233], v180 offset:54272
	ds_read_b128 v[234:237], v180 offset:55296
	ds_read_b128 v[238:241], v180 offset:56320
	global_load_lds_dwordx4 v[242:243], off
	s_add_i32 m0, s50, 0x2000
	s_add_u32 s48, s48, 0x40080
	v_lshl_add_u64 v[242:243], v[244:245], 0, s[22:23]
	s_addc_u32 s49, s49, 0
	s_add_i32 s50, s74, s81
	global_load_lds_dwordx4 v[242:243], off
	v_lshl_add_u64 v[242:243], s[48:49], 0, v[130:131]
	s_mov_b32 m0, s50
	s_nop 0
	global_load_lds_dwordx4 v[242:243], off
	v_lshl_add_u64 v[242:243], s[48:49], 0, v[132:133]
	s_add_i32 m0, s50, 0x2000
	s_nop 0
	global_load_lds_dwordx4 v[242:243], off
	v_lshl_add_u64 v[242:243], v[246:247], 0, s[22:23]
	s_mov_b32 m0, s20
	s_nop 0
	global_load_lds_dwordx4 v[242:243], off
	v_lshl_add_u64 v[242:243], v[248:249], 0, s[22:23]
	s_mov_b32 m0, s63
	s_nop 0
	global_load_lds_dwordx4 v[242:243], off
	s_waitcnt vmcnt(8) lgkmcnt(0)
	s_barrier
	s_setprio 1
	v_mfma_f32_16x16x32_bf16 v[60:63], v[170:173], v[210:213], v[60:63]
	v_mfma_f32_16x16x32_bf16 v[56:59], v[186:189], v[210:213], v[56:59]
	v_mfma_f32_16x16x32_bf16 v[52:55], v[170:173], v[218:221], v[52:55]
	v_mfma_f32_16x16x32_bf16 v[48:51], v[186:189], v[218:221], v[48:51]
	v_mfma_f32_16x16x32_bf16 v[44:47], v[170:173], v[226:229], v[44:47]
	v_mfma_f32_16x16x32_bf16 v[36:39], v[186:189], v[226:229], v[36:39]
	v_mfma_f32_16x16x32_bf16 v[28:31], v[170:173], v[234:237], v[28:31]
	v_mfma_f32_16x16x32_bf16 v[20:23], v[186:189], v[234:237], v[20:23]
	v_mfma_f32_16x16x32_bf16 v[60:63], v[182:185], v[214:217], v[60:63]
	v_mfma_f32_16x16x32_bf16 v[56:59], v[190:193], v[214:217], v[56:59]
	v_mfma_f32_16x16x32_bf16 v[52:55], v[182:185], v[222:225], v[52:55]
	v_mfma_f32_16x16x32_bf16 v[48:51], v[190:193], v[222:225], v[48:51]
	v_mfma_f32_16x16x32_bf16 v[44:47], v[182:185], v[230:233], v[44:47]
	v_mfma_f32_16x16x32_bf16 v[36:39], v[190:193], v[230:233], v[36:39]
	v_mfma_f32_16x16x32_bf16 v[28:31], v[182:185], v[238:241], v[28:31]
	v_mfma_f32_16x16x32_bf16 v[20:23], v[190:193], v[238:241], v[20:23]
	s_setprio 0
	s_setprio 1
	v_mfma_f32_16x16x32_bf16 v[40:43], v[194:197], v[210:213], v[40:43]
	v_mfma_f32_16x16x32_bf16 v[32:35], v[202:205], v[210:213], v[32:35]
	v_mfma_f32_16x16x32_bf16 v[24:27], v[194:197], v[218:221], v[24:27]
	v_mfma_f32_16x16x32_bf16 v[16:19], v[202:205], v[218:221], v[16:19]
	v_mfma_f32_16x16x32_bf16 v[12:15], v[194:197], v[226:229], v[12:15]
	v_mfma_f32_16x16x32_bf16 v[8:11], v[202:205], v[226:229], v[8:11]
	v_mfma_f32_16x16x32_bf16 v[4:7], v[194:197], v[234:237], v[4:7]
	v_mfma_f32_16x16x32_bf16 v[0:3], v[202:205], v[234:237], v[0:3]
	v_mfma_f32_16x16x32_bf16 v[40:43], v[198:201], v[214:217], v[40:43]
	v_mfma_f32_16x16x32_bf16 v[32:35], v[206:209], v[214:217], v[32:35]
	v_mfma_f32_16x16x32_bf16 v[24:27], v[198:201], v[222:225], v[24:27]
	v_mfma_f32_16x16x32_bf16 v[16:19], v[206:209], v[222:225], v[16:19]
	v_mfma_f32_16x16x32_bf16 v[12:15], v[198:201], v[230:233], v[12:15]
	v_mfma_f32_16x16x32_bf16 v[8:11], v[206:209], v[230:233], v[8:11]
	v_mfma_f32_16x16x32_bf16 v[4:7], v[198:201], v[238:241], v[4:7]
	v_mfma_f32_16x16x32_bf16 v[0:3], v[206:209], v[238:241], v[0:3]
	s_setprio 0
	s_barrier
	s_add_i32 s72, s72, 2
	s_add_u32 s46, s46, 0x100
	s_addc_u32 s47, s47, 0
	s_cmp_gt_u32 s72, 13
	s_cbranch_scc0 .LBB0_1024
	s_and_b64 vcc, exec, s[12:13]
	s_cbranch_vccz .LBB0_1027
	s_barrier

; __global__ void __launch_bounds__(512, 2) mega_fwd(Args a) {
	.amdhsa_kernel _Z8mega_fwd4Args
		.amdhsa_group_segment_fixed_size 0
		.amdhsa_private_segment_fixed_size 0
		.amdhsa_kernarg_size 512
		.amdhsa_user_sgpr_count 2
		.amdhsa_user_sgpr_dispatch_ptr 0
		.amdhsa_user_sgpr_queue_ptr 0
		.amdhsa_user_sgpr_kernarg_segment_ptr 1
		.amdhsa_user_sgpr_dispatch_id 0
		.amdhsa_user_sgpr_kernarg_preload_length 0
		.amdhsa_user_sgpr_kernarg_preload_offset 0
		.amdhsa_user_sgpr_private_segment_size 0
		.amdhsa_uses_dynamic_stack 0
		.amdhsa_enable_private_segment 0
		.amdhsa_system_sgpr_workgroup_id_x 1
		.amdhsa_system_sgpr_workgroup_id_y 0
		.amdhsa_system_sgpr_workgroup_id_z 0
		.amdhsa_system_sgpr_workgroup_info 0
		.amdhsa_system_vgpr_workitem_id 2
		.amdhsa_next_free_vgpr 256
		.amdhsa_next_free_sgpr 102
		.amdhsa_accum_offset 256
		.amdhsa_reserve_vcc 1
		.amdhsa_float_round_mode_32 0
		.amdhsa_float_round_mode_16_64 0
		.amdhsa_float_denorm_mode_32 3
		.amdhsa_float_denorm_mode_16_64 3
		.amdhsa_dx10_clamp 1
		.amdhsa_ieee_mode 1
		.amdhsa_fp16_overflow 0
		.amdhsa_tg_split 0
		.amdhsa_exception_fp_ieee_invalid_op 0
		.amdhsa_exception_fp_denorm_src 0
		.amdhsa_exception_fp_ieee_div_zero 0
		.amdhsa_exception_fp_ieee_overflow 0
		.amdhsa_exception_fp_ieee_underflow 0
		.amdhsa_exception_fp_ieee_inexact 0
		.amdhsa_exception_int_div_zero 0
	.end_amdhsa_kernel

; __global__ void __launch_bounds__(512, 2) mega_fwd(Args a) {
amdhsa.kernels:
  - .agpr_count:     0
    .args:
      - .offset:         0
        .size:           256
        .value_kind:     by_value
      - .offset:         256
        .size:           4
        .value_kind:     hidden_block_count_x
      - .offset:         260
        .size:           4
        .value_kind:     hidden_block_count_y
      - .offset:         264
        .size:           4
        .value_kind:     hidden_block_count_z
      - .offset:         268
        .size:           2
        .value_kind:     hidden_group_size_x
      - .offset:         270
        .size:           2
        .value_kind:     hidden_group_size_y
      - .offset:         272
        .size:           2
        .value_kind:     hidden_group_size_z
      - .offset:         274
        .size:           2
        .value_kind:     hidden_remainder_x
      - .offset:         276
        .size:           2
        .value_kind:     hidden_remainder_y
      - .offset:         278
        .size:           2
        .value_kind:     hidden_remainder_z
      - .offset:         296
        .size:           8
        .value_kind:     hidden_global_offset_x
      - .offset:         304
        .size:           8
        .value_kind:     hidden_global_offset_y
      - .offset:         312
        .size:           8
        .value_kind:     hidden_global_offset_z
      - .offset:         320
        .size:           2
        .value_kind:     hidden_grid_dims
      - .offset:         344
        .size:           8
        .value_kind:     hidden_multigrid_sync_arg
      - .offset:         376
        .size:           4
        .value_kind:     hidden_dynamic_lds_size
    .group_segment_fixed_size: 0
    .kernarg_segment_align: 8
    .kernarg_segment_size: 512
    .language:       OpenCL C
    .language_version:
      - 2
      - 0
    .max_flat_workgroup_size: 512
    .name:           _Z8mega_fwd4Args
    .private_segment_fixed_size: 0
    .sgpr_count:     108
    .sgpr_spill_count: 32
    .symbol:         _Z8mega_fwd4Args.kd
    .uniform_work_group_size: 1
    .uses_dynamic_stack: false
    .vgpr_count:     256
    .vgpr_spill_count: 0
    .wavefront_size: 64
